# epilogue store-ladder de-serialisation in the gemm_in / gemm_out tile epilogues: the four LDS reads of each staged row group issued together into separate registers, counted lgkmcnt waits before each
# baseline (speedup 1.0000x reference)
.LBB0_239:
	s_mul_hi_i32 s0, s4, 0x2e8ba2e9
	s_lshr_b32 s1, s0, 31
	s_ashr_i32 s0, s0, 1
	s_add_i32 s1, s0, s1
	s_add_i32 s0, s1, s7
	s_cmpk_gt_i32 s0, 0x7f
	s_mul_i32 s12, s1, -11
	s_cselect_b64 s[10:11], -1, 0
	s_add_i32 s12, s4, s12
	s_and_b64 s[10:11], s[90:91], s[10:11]
	s_add_i32 s12, s12, -3
	s_cmp_lt_u32 s12, -2
	s_cselect_b64 s[12:13], -1, 0
	s_and_b64 s[10:11], s[10:11], s[12:13]
	s_and_b64 vcc, exec, s[10:11]
	s_cbranch_vccnz .LBB0_238
	s_lshl_b32 s0, s0, 8
	v_add_u32_e32 v0, s0, v152
	v_ashrrev_i32_e32 v1, 31, v0
	v_lshlrev_b64 v[0:1], 11, v[0:1]
	s_mulk_i32 s1, 0xf500
	v_lshl_add_u64 v[148:149], v[250:251], 0, v[0:1]
	s_add_i32 s1, s1, s8
	v_add_co_u32_e32 v150, vcc, 0x20000, v148
	v_add_u32_e32 v2, s1, v152
	s_nop 0
	v_addc_co_u32_e32 v151, vcc, 0, v149, vcc
	v_ashrrev_i32_e32 v3, 31, v2
	v_add_co_u32_e32 v144, vcc, 0x40000, v148
	v_lshlrev_b64 v[16:17], 11, v[2:3]
	s_nop 0
	v_addc_co_u32_e32 v145, vcc, 0, v149, vcc
	global_load_dwordx4 v[0:3], v[148:149], off
	v_add_co_u32_e32 v146, vcc, 0x60000, v148
	v_lshl_add_u64 v[140:141], v[176:177], 0, v[16:17]
	global_load_dwordx4 v[8:11], v[144:145], off
	global_load_dwordx4 v[16:19], v[140:141], off
	v_addc_co_u32_e32 v147, vcc, 0, v149, vcc
	global_load_dwordx4 v[4:7], v[150:151], off
	v_add_co_u32_e32 v138, vcc, s94, v140
	global_load_dwordx4 v[12:15], v[146:147], off
	s_nop 0
	v_addc_co_u32_e32 v139, vcc, 0, v141, vcc
	v_add_co_u32_e32 v134, vcc, 0x40000, v140
	global_load_dwordx4 v[20:23], v[138:139], off
	s_nop 0
	v_addc_co_u32_e32 v135, vcc, 0, v141, vcc
	global_load_dwordx4 v[24:27], v[134:135], off
	v_add_co_u32_e32 v136, vcc, s95, v140
	s_nop 1
	v_addc_co_u32_e32 v137, vcc, 0, v141, vcc
	global_load_dwordx4 v[28:31], v[136:137], off
	global_load_dwordx4 v[172:175], v[148:149], off offset:128
	global_load_dwordx4 v[182:185], v[150:151], off offset:128
	global_load_dwordx4 v[186:189], v[144:145], off offset:128
	global_load_dwordx4 v[190:193], v[146:147], off offset:128
	global_load_dwordx4 v[194:197], v[140:141], off offset:128
	global_load_dwordx4 v[198:201], v[138:139], off offset:128
	global_load_dwordx4 v[202:205], v[134:135], off offset:128
	global_load_dwordx4 v[206:209], v[136:137], off offset:128
	s_waitcnt vmcnt(15)
	ds_write_b128 v162, v[0:3]
	s_waitcnt vmcnt(13)
	ds_write_b128 v162, v[16:19] offset:36864
	s_waitcnt vmcnt(12)
	ds_write_b128 v162, v[4:7] offset:9216
	ds_write_b128 v162, v[8:11] offset:18432
	s_waitcnt vmcnt(11)
	ds_write_b128 v162, v[12:15] offset:27648
	s_waitcnt vmcnt(10)
	ds_write_b128 v162, v[20:23] offset:46080
	s_waitcnt vmcnt(9)
	ds_write_b128 v162, v[24:27] offset:55296
	s_waitcnt vmcnt(8)
	ds_write_b128 v162, v[28:31] offset:64512
	s_waitcnt lgkmcnt(0)
	s_barrier
	ds_read_b128 v[0:3], v163 offset:36864
	ds_read_b128 v[210:213], v163 offset:36896
	ds_read_b128 v[4:7], v163 offset:41472
	ds_read_b128 v[214:217], v163 offset:41504
	ds_read_b128 v[8:11], v154
	ds_read_b128 v[218:221], v154 offset:32
	ds_read_b128 v[12:15], v154 offset:4608
	ds_read_b128 v[222:225], v154 offset:4640
	ds_read_b128 v[16:19], v154 offset:9216
	ds_read_b128 v[226:229], v154 offset:9248
	ds_read_b128 v[230:233], v154 offset:13824
	ds_read_b128 v[234:237], v154 offset:13856
	s_waitcnt lgkmcnt(7)
	v_mfma_f32_32x32x16_bf16 v[112:127], v[8:11], v[0:3], 0
	v_mfma_f32_32x32x16_bf16 v[96:111], v[8:11], v[4:7], 0
	s_waitcnt lgkmcnt(5)
	v_mfma_f32_32x32x16_bf16 v[80:95], v[12:15], v[0:3], 0
	v_mfma_f32_32x32x16_bf16 v[64:79], v[12:15], v[4:7], 0
	s_waitcnt lgkmcnt(3)
	v_mfma_f32_32x32x16_bf16 v[48:63], v[16:19], v[0:3], 0
	v_mfma_f32_32x32x16_bf16 v[32:47], v[16:19], v[4:7], 0
	s_waitcnt lgkmcnt(1)
	v_mfma_f32_32x32x16_bf16 v[16:31], v[230:233], v[0:3], 0
	v_mfma_f32_32x32x16_bf16 v[0:15], v[230:233], v[4:7], 0
	global_load_dwordx4 v[230:233], v[148:149], off offset:256
	global_load_dwordx4 v[238:241], v[150:151], off offset:256
	s_waitcnt vmcnt(9)
	ds_write_b128 v164, v[172:175]
	s_waitcnt vmcnt(8)
	ds_write_b128 v164, v[182:185] offset:9216
	ds_read_b128 v[172:175], v163 offset:36928
	ds_read_b128 v[182:185], v163 offset:41536
	ds_read_b128 v[242:245], v154 offset:64
	ds_read_b128 v[246:249], v154 offset:4672
	ds_read_b128 v[130:133], v154 offset:9280
	ds_read_b128 v[158:161], v154 offset:13888
	v_mfma_f32_32x32x16_bf16 v[80:95], v[222:225], v[210:213], v[80:95]
	v_mfma_f32_32x32x16_bf16 v[64:79], v[222:225], v[214:217], v[64:79]
	v_mfma_f32_32x32x16_bf16 v[48:63], v[226:229], v[210:213], v[48:63]
	v_mfma_f32_32x32x16_bf16 v[32:47], v[226:229], v[214:217], v[32:47]
	s_waitcnt lgkmcnt(8)
	v_mfma_f32_32x32x16_bf16 v[16:31], v[234:237], v[210:213], v[16:31]
	v_mfma_f32_32x32x16_bf16 v[0:15], v[234:237], v[214:217], v[0:15]
	v_mfma_f32_32x32x16_bf16 v[112:127], v[218:221], v[210:213], v[112:127]
	v_mfma_f32_32x32x16_bf16 v[96:111], v[218:221], v[214:217], v[96:111]
	global_load_dwordx4 v[210:213], v[144:145], off offset:256
	global_load_dwordx4 v[214:217], v[146:147], off offset:256
	s_waitcnt vmcnt(9)
	ds_write_b128 v164, v[186:189] offset:18432
	s_waitcnt vmcnt(8)
	ds_write_b128 v164, v[190:193] offset:27648
	ds_read_b128 v[186:189], v163 offset:36960
	ds_read_b128 v[190:193], v163 offset:41568
	ds_read_b128 v[218:221], v154 offset:96
	ds_read_b128 v[222:225], v154 offset:4704
	ds_read_b128 v[226:229], v154 offset:9312
	ds_read_b128 v[234:237], v154 offset:13920
	s_waitcnt lgkmcnt(10)
	v_mfma_f32_32x32x16_bf16 v[80:95], v[246:249], v[172:175], v[80:95]
	v_mfma_f32_32x32x16_bf16 v[64:79], v[246:249], v[182:185], v[64:79]
	s_waitcnt lgkmcnt(9)
	v_mfma_f32_32x32x16_bf16 v[48:63], v[130:133], v[172:175], v[48:63]
	v_mfma_f32_32x32x16_bf16 v[32:47], v[130:133], v[182:185], v[32:47]
	s_waitcnt lgkmcnt(8)
	v_mfma_f32_32x32x16_bf16 v[16:31], v[158:161], v[172:175], v[16:31]
	v_mfma_f32_32x32x16_bf16 v[0:15], v[158:161], v[182:185], v[0:15]
	v_mfma_f32_32x32x16_bf16 v[112:127], v[242:245], v[172:175], v[112:127]
	v_mfma_f32_32x32x16_bf16 v[96:111], v[242:245], v[182:185], v[96:111]
	global_load_dwordx4 v[130:133], v[140:141], off offset:256
	global_load_dwordx4 v[158:161], v[138:139], off offset:256
	s_waitcnt vmcnt(9)
	ds_write_b128 v165, v[194:197]
	s_waitcnt vmcnt(8)
	ds_write_b128 v166, v[198:201]
	s_waitcnt lgkmcnt(4)
	v_mfma_f32_32x32x16_bf16 v[80:95], v[222:225], v[186:189], v[80:95]
	v_mfma_f32_32x32x16_bf16 v[64:79], v[222:225], v[190:193], v[64:79]
	s_waitcnt lgkmcnt(3)
	v_mfma_f32_32x32x16_bf16 v[48:63], v[226:229], v[186:189], v[48:63]
	v_mfma_f32_32x32x16_bf16 v[32:47], v[226:229], v[190:193], v[32:47]
	s_waitcnt lgkmcnt(2)
	v_mfma_f32_32x32x16_bf16 v[16:31], v[234:237], v[186:189], v[16:31]
	v_mfma_f32_32x32x16_bf16 v[0:15], v[234:237], v[190:193], v[0:15]
	v_mfma_f32_32x32x16_bf16 v[112:127], v[218:221], v[186:189], v[112:127]
	v_mfma_f32_32x32x16_bf16 v[96:111], v[218:221], v[190:193], v[96:111]
	global_load_dwordx4 v[172:175], v[134:135], off offset:256
	global_load_dwordx4 v[182:185], v[136:137], off offset:256
	s_waitcnt vmcnt(9)
	ds_write_b128 v167, v[202:205]
	s_waitcnt vmcnt(8)
	ds_write_b128 v168, v[206:209]
	s_waitcnt lgkmcnt(0)
	s_barrier
	ds_read_b128 v[186:189], v169
	ds_read_b128 v[190:193], v169 offset:32
	ds_read_b128 v[194:197], v169 offset:4608
	ds_read_b128 v[198:201], v169 offset:4640
	ds_read_b128 v[202:205], v155
	ds_read_b128 v[206:209], v155 offset:32
	ds_read_b128 v[218:221], v155 offset:4608
	ds_read_b128 v[222:225], v155 offset:4640
	ds_read_b128 v[226:229], v155 offset:9216
	ds_read_b128 v[234:237], v155 offset:9248
	ds_read_b128 v[242:245], v155 offset:13824
	ds_read_b128 v[246:249], v155 offset:13856
	s_waitcnt lgkmcnt(5)
	v_mfma_f32_32x32x16_bf16 v[80:95], v[218:221], v[186:189], v[80:95]
	v_mfma_f32_32x32x16_bf16 v[64:79], v[218:221], v[194:197], v[64:79]
	s_waitcnt lgkmcnt(3)
	v_mfma_f32_32x32x16_bf16 v[48:63], v[226:229], v[186:189], v[48:63]
	v_mfma_f32_32x32x16_bf16 v[32:47], v[226:229], v[194:197], v[32:47]
	s_waitcnt lgkmcnt(1)
	v_mfma_f32_32x32x16_bf16 v[16:31], v[242:245], v[186:189], v[16:31]
	v_mfma_f32_32x32x16_bf16 v[0:15], v[242:245], v[194:197], v[0:15]
	v_mfma_f32_32x32x16_bf16 v[112:127], v[202:205], v[186:189], v[112:127]
	v_mfma_f32_32x32x16_bf16 v[96:111], v[202:205], v[194:197], v[96:111]
	global_load_dwordx4 v[186:189], v[148:149], off offset:384
	global_load_dwordx4 v[194:197], v[150:151], off offset:384
	s_waitcnt vmcnt(9)
	ds_write_b128 v128, v[230:233]
	s_waitcnt vmcnt(8)
	ds_write_b128 v128, v[238:241] offset:9216
	ds_read_b128 v[202:205], v169 offset:64
	ds_read_b128 v[218:221], v169 offset:4672
	ds_read_b128 v[226:229], v155 offset:64
	ds_read_b128 v[230:233], v155 offset:4672
	ds_read_b128 v[238:241], v155 offset:9280
	ds_read_b128 v[242:245], v155 offset:13888
	v_mfma_f32_32x32x16_bf16 v[80:95], v[222:225], v[190:193], v[80:95]
	v_mfma_f32_32x32x16_bf16 v[64:79], v[222:225], v[198:201], v[64:79]
	v_mfma_f32_32x32x16_bf16 v[48:63], v[234:237], v[190:193], v[48:63]
	v_mfma_f32_32x32x16_bf16 v[32:47], v[234:237], v[198:201], v[32:47]
	s_waitcnt lgkmcnt(8)
	v_mfma_f32_32x32x16_bf16 v[16:31], v[246:249], v[190:193], v[16:31]
	v_mfma_f32_32x32x16_bf16 v[0:15], v[246:249], v[198:201], v[0:15]
	v_mfma_f32_32x32x16_bf16 v[112:127], v[206:209], v[190:193], v[112:127]
	v_mfma_f32_32x32x16_bf16 v[96:111], v[206:209], v[198:201], v[96:111]
	global_load_dwordx4 v[190:193], v[144:145], off offset:384
	global_load_dwordx4 v[198:201], v[146:147], off offset:384
	s_waitcnt vmcnt(9)
	ds_write_b128 v128, v[210:213] offset:18432
	s_waitcnt vmcnt(8)
	ds_write_b128 v128, v[214:217] offset:27648
	ds_read_b128 v[206:209], v169 offset:96
	ds_read_b128 v[210:213], v169 offset:4704
	ds_read_b128 v[214:217], v155 offset:96
	ds_read_b128 v[222:225], v155 offset:4704
	ds_read_b128 v[234:237], v155 offset:9312
	ds_read_b128 v[246:249], v155 offset:13920
	s_waitcnt lgkmcnt(10)
	v_mfma_f32_32x32x16_bf16 v[80:95], v[230:233], v[202:205], v[80:95]
	v_mfma_f32_32x32x16_bf16 v[64:79], v[230:233], v[218:221], v[64:79]
	s_waitcnt lgkmcnt(9)
	v_mfma_f32_32x32x16_bf16 v[48:63], v[238:241], v[202:205], v[48:63]
	v_mfma_f32_32x32x16_bf16 v[32:47], v[238:241], v[218:221], v[32:47]
	s_waitcnt lgkmcnt(8)
	v_mfma_f32_32x32x16_bf16 v[16:31], v[242:245], v[202:205], v[16:31]
	v_mfma_f32_32x32x16_bf16 v[0:15], v[242:245], v[218:221], v[0:15]
	v_mfma_f32_32x32x16_bf16 v[112:127], v[226:229], v[202:205], v[112:127]
	v_mfma_f32_32x32x16_bf16 v[96:111], v[226:229], v[218:221], v[96:111]
	s_waitcnt vmcnt(7)
	ds_write_b128 v128, v[130:133] offset:36864
	global_load_dwordx4 v[130:133], v[140:141], off offset:384
	s_waitcnt vmcnt(7)
	ds_write_b128 v128, v[158:161] offset:46080
	global_load_dwordx4 v[158:161], v[138:139], off offset:384
	s_waitcnt lgkmcnt(4)
	v_mfma_f32_32x32x16_bf16 v[80:95], v[222:225], v[206:209], v[80:95]
	v_mfma_f32_32x32x16_bf16 v[64:79], v[222:225], v[210:213], v[64:79]
	s_waitcnt lgkmcnt(3)
	v_mfma_f32_32x32x16_bf16 v[48:63], v[234:237], v[206:209], v[48:63]
	v_mfma_f32_32x32x16_bf16 v[32:47], v[234:237], v[210:213], v[32:47]
	s_waitcnt lgkmcnt(2)
	v_mfma_f32_32x32x16_bf16 v[16:31], v[246:249], v[206:209], v[16:31]
	v_mfma_f32_32x32x16_bf16 v[0:15], v[246:249], v[210:213], v[0:15]
	v_mfma_f32_32x32x16_bf16 v[112:127], v[214:217], v[206:209], v[112:127]
	v_mfma_f32_32x32x16_bf16 v[96:111], v[214:217], v[210:213], v[96:111]
	global_load_dwordx4 v[202:205], v[134:135], off offset:384
	global_load_dwordx4 v[206:209], v[136:137], off offset:384
	s_waitcnt vmcnt(9)
	ds_write_b128 v128, v[172:175] offset:55296
	s_waitcnt vmcnt(8)
	ds_write_b128 v128, v[182:185] offset:64512
	s_waitcnt lgkmcnt(0)
	s_barrier
	ds_read_b128 v[172:175], v163 offset:36864
	ds_read_b128 v[182:185], v163 offset:36896
	ds_read_b128 v[210:213], v163 offset:41472
	ds_read_b128 v[214:217], v163 offset:41504
	ds_read_b128 v[218:221], v154
	ds_read_b128 v[222:225], v154 offset:32
	ds_read_b128 v[226:229], v154 offset:4608
	ds_read_b128 v[230:233], v154 offset:4640
	ds_read_b128 v[234:237], v154 offset:9216
	ds_read_b128 v[238:241], v154 offset:9248
	ds_read_b128 v[242:245], v154 offset:13824
	ds_read_b128 v[246:249], v154 offset:13856
	s_waitcnt lgkmcnt(5)
	v_mfma_f32_32x32x16_bf16 v[80:95], v[226:229], v[172:175], v[80:95]
	v_mfma_f32_32x32x16_bf16 v[64:79], v[226:229], v[210:213], v[64:79]
	s_waitcnt lgkmcnt(3)
	v_mfma_f32_32x32x16_bf16 v[48:63], v[234:237], v[172:175], v[48:63]
	v_mfma_f32_32x32x16_bf16 v[32:47], v[234:237], v[210:213], v[32:47]
	s_waitcnt lgkmcnt(1)
	v_mfma_f32_32x32x16_bf16 v[16:31], v[242:245], v[172:175], v[16:31]
	v_mfma_f32_32x32x16_bf16 v[0:15], v[242:245], v[210:213], v[0:15]
	v_mfma_f32_32x32x16_bf16 v[112:127], v[218:221], v[172:175], v[112:127]
	v_mfma_f32_32x32x16_bf16 v[96:111], v[218:221], v[210:213], v[96:111]
	global_load_dwordx4 v[172:175], v[148:149], off offset:512
	global_load_dwordx4 v[210:213], v[150:151], off offset:512
	s_waitcnt vmcnt(9)
	ds_write_b128 v164, v[186:189]
	s_waitcnt vmcnt(8)
	ds_write_b128 v164, v[194:197] offset:9216
	ds_read_b128 v[186:189], v163 offset:36928
	ds_read_b128 v[194:197], v163 offset:41536
	ds_read_b128 v[218:221], v154 offset:64
	ds_read_b128 v[226:229], v154 offset:4672
	ds_read_b128 v[234:237], v154 offset:9280
	ds_read_b128 v[242:245], v154 offset:13888
	v_mfma_f32_32x32x16_bf16 v[80:95], v[230:233], v[182:185], v[80:95]
	v_mfma_f32_32x32x16_bf16 v[64:79], v[230:233], v[214:217], v[64:79]
	v_mfma_f32_32x32x16_bf16 v[48:63], v[238:241], v[182:185], v[48:63]
	v_mfma_f32_32x32x16_bf16 v[32:47], v[238:241], v[214:217], v[32:47]
	s_waitcnt lgkmcnt(8)
	v_mfma_f32_32x32x16_bf16 v[16:31], v[246:249], v[182:185], v[16:31]
	v_mfma_f32_32x32x16_bf16 v[0:15], v[246:249], v[214:217], v[0:15]
	v_mfma_f32_32x32x16_bf16 v[112:127], v[222:225], v[182:185], v[112:127]
	v_mfma_f32_32x32x16_bf16 v[96:111], v[222:225], v[214:217], v[96:111]
	global_load_dwordx4 v[182:185], v[144:145], off offset:512
	global_load_dwordx4 v[214:217], v[146:147], off offset:512
	s_waitcnt vmcnt(9)
	ds_write_b128 v164, v[190:193] offset:18432
	s_waitcnt vmcnt(8)
	ds_write_b128 v164, v[198:201] offset:27648
	ds_read_b128 v[190:193], v163 offset:36960
	ds_read_b128 v[198:201], v163 offset:41568
	ds_read_b128 v[222:225], v154 offset:96
	ds_read_b128 v[230:233], v154 offset:4704
	ds_read_b128 v[238:241], v154 offset:9312
	ds_read_b128 v[246:249], v154 offset:13920
	s_waitcnt lgkmcnt(10)
	v_mfma_f32_32x32x16_bf16 v[80:95], v[226:229], v[186:189], v[80:95]
	v_mfma_f32_32x32x16_bf16 v[64:79], v[226:229], v[194:197], v[64:79]
	s_waitcnt lgkmcnt(9)
	v_mfma_f32_32x32x16_bf16 v[48:63], v[234:237], v[186:189], v[48:63]
	v_mfma_f32_32x32x16_bf16 v[32:47], v[234:237], v[194:197], v[32:47]
	s_waitcnt lgkmcnt(8)
	v_mfma_f32_32x32x16_bf16 v[16:31], v[242:245], v[186:189], v[16:31]
	v_mfma_f32_32x32x16_bf16 v[0:15], v[242:245], v[194:197], v[0:15]
	v_mfma_f32_32x32x16_bf16 v[112:127], v[218:221], v[186:189], v[112:127]
	v_mfma_f32_32x32x16_bf16 v[96:111], v[218:221], v[194:197], v[96:111]
	s_waitcnt vmcnt(7)
	ds_write_b128 v165, v[130:133]
	global_load_dwordx4 v[130:133], v[140:141], off offset:512
	s_waitcnt vmcnt(7)
	ds_write_b128 v166, v[158:161]
	global_load_dwordx4 v[158:161], v[138:139], off offset:512
	s_waitcnt lgkmcnt(4)
	v_mfma_f32_32x32x16_bf16 v[80:95], v[230:233], v[190:193], v[80:95]
	v_mfma_f32_32x32x16_bf16 v[64:79], v[230:233], v[198:201], v[64:79]
	s_waitcnt lgkmcnt(3)
	v_mfma_f32_32x32x16_bf16 v[48:63], v[238:241], v[190:193], v[48:63]
	v_mfma_f32_32x32x16_bf16 v[32:47], v[238:241], v[198:201], v[32:47]
	s_waitcnt lgkmcnt(2)
	v_mfma_f32_32x32x16_bf16 v[16:31], v[246:249], v[190:193], v[16:31]
	v_mfma_f32_32x32x16_bf16 v[0:15], v[246:249], v[198:201], v[0:15]
	v_mfma_f32_32x32x16_bf16 v[112:127], v[222:225], v[190:193], v[112:127]
	v_mfma_f32_32x32x16_bf16 v[96:111], v[222:225], v[198:201], v[96:111]
	global_load_dwordx4 v[186:189], v[134:135], off offset:512
	global_load_dwordx4 v[190:193], v[136:137], off offset:512
	s_waitcnt vmcnt(9)
	ds_write_b128 v167, v[202:205]
	s_waitcnt vmcnt(8)
	ds_write_b128 v168, v[206:209]
	s_waitcnt lgkmcnt(0)
	s_barrier
	ds_read_b128 v[194:197], v169
	ds_read_b128 v[198:201], v169 offset:32
	ds_read_b128 v[202:205], v169 offset:4608
	ds_read_b128 v[206:209], v169 offset:4640
	ds_read_b128 v[218:221], v155
	ds_read_b128 v[222:225], v155 offset:32
	ds_read_b128 v[226:229], v155 offset:4608
	ds_read_b128 v[230:233], v155 offset:4640
	ds_read_b128 v[234:237], v155 offset:9216
	ds_read_b128 v[238:241], v155 offset:9248
	ds_read_b128 v[242:245], v155 offset:13824
	ds_read_b128 v[246:249], v155 offset:13856
	s_waitcnt lgkmcnt(5)
	v_mfma_f32_32x32x16_bf16 v[80:95], v[226:229], v[194:197], v[80:95]
	v_mfma_f32_32x32x16_bf16 v[64:79], v[226:229], v[202:205], v[64:79]
	s_waitcnt lgkmcnt(3)
	v_mfma_f32_32x32x16_bf16 v[48:63], v[234:237], v[194:197], v[48:63]
	v_mfma_f32_32x32x16_bf16 v[32:47], v[234:237], v[202:205], v[32:47]
	s_waitcnt lgkmcnt(1)
	v_mfma_f32_32x32x16_bf16 v[16:31], v[242:245], v[194:197], v[16:31]
	v_mfma_f32_32x32x16_bf16 v[0:15], v[242:245], v[202:205], v[0:15]
	v_mfma_f32_32x32x16_bf16 v[112:127], v[218:221], v[194:197], v[112:127]
	v_mfma_f32_32x32x16_bf16 v[96:111], v[218:221], v[202:205], v[96:111]
	global_load_dwordx4 v[194:197], v[148:149], off offset:640
	global_load_dwordx4 v[202:205], v[150:151], off offset:640
	s_waitcnt vmcnt(9)
	ds_write_b128 v128, v[172:175]
	s_waitcnt vmcnt(8)
	ds_write_b128 v128, v[210:213] offset:9216
	ds_read_b128 v[172:175], v169 offset:64
	ds_read_b128 v[210:213], v169 offset:4672
	ds_read_b128 v[218:221], v155 offset:64
	ds_read_b128 v[226:229], v155 offset:4672
	ds_read_b128 v[234:237], v155 offset:9280
	ds_read_b128 v[242:245], v155 offset:13888
	v_mfma_f32_32x32x16_bf16 v[80:95], v[230:233], v[198:201], v[80:95]
	v_mfma_f32_32x32x16_bf16 v[64:79], v[230:233], v[206:209], v[64:79]
	v_mfma_f32_32x32x16_bf16 v[48:63], v[238:241], v[198:201], v[48:63]
	v_mfma_f32_32x32x16_bf16 v[32:47], v[238:241], v[206:209], v[32:47]
	s_waitcnt lgkmcnt(8)
	v_mfma_f32_32x32x16_bf16 v[16:31], v[246:249], v[198:201], v[16:31]
	v_mfma_f32_32x32x16_bf16 v[0:15], v[246:249], v[206:209], v[0:15]
	v_mfma_f32_32x32x16_bf16 v[112:127], v[222:225], v[198:201], v[112:127]
	v_mfma_f32_32x32x16_bf16 v[96:111], v[222:225], v[206:209], v[96:111]
	global_load_dwordx4 v[198:201], v[144:145], off offset:640
	global_load_dwordx4 v[206:209], v[146:147], off offset:640
	s_waitcnt vmcnt(9)
	ds_write_b128 v128, v[182:185] offset:18432
	s_waitcnt vmcnt(8)
	ds_write_b128 v128, v[214:217] offset:27648
	ds_read_b128 v[182:185], v169 offset:96
	ds_read_b128 v[214:217], v169 offset:4704
	ds_read_b128 v[222:225], v155 offset:96
	ds_read_b128 v[230:233], v155 offset:4704
	ds_read_b128 v[238:241], v155 offset:9312
	ds_read_b128 v[246:249], v155 offset:13920
	s_waitcnt lgkmcnt(10)
	v_mfma_f32_32x32x16_bf16 v[80:95], v[226:229], v[172:175], v[80:95]
	v_mfma_f32_32x32x16_bf16 v[64:79], v[226:229], v[210:213], v[64:79]
	s_waitcnt lgkmcnt(9)
	v_mfma_f32_32x32x16_bf16 v[48:63], v[234:237], v[172:175], v[48:63]
	v_mfma_f32_32x32x16_bf16 v[32:47], v[234:237], v[210:213], v[32:47]
	s_waitcnt lgkmcnt(8)
	v_mfma_f32_32x32x16_bf16 v[16:31], v[242:245], v[172:175], v[16:31]
	v_mfma_f32_32x32x16_bf16 v[0:15], v[242:245], v[210:213], v[0:15]
	v_mfma_f32_32x32x16_bf16 v[112:127], v[218:221], v[172:175], v[112:127]
	v_mfma_f32_32x32x16_bf16 v[96:111], v[218:221], v[210:213], v[96:111]
	s_waitcnt vmcnt(7)
	ds_write_b128 v128, v[130:133] offset:36864
	global_load_dwordx4 v[130:133], v[140:141], off offset:640
	s_waitcnt vmcnt(7)
	ds_write_b128 v128, v[158:161] offset:46080
	global_load_dwordx4 v[158:161], v[138:139], off offset:640
	s_waitcnt lgkmcnt(4)
	v_mfma_f32_32x32x16_bf16 v[80:95], v[230:233], v[182:185], v[80:95]
	v_mfma_f32_32x32x16_bf16 v[64:79], v[230:233], v[214:217], v[64:79]
	s_waitcnt lgkmcnt(3)
	v_mfma_f32_32x32x16_bf16 v[48:63], v[238:241], v[182:185], v[48:63]
	v_mfma_f32_32x32x16_bf16 v[32:47], v[238:241], v[214:217], v[32:47]
	s_waitcnt lgkmcnt(2)
	v_mfma_f32_32x32x16_bf16 v[16:31], v[246:249], v[182:185], v[16:31]
	v_mfma_f32_32x32x16_bf16 v[0:15], v[246:249], v[214:217], v[0:15]
	v_mfma_f32_32x32x16_bf16 v[112:127], v[222:225], v[182:185], v[112:127]
	v_mfma_f32_32x32x16_bf16 v[96:111], v[222:225], v[214:217], v[96:111]
	global_load_dwordx4 v[172:175], v[134:135], off offset:640
	global_load_dwordx4 v[182:185], v[136:137], off offset:640
	s_waitcnt vmcnt(9)
	ds_write_b128 v128, v[186:189] offset:55296
	s_waitcnt vmcnt(8)
	ds_write_b128 v128, v[190:193] offset:64512
	s_waitcnt lgkmcnt(0)
	s_barrier
	ds_read_b128 v[186:189], v163 offset:36864
	ds_read_b128 v[190:193], v163 offset:36896
	ds_read_b128 v[210:213], v163 offset:41472
	ds_read_b128 v[214:217], v163 offset:41504
	ds_read_b128 v[218:221], v154
	ds_read_b128 v[222:225], v154 offset:32
	ds_read_b128 v[226:229], v154 offset:4608
	ds_read_b128 v[230:233], v154 offset:4640
	ds_read_b128 v[234:237], v154 offset:9216
	ds_read_b128 v[238:241], v154 offset:9248
	ds_read_b128 v[242:245], v154 offset:13824
	ds_read_b128 v[246:249], v154 offset:13856
	s_waitcnt lgkmcnt(5)
	v_mfma_f32_32x32x16_bf16 v[80:95], v[226:229], v[186:189], v[80:95]
	v_mfma_f32_32x32x16_bf16 v[64:79], v[226:229], v[210:213], v[64:79]
	s_waitcnt lgkmcnt(3)
	v_mfma_f32_32x32x16_bf16 v[48:63], v[234:237], v[186:189], v[48:63]
	v_mfma_f32_32x32x16_bf16 v[32:47], v[234:237], v[210:213], v[32:47]
	s_waitcnt lgkmcnt(1)
	v_mfma_f32_32x32x16_bf16 v[16:31], v[242:245], v[186:189], v[16:31]
	v_mfma_f32_32x32x16_bf16 v[0:15], v[242:245], v[210:213], v[0:15]
	v_mfma_f32_32x32x16_bf16 v[112:127], v[218:221], v[186:189], v[112:127]
	v_mfma_f32_32x32x16_bf16 v[96:111], v[218:221], v[210:213], v[96:111]
	global_load_dwordx4 v[186:189], v[148:149], off offset:768
	global_load_dwordx4 v[210:213], v[150:151], off offset:768
	s_waitcnt vmcnt(9)
	ds_write_b128 v164, v[194:197]
	s_waitcnt vmcnt(8)
	ds_write_b128 v164, v[202:205] offset:9216
	ds_read_b128 v[194:197], v163 offset:36928
	ds_read_b128 v[202:205], v163 offset:41536
	ds_read_b128 v[218:221], v154 offset:64
	ds_read_b128 v[226:229], v154 offset:4672
	ds_read_b128 v[234:237], v154 offset:9280
	ds_read_b128 v[242:245], v154 offset:13888
	v_mfma_f32_32x32x16_bf16 v[80:95], v[230:233], v[190:193], v[80:95]
	v_mfma_f32_32x32x16_bf16 v[64:79], v[230:233], v[214:217], v[64:79]
	v_mfma_f32_32x32x16_bf16 v[48:63], v[238:241], v[190:193], v[48:63]
	v_mfma_f32_32x32x16_bf16 v[32:47], v[238:241], v[214:217], v[32:47]
	s_waitcnt lgkmcnt(8)
	v_mfma_f32_32x32x16_bf16 v[16:31], v[246:249], v[190:193], v[16:31]
	v_mfma_f32_32x32x16_bf16 v[0:15], v[246:249], v[214:217], v[0:15]
	v_mfma_f32_32x32x16_bf16 v[112:127], v[222:225], v[190:193], v[112:127]
	v_mfma_f32_32x32x16_bf16 v[96:111], v[222:225], v[214:217], v[96:111]
	global_load_dwordx4 v[190:193], v[144:145], off offset:768
	global_load_dwordx4 v[214:217], v[146:147], off offset:768
	s_waitcnt vmcnt(9)
	ds_write_b128 v164, v[198:201] offset:18432
	s_waitcnt vmcnt(8)
	ds_write_b128 v164, v[206:209] offset:27648
	ds_read_b128 v[198:201], v163 offset:36960
	ds_read_b128 v[206:209], v163 offset:41568
	ds_read_b128 v[222:225], v154 offset:96
	ds_read_b128 v[230:233], v154 offset:4704
	ds_read_b128 v[238:241], v154 offset:9312
	ds_read_b128 v[246:249], v154 offset:13920
	s_waitcnt lgkmcnt(10)
	v_mfma_f32_32x32x16_bf16 v[80:95], v[226:229], v[194:197], v[80:95]
	v_mfma_f32_32x32x16_bf16 v[64:79], v[226:229], v[202:205], v[64:79]
	s_waitcnt lgkmcnt(9)
	v_mfma_f32_32x32x16_bf16 v[48:63], v[234:237], v[194:197], v[48:63]
	v_mfma_f32_32x32x16_bf16 v[32:47], v[234:237], v[202:205], v[32:47]
	s_waitcnt lgkmcnt(8)
	v_mfma_f32_32x32x16_bf16 v[16:31], v[242:245], v[194:197], v[16:31]
	v_mfma_f32_32x32x16_bf16 v[0:15], v[242:245], v[202:205], v[0:15]
	v_mfma_f32_32x32x16_bf16 v[112:127], v[218:221], v[194:197], v[112:127]
	v_mfma_f32_32x32x16_bf16 v[96:111], v[218:221], v[202:205], v[96:111]
	s_waitcnt vmcnt(7)
	ds_write_b128 v165, v[130:133]
	global_load_dwordx4 v[130:133], v[140:141], off offset:768
	s_waitcnt vmcnt(7)
	ds_write_b128 v166, v[158:161]
	global_load_dwordx4 v[158:161], v[138:139], off offset:768
	s_waitcnt lgkmcnt(4)
	v_mfma_f32_32x32x16_bf16 v[80:95], v[230:233], v[198:201], v[80:95]
	v_mfma_f32_32x32x16_bf16 v[64:79], v[230:233], v[206:209], v[64:79]
	s_waitcnt lgkmcnt(3)
	v_mfma_f32_32x32x16_bf16 v[48:63], v[238:241], v[198:201], v[48:63]
	v_mfma_f32_32x32x16_bf16 v[32:47], v[238:241], v[206:209], v[32:47]
	s_waitcnt lgkmcnt(2)
	v_mfma_f32_32x32x16_bf16 v[16:31], v[246:249], v[198:201], v[16:31]
	v_mfma_f32_32x32x16_bf16 v[0:15], v[246:249], v[206:209], v[0:15]
	v_mfma_f32_32x32x16_bf16 v[112:127], v[222:225], v[198:201], v[112:127]
	v_mfma_f32_32x32x16_bf16 v[96:111], v[222:225], v[206:209], v[96:111]
	global_load_dwordx4 v[194:197], v[134:135], off offset:768
	global_load_dwordx4 v[198:201], v[136:137], off offset:768
	s_waitcnt vmcnt(9)
	ds_write_b128 v167, v[172:175]
	s_waitcnt vmcnt(8)
	ds_write_b128 v168, v[182:185]
	s_waitcnt lgkmcnt(0)
	s_barrier
	ds_read_b128 v[172:175], v169
	ds_read_b128 v[182:185], v169 offset:32
	ds_read_b128 v[202:205], v169 offset:4608
	ds_read_b128 v[206:209], v169 offset:4640
	ds_read_b128 v[218:221], v155
	ds_read_b128 v[222:225], v155 offset:32
	ds_read_b128 v[226:229], v155 offset:4608
	ds_read_b128 v[230:233], v155 offset:4640
	ds_read_b128 v[234:237], v155 offset:9216
	ds_read_b128 v[238:241], v155 offset:9248
	ds_read_b128 v[242:245], v155 offset:13824
	ds_read_b128 v[246:249], v155 offset:13856
	s_waitcnt lgkmcnt(5)
	v_mfma_f32_32x32x16_bf16 v[80:95], v[226:229], v[172:175], v[80:95]
	v_mfma_f32_32x32x16_bf16 v[64:79], v[226:229], v[202:205], v[64:79]
	s_waitcnt lgkmcnt(3)
	v_mfma_f32_32x32x16_bf16 v[48:63], v[234:237], v[172:175], v[48:63]
	v_mfma_f32_32x32x16_bf16 v[32:47], v[234:237], v[202:205], v[32:47]
	s_waitcnt lgkmcnt(1)
	v_mfma_f32_32x32x16_bf16 v[16:31], v[242:245], v[172:175], v[16:31]
	v_mfma_f32_32x32x16_bf16 v[0:15], v[242:245], v[202:205], v[0:15]
	v_mfma_f32_32x32x16_bf16 v[112:127], v[218:221], v[172:175], v[112:127]
	v_mfma_f32_32x32x16_bf16 v[96:111], v[218:221], v[202:205], v[96:111]
	global_load_dwordx4 v[172:175], v[148:149], off offset:896
	global_load_dwordx4 v[202:205], v[150:151], off offset:896
	s_waitcnt vmcnt(9)
	ds_write_b128 v128, v[186:189]
	s_waitcnt vmcnt(8)
	ds_write_b128 v128, v[210:213] offset:9216
	ds_read_b128 v[186:189], v169 offset:64
	ds_read_b128 v[210:213], v169 offset:4672
	ds_read_b128 v[218:221], v155 offset:64
	ds_read_b128 v[226:229], v155 offset:4672
	ds_read_b128 v[234:237], v155 offset:9280
	ds_read_b128 v[242:245], v155 offset:13888
	v_mfma_f32_32x32x16_bf16 v[80:95], v[230:233], v[182:185], v[80:95]
	v_mfma_f32_32x32x16_bf16 v[64:79], v[230:233], v[206:209], v[64:79]
	v_mfma_f32_32x32x16_bf16 v[48:63], v[238:241], v[182:185], v[48:63]
	v_mfma_f32_32x32x16_bf16 v[32:47], v[238:241], v[206:209], v[32:47]
	s_waitcnt lgkmcnt(8)
	v_mfma_f32_32x32x16_bf16 v[16:31], v[246:249], v[182:185], v[16:31]
	v_mfma_f32_32x32x16_bf16 v[0:15], v[246:249], v[206:209], v[0:15]
	v_mfma_f32_32x32x16_bf16 v[112:127], v[222:225], v[182:185], v[112:127]
	v_mfma_f32_32x32x16_bf16 v[96:111], v[222:225], v[206:209], v[96:111]
	global_load_dwordx4 v[182:185], v[144:145], off offset:896
	global_load_dwordx4 v[206:209], v[146:147], off offset:896
	s_waitcnt vmcnt(9)
	ds_write_b128 v128, v[190:193] offset:18432
	s_waitcnt vmcnt(8)
	ds_write_b128 v128, v[214:217] offset:27648
	ds_read_b128 v[190:193], v169 offset:96
	ds_read_b128 v[214:217], v169 offset:4704
	ds_read_b128 v[222:225], v155 offset:96
	ds_read_b128 v[230:233], v155 offset:4704
	ds_read_b128 v[238:241], v155 offset:9312
	ds_read_b128 v[246:249], v155 offset:13920
	s_waitcnt lgkmcnt(10)
	v_mfma_f32_32x32x16_bf16 v[80:95], v[226:229], v[186:189], v[80:95]
	v_mfma_f32_32x32x16_bf16 v[64:79], v[226:229], v[210:213], v[64:79]
	s_waitcnt lgkmcnt(9)
	v_mfma_f32_32x32x16_bf16 v[48:63], v[234:237], v[186:189], v[48:63]
	v_mfma_f32_32x32x16_bf16 v[32:47], v[234:237], v[210:213], v[32:47]
	s_waitcnt lgkmcnt(8)
	v_mfma_f32_32x32x16_bf16 v[16:31], v[242:245], v[186:189], v[16:31]
	v_mfma_f32_32x32x16_bf16 v[0:15], v[242:245], v[210:213], v[0:15]
	v_mfma_f32_32x32x16_bf16 v[112:127], v[218:221], v[186:189], v[112:127]
	v_mfma_f32_32x32x16_bf16 v[96:111], v[218:221], v[210:213], v[96:111]
	s_waitcnt vmcnt(7)
	ds_write_b128 v128, v[130:133] offset:36864
	global_load_dwordx4 v[130:133], v[140:141], off offset:896
	s_waitcnt vmcnt(7)
	ds_write_b128 v128, v[158:161] offset:46080
	global_load_dwordx4 v[158:161], v[138:139], off offset:896
	s_waitcnt lgkmcnt(4)
	v_mfma_f32_32x32x16_bf16 v[80:95], v[230:233], v[190:193], v[80:95]
	v_mfma_f32_32x32x16_bf16 v[64:79], v[230:233], v[214:217], v[64:79]
	s_waitcnt lgkmcnt(3)
	v_mfma_f32_32x32x16_bf16 v[48:63], v[238:241], v[190:193], v[48:63]
	v_mfma_f32_32x32x16_bf16 v[32:47], v[238:241], v[214:217], v[32:47]
	s_waitcnt lgkmcnt(2)
	v_mfma_f32_32x32x16_bf16 v[16:31], v[246:249], v[190:193], v[16:31]
	v_mfma_f32_32x32x16_bf16 v[0:15], v[246:249], v[214:217], v[0:15]
	v_mfma_f32_32x32x16_bf16 v[112:127], v[222:225], v[190:193], v[112:127]
	v_mfma_f32_32x32x16_bf16 v[96:111], v[222:225], v[214:217], v[96:111]
	global_load_dwordx4 v[186:189], v[134:135], off offset:896
	global_load_dwordx4 v[190:193], v[136:137], off offset:896
	s_waitcnt vmcnt(9)
	ds_write_b128 v128, v[194:197] offset:55296
	s_waitcnt vmcnt(8)
	ds_write_b128 v128, v[198:201] offset:64512
	s_waitcnt lgkmcnt(0)
	s_barrier
	ds_read_b128 v[194:197], v163 offset:36864
	ds_read_b128 v[198:201], v163 offset:36896
	ds_read_b128 v[210:213], v163 offset:41472
	ds_read_b128 v[214:217], v163 offset:41504
	ds_read_b128 v[218:221], v154
	ds_read_b128 v[222:225], v154 offset:32
	ds_read_b128 v[226:229], v154 offset:4608
	ds_read_b128 v[230:233], v154 offset:4640
	ds_read_b128 v[234:237], v154 offset:9216
	ds_read_b128 v[238:241], v154 offset:9248
	ds_read_b128 v[242:245], v154 offset:13824
	ds_read_b128 v[246:249], v154 offset:13856
	s_waitcnt lgkmcnt(5)
	v_mfma_f32_32x32x16_bf16 v[80:95], v[226:229], v[194:197], v[80:95]
	v_mfma_f32_32x32x16_bf16 v[64:79], v[226:229], v[210:213], v[64:79]
	s_waitcnt lgkmcnt(3)
	v_mfma_f32_32x32x16_bf16 v[48:63], v[234:237], v[194:197], v[48:63]
	v_mfma_f32_32x32x16_bf16 v[32:47], v[234:237], v[210:213], v[32:47]
	s_waitcnt lgkmcnt(1)
	v_mfma_f32_32x32x16_bf16 v[16:31], v[242:245], v[194:197], v[16:31]
	v_mfma_f32_32x32x16_bf16 v[0:15], v[242:245], v[210:213], v[0:15]
	v_mfma_f32_32x32x16_bf16 v[112:127], v[218:221], v[194:197], v[112:127]
	v_mfma_f32_32x32x16_bf16 v[96:111], v[218:221], v[210:213], v[96:111]
	global_load_dwordx4 v[194:197], v[148:149], off offset:1024
	global_load_dwordx4 v[210:213], v[150:151], off offset:1024
	s_waitcnt vmcnt(9)
	ds_write_b128 v164, v[172:175]
	s_waitcnt vmcnt(8)
	ds_write_b128 v164, v[202:205] offset:9216
	ds_read_b128 v[172:175], v163 offset:36928
	ds_read_b128 v[202:205], v163 offset:41536
	ds_read_b128 v[218:221], v154 offset:64
	ds_read_b128 v[226:229], v154 offset:4672
	ds_read_b128 v[234:237], v154 offset:9280
	ds_read_b128 v[242:245], v154 offset:13888
	v_mfma_f32_32x32x16_bf16 v[80:95], v[230:233], v[198:201], v[80:95]
	v_mfma_f32_32x32x16_bf16 v[64:79], v[230:233], v[214:217], v[64:79]
	v_mfma_f32_32x32x16_bf16 v[48:63], v[238:241], v[198:201], v[48:63]
	v_mfma_f32_32x32x16_bf16 v[32:47], v[238:241], v[214:217], v[32:47]
	s_waitcnt lgkmcnt(8)
	v_mfma_f32_32x32x16_bf16 v[16:31], v[246:249], v[198:201], v[16:31]
	v_mfma_f32_32x32x16_bf16 v[0:15], v[246:249], v[214:217], v[0:15]
	v_mfma_f32_32x32x16_bf16 v[112:127], v[222:225], v[198:201], v[112:127]
	v_mfma_f32_32x32x16_bf16 v[96:111], v[222:225], v[214:217], v[96:111]
	global_load_dwordx4 v[198:201], v[144:145], off offset:1024
	global_load_dwordx4 v[214:217], v[146:147], off offset:1024
	s_waitcnt vmcnt(9)
	ds_write_b128 v164, v[182:185] offset:18432
	s_waitcnt vmcnt(8)
	ds_write_b128 v164, v[206:209] offset:27648
	ds_read_b128 v[182:185], v163 offset:36960
	ds_read_b128 v[206:209], v163 offset:41568
	ds_read_b128 v[222:225], v154 offset:96
	ds_read_b128 v[230:233], v154 offset:4704
	ds_read_b128 v[238:241], v154 offset:9312
	ds_read_b128 v[246:249], v154 offset:13920
	s_waitcnt lgkmcnt(10)
	v_mfma_f32_32x32x16_bf16 v[80:95], v[226:229], v[172:175], v[80:95]
	v_mfma_f32_32x32x16_bf16 v[64:79], v[226:229], v[202:205], v[64:79]
	s_waitcnt lgkmcnt(9)
	v_mfma_f32_32x32x16_bf16 v[48:63], v[234:237], v[172:175], v[48:63]
	v_mfma_f32_32x32x16_bf16 v[32:47], v[234:237], v[202:205], v[32:47]
	s_waitcnt lgkmcnt(8)
	v_mfma_f32_32x32x16_bf16 v[16:31], v[242:245], v[172:175], v[16:31]
	v_mfma_f32_32x32x16_bf16 v[0:15], v[242:245], v[202:205], v[0:15]
	v_mfma_f32_32x32x16_bf16 v[112:127], v[218:221], v[172:175], v[112:127]
	v_mfma_f32_32x32x16_bf16 v[96:111], v[218:221], v[202:205], v[96:111]
	s_waitcnt vmcnt(7)
	ds_write_b128 v165, v[130:133]
	global_load_dwordx4 v[130:133], v[140:141], off offset:1024
	s_waitcnt vmcnt(7)
	ds_write_b128 v166, v[158:161]
	global_load_dwordx4 v[158:161], v[138:139], off offset:1024
	s_waitcnt lgkmcnt(4)
	v_mfma_f32_32x32x16_bf16 v[80:95], v[230:233], v[182:185], v[80:95]
	v_mfma_f32_32x32x16_bf16 v[64:79], v[230:233], v[206:209], v[64:79]
	s_waitcnt lgkmcnt(3)
	v_mfma_f32_32x32x16_bf16 v[48:63], v[238:241], v[182:185], v[48:63]
	v_mfma_f32_32x32x16_bf16 v[32:47], v[238:241], v[206:209], v[32:47]
	s_waitcnt lgkmcnt(2)
	v_mfma_f32_32x32x16_bf16 v[16:31], v[246:249], v[182:185], v[16:31]
	v_mfma_f32_32x32x16_bf16 v[0:15], v[246:249], v[206:209], v[0:15]
	v_mfma_f32_32x32x16_bf16 v[112:127], v[222:225], v[182:185], v[112:127]
	v_mfma_f32_32x32x16_bf16 v[96:111], v[222:225], v[206:209], v[96:111]
	global_load_dwordx4 v[172:175], v[134:135], off offset:1024
	global_load_dwordx4 v[182:185], v[136:137], off offset:1024
	s_waitcnt vmcnt(9)
	ds_write_b128 v167, v[186:189]
	s_waitcnt vmcnt(8)
	ds_write_b128 v168, v[190:193]
	s_waitcnt lgkmcnt(0)
	s_barrier
	ds_read_b128 v[186:189], v169
	ds_read_b128 v[190:193], v169 offset:32
	ds_read_b128 v[202:205], v169 offset:4608
	ds_read_b128 v[206:209], v169 offset:4640
	ds_read_b128 v[218:221], v155
	ds_read_b128 v[222:225], v155 offset:32
	ds_read_b128 v[226:229], v155 offset:4608
	ds_read_b128 v[230:233], v155 offset:4640
	ds_read_b128 v[234:237], v155 offset:9216
	ds_read_b128 v[238:241], v155 offset:9248
	ds_read_b128 v[242:245], v155 offset:13824
	ds_read_b128 v[246:249], v155 offset:13856
	s_waitcnt lgkmcnt(5)
	v_mfma_f32_32x32x16_bf16 v[80:95], v[226:229], v[186:189], v[80:95]
	v_mfma_f32_32x32x16_bf16 v[64:79], v[226:229], v[202:205], v[64:79]
	s_waitcnt lgkmcnt(3)
	v_mfma_f32_32x32x16_bf16 v[48:63], v[234:237], v[186:189], v[48:63]
	v_mfma_f32_32x32x16_bf16 v[32:47], v[234:237], v[202:205], v[32:47]
	s_waitcnt lgkmcnt(1)
	v_mfma_f32_32x32x16_bf16 v[16:31], v[242:245], v[186:189], v[16:31]
	v_mfma_f32_32x32x16_bf16 v[0:15], v[242:245], v[202:205], v[0:15]
	v_mfma_f32_32x32x16_bf16 v[112:127], v[218:221], v[186:189], v[112:127]
	v_mfma_f32_32x32x16_bf16 v[96:111], v[218:221], v[202:205], v[96:111]
	global_load_dwordx4 v[186:189], v[148:149], off offset:1152
	global_load_dwordx4 v[202:205], v[150:151], off offset:1152
	s_waitcnt vmcnt(9)
	ds_write_b128 v128, v[194:197]
	s_waitcnt vmcnt(8)
	ds_write_b128 v128, v[210:213] offset:9216
	ds_read_b128 v[194:197], v169 offset:64
	ds_read_b128 v[210:213], v169 offset:4672
	ds_read_b128 v[218:221], v155 offset:64
	ds_read_b128 v[226:229], v155 offset:4672
	ds_read_b128 v[234:237], v155 offset:9280
	ds_read_b128 v[242:245], v155 offset:13888
	v_mfma_f32_32x32x16_bf16 v[80:95], v[230:233], v[190:193], v[80:95]
	v_mfma_f32_32x32x16_bf16 v[64:79], v[230:233], v[206:209], v[64:79]
	v_mfma_f32_32x32x16_bf16 v[48:63], v[238:241], v[190:193], v[48:63]
	v_mfma_f32_32x32x16_bf16 v[32:47], v[238:241], v[206:209], v[32:47]
	s_waitcnt lgkmcnt(8)
	v_mfma_f32_32x32x16_bf16 v[16:31], v[246:249], v[190:193], v[16:31]
	v_mfma_f32_32x32x16_bf16 v[0:15], v[246:249], v[206:209], v[0:15]
	v_mfma_f32_32x32x16_bf16 v[112:127], v[222:225], v[190:193], v[112:127]
	v_mfma_f32_32x32x16_bf16 v[96:111], v[222:225], v[206:209], v[96:111]
	global_load_dwordx4 v[190:193], v[144:145], off offset:1152
	global_load_dwordx4 v[206:209], v[146:147], off offset:1152
	s_waitcnt vmcnt(9)
	ds_write_b128 v128, v[198:201] offset:18432
	s_waitcnt vmcnt(8)
	ds_write_b128 v128, v[214:217] offset:27648
	ds_read_b128 v[198:201], v169 offset:96
	ds_read_b128 v[214:217], v169 offset:4704
	ds_read_b128 v[222:225], v155 offset:96
	ds_read_b128 v[230:233], v155 offset:4704
	ds_read_b128 v[238:241], v155 offset:9312
	ds_read_b128 v[246:249], v155 offset:13920
	s_waitcnt lgkmcnt(10)
	v_mfma_f32_32x32x16_bf16 v[80:95], v[226:229], v[194:197], v[80:95]
	v_mfma_f32_32x32x16_bf16 v[64:79], v[226:229], v[210:213], v[64:79]
	s_waitcnt lgkmcnt(9)
	v_mfma_f32_32x32x16_bf16 v[48:63], v[234:237], v[194:197], v[48:63]
	v_mfma_f32_32x32x16_bf16 v[32:47], v[234:237], v[210:213], v[32:47]
	s_waitcnt lgkmcnt(8)
	v_mfma_f32_32x32x16_bf16 v[16:31], v[242:245], v[194:197], v[16:31]
	v_mfma_f32_32x32x16_bf16 v[0:15], v[242:245], v[210:213], v[0:15]
	v_mfma_f32_32x32x16_bf16 v[112:127], v[218:221], v[194:197], v[112:127]
	v_mfma_f32_32x32x16_bf16 v[96:111], v[218:221], v[210:213], v[96:111]
	s_waitcnt vmcnt(7)
	ds_write_b128 v128, v[130:133] offset:36864
	global_load_dwordx4 v[130:133], v[140:141], off offset:1152
	s_waitcnt vmcnt(7)
	ds_write_b128 v128, v[158:161] offset:46080
	global_load_dwordx4 v[158:161], v[138:139], off offset:1152
	s_waitcnt lgkmcnt(4)
	v_mfma_f32_32x32x16_bf16 v[80:95], v[230:233], v[198:201], v[80:95]
	v_mfma_f32_32x32x16_bf16 v[64:79], v[230:233], v[214:217], v[64:79]
	s_waitcnt lgkmcnt(3)
	v_mfma_f32_32x32x16_bf16 v[48:63], v[238:241], v[198:201], v[48:63]
	v_mfma_f32_32x32x16_bf16 v[32:47], v[238:241], v[214:217], v[32:47]
	s_waitcnt lgkmcnt(2)
	v_mfma_f32_32x32x16_bf16 v[16:31], v[246:249], v[198:201], v[16:31]
	v_mfma_f32_32x32x16_bf16 v[0:15], v[246:249], v[214:217], v[0:15]
	v_mfma_f32_32x32x16_bf16 v[112:127], v[222:225], v[198:201], v[112:127]
	v_mfma_f32_32x32x16_bf16 v[96:111], v[222:225], v[214:217], v[96:111]
	global_load_dwordx4 v[194:197], v[134:135], off offset:1152
	global_load_dwordx4 v[198:201], v[136:137], off offset:1152
	s_waitcnt vmcnt(9)
	ds_write_b128 v128, v[172:175] offset:55296
	s_waitcnt vmcnt(8)
	ds_write_b128 v128, v[182:185] offset:64512
	s_waitcnt lgkmcnt(0)
	s_barrier
	ds_read_b128 v[172:175], v163 offset:36864
	ds_read_b128 v[182:185], v163 offset:36896
	ds_read_b128 v[210:213], v163 offset:41472
	ds_read_b128 v[214:217], v163 offset:41504
	ds_read_b128 v[218:221], v154
	ds_read_b128 v[222:225], v154 offset:32
	ds_read_b128 v[226:229], v154 offset:4608
	ds_read_b128 v[230:233], v154 offset:4640
	ds_read_b128 v[234:237], v154 offset:9216
	ds_read_b128 v[238:241], v154 offset:9248
	ds_read_b128 v[242:245], v154 offset:13824
	ds_read_b128 v[246:249], v154 offset:13856
	s_waitcnt lgkmcnt(5)
	v_mfma_f32_32x32x16_bf16 v[80:95], v[226:229], v[172:175], v[80:95]
	v_mfma_f32_32x32x16_bf16 v[64:79], v[226:229], v[210:213], v[64:79]
	s_waitcnt lgkmcnt(3)
	v_mfma_f32_32x32x16_bf16 v[48:63], v[234:237], v[172:175], v[48:63]
	v_mfma_f32_32x32x16_bf16 v[32:47], v[234:237], v[210:213], v[32:47]
	s_waitcnt lgkmcnt(1)
	v_mfma_f32_32x32x16_bf16 v[16:31], v[242:245], v[172:175], v[16:31]
	v_mfma_f32_32x32x16_bf16 v[0:15], v[242:245], v[210:213], v[0:15]
	v_mfma_f32_32x32x16_bf16 v[112:127], v[218:221], v[172:175], v[112:127]
	v_mfma_f32_32x32x16_bf16 v[96:111], v[218:221], v[210:213], v[96:111]
	global_load_dwordx4 v[172:175], v[148:149], off offset:1280
	global_load_dwordx4 v[210:213], v[150:151], off offset:1280
	s_waitcnt vmcnt(9)
	ds_write_b128 v164, v[186:189]
	s_waitcnt vmcnt(8)
	ds_write_b128 v164, v[202:205] offset:9216
	ds_read_b128 v[186:189], v163 offset:36928
	ds_read_b128 v[202:205], v163 offset:41536
	ds_read_b128 v[218:221], v154 offset:64
	ds_read_b128 v[226:229], v154 offset:4672
	ds_read_b128 v[234:237], v154 offset:9280
	ds_read_b128 v[242:245], v154 offset:13888
	v_mfma_f32_32x32x16_bf16 v[80:95], v[230:233], v[182:185], v[80:95]
	v_mfma_f32_32x32x16_bf16 v[64:79], v[230:233], v[214:217], v[64:79]
	v_mfma_f32_32x32x16_bf16 v[48:63], v[238:241], v[182:185], v[48:63]
	v_mfma_f32_32x32x16_bf16 v[32:47], v[238:241], v[214:217], v[32:47]
	s_waitcnt lgkmcnt(8)
	v_mfma_f32_32x32x16_bf16 v[16:31], v[246:249], v[182:185], v[16:31]
	v_mfma_f32_32x32x16_bf16 v[0:15], v[246:249], v[214:217], v[0:15]
	v_mfma_f32_32x32x16_bf16 v[112:127], v[222:225], v[182:185], v[112:127]
	v_mfma_f32_32x32x16_bf16 v[96:111], v[222:225], v[214:217], v[96:111]
	global_load_dwordx4 v[182:185], v[144:145], off offset:1280
	global_load_dwordx4 v[214:217], v[146:147], off offset:1280
	s_waitcnt vmcnt(9)
	ds_write_b128 v164, v[190:193] offset:18432
	s_waitcnt vmcnt(8)
	ds_write_b128 v164, v[206:209] offset:27648
	ds_read_b128 v[190:193], v163 offset:36960
	ds_read_b128 v[206:209], v163 offset:41568
	ds_read_b128 v[222:225], v154 offset:96
	ds_read_b128 v[230:233], v154 offset:4704
	ds_read_b128 v[238:241], v154 offset:9312
	ds_read_b128 v[246:249], v154 offset:13920
	s_waitcnt lgkmcnt(10)
	v_mfma_f32_32x32x16_bf16 v[80:95], v[226:229], v[186:189], v[80:95]
	v_mfma_f32_32x32x16_bf16 v[64:79], v[226:229], v[202:205], v[64:79]
	s_waitcnt lgkmcnt(9)
	v_mfma_f32_32x32x16_bf16 v[48:63], v[234:237], v[186:189], v[48:63]
	v_mfma_f32_32x32x16_bf16 v[32:47], v[234:237], v[202:205], v[32:47]
	s_waitcnt lgkmcnt(8)
	v_mfma_f32_32x32x16_bf16 v[16:31], v[242:245], v[186:189], v[16:31]
	v_mfma_f32_32x32x16_bf16 v[0:15], v[242:245], v[202:205], v[0:15]
	v_mfma_f32_32x32x16_bf16 v[112:127], v[218:221], v[186:189], v[112:127]
	v_mfma_f32_32x32x16_bf16 v[96:111], v[218:221], v[202:205], v[96:111]
	s_waitcnt vmcnt(7)
	ds_write_b128 v165, v[130:133]
	global_load_dwordx4 v[130:133], v[140:141], off offset:1280
	s_waitcnt vmcnt(7)
	ds_write_b128 v166, v[158:161]
	global_load_dwordx4 v[158:161], v[138:139], off offset:1280
	s_waitcnt lgkmcnt(4)
	v_mfma_f32_32x32x16_bf16 v[80:95], v[230:233], v[190:193], v[80:95]
	v_mfma_f32_32x32x16_bf16 v[64:79], v[230:233], v[206:209], v[64:79]
	s_waitcnt lgkmcnt(3)
	v_mfma_f32_32x32x16_bf16 v[48:63], v[238:241], v[190:193], v[48:63]
	v_mfma_f32_32x32x16_bf16 v[32:47], v[238:241], v[206:209], v[32:47]
	s_waitcnt lgkmcnt(2)
	v_mfma_f32_32x32x16_bf16 v[16:31], v[246:249], v[190:193], v[16:31]
	v_mfma_f32_32x32x16_bf16 v[0:15], v[246:249], v[206:209], v[0:15]
	v_mfma_f32_32x32x16_bf16 v[112:127], v[222:225], v[190:193], v[112:127]
	v_mfma_f32_32x32x16_bf16 v[96:111], v[222:225], v[206:209], v[96:111]
	global_load_dwordx4 v[186:189], v[134:135], off offset:1280
	global_load_dwordx4 v[190:193], v[136:137], off offset:1280
	s_waitcnt vmcnt(9)
	ds_write_b128 v167, v[194:197]
	s_waitcnt vmcnt(8)
	ds_write_b128 v168, v[198:201]
	s_waitcnt lgkmcnt(0)
	s_barrier
	ds_read_b128 v[194:197], v169
	ds_read_b128 v[198:201], v169 offset:32
	ds_read_b128 v[202:205], v169 offset:4608
	ds_read_b128 v[206:209], v169 offset:4640
	ds_read_b128 v[218:221], v155
	ds_read_b128 v[222:225], v155 offset:32
	ds_read_b128 v[226:229], v155 offset:4608
	ds_read_b128 v[230:233], v155 offset:4640
	ds_read_b128 v[234:237], v155 offset:9216
	ds_read_b128 v[238:241], v155 offset:9248
	ds_read_b128 v[242:245], v155 offset:13824
	ds_read_b128 v[246:249], v155 offset:13856
	s_waitcnt lgkmcnt(5)
	v_mfma_f32_32x32x16_bf16 v[80:95], v[226:229], v[194:197], v[80:95]
	v_mfma_f32_32x32x16_bf16 v[64:79], v[226:229], v[202:205], v[64:79]
	s_waitcnt lgkmcnt(3)
	v_mfma_f32_32x32x16_bf16 v[48:63], v[234:237], v[194:197], v[48:63]
	v_mfma_f32_32x32x16_bf16 v[32:47], v[234:237], v[202:205], v[32:47]
	s_waitcnt lgkmcnt(1)
	v_mfma_f32_32x32x16_bf16 v[16:31], v[242:245], v[194:197], v[16:31]
	v_mfma_f32_32x32x16_bf16 v[0:15], v[242:245], v[202:205], v[0:15]
	v_mfma_f32_32x32x16_bf16 v[112:127], v[218:221], v[194:197], v[112:127]
	v_mfma_f32_32x32x16_bf16 v[96:111], v[218:221], v[202:205], v[96:111]
	global_load_dwordx4 v[194:197], v[148:149], off offset:1408
	global_load_dwordx4 v[202:205], v[150:151], off offset:1408
	s_waitcnt vmcnt(9)
	ds_write_b128 v128, v[172:175]
	s_waitcnt vmcnt(8)
	ds_write_b128 v128, v[210:213] offset:9216
	ds_read_b128 v[172:175], v169 offset:64
	ds_read_b128 v[210:213], v169 offset:4672
	ds_read_b128 v[218:221], v155 offset:64
	ds_read_b128 v[226:229], v155 offset:4672
	ds_read_b128 v[234:237], v155 offset:9280
	ds_read_b128 v[242:245], v155 offset:13888
	v_mfma_f32_32x32x16_bf16 v[80:95], v[230:233], v[198:201], v[80:95]
	v_mfma_f32_32x32x16_bf16 v[64:79], v[230:233], v[206:209], v[64:79]
	v_mfma_f32_32x32x16_bf16 v[48:63], v[238:241], v[198:201], v[48:63]
	v_mfma_f32_32x32x16_bf16 v[32:47], v[238:241], v[206:209], v[32:47]
	s_waitcnt lgkmcnt(8)
	v_mfma_f32_32x32x16_bf16 v[16:31], v[246:249], v[198:201], v[16:31]
	v_mfma_f32_32x32x16_bf16 v[0:15], v[246:249], v[206:209], v[0:15]
	v_mfma_f32_32x32x16_bf16 v[112:127], v[222:225], v[198:201], v[112:127]
	v_mfma_f32_32x32x16_bf16 v[96:111], v[222:225], v[206:209], v[96:111]
	global_load_dwordx4 v[198:201], v[144:145], off offset:1408
	global_load_dwordx4 v[206:209], v[146:147], off offset:1408
	s_waitcnt vmcnt(9)
	ds_write_b128 v128, v[182:185] offset:18432
	s_waitcnt vmcnt(8)
	ds_write_b128 v128, v[214:217] offset:27648
	ds_read_b128 v[182:185], v169 offset:96
	ds_read_b128 v[214:217], v169 offset:4704
	ds_read_b128 v[222:225], v155 offset:96
	ds_read_b128 v[230:233], v155 offset:4704
	ds_read_b128 v[238:241], v155 offset:9312
	ds_read_b128 v[246:249], v155 offset:13920
	s_waitcnt lgkmcnt(10)
	v_mfma_f32_32x32x16_bf16 v[80:95], v[226:229], v[172:175], v[80:95]
	v_mfma_f32_32x32x16_bf16 v[64:79], v[226:229], v[210:213], v[64:79]
	s_waitcnt lgkmcnt(9)
	v_mfma_f32_32x32x16_bf16 v[48:63], v[234:237], v[172:175], v[48:63]
	v_mfma_f32_32x32x16_bf16 v[32:47], v[234:237], v[210:213], v[32:47]
	s_waitcnt lgkmcnt(8)
	v_mfma_f32_32x32x16_bf16 v[16:31], v[242:245], v[172:175], v[16:31]
	v_mfma_f32_32x32x16_bf16 v[0:15], v[242:245], v[210:213], v[0:15]
	v_mfma_f32_32x32x16_bf16 v[112:127], v[218:221], v[172:175], v[112:127]
	v_mfma_f32_32x32x16_bf16 v[96:111], v[218:221], v[210:213], v[96:111]
	s_waitcnt vmcnt(7)
	ds_write_b128 v128, v[130:133] offset:36864
	global_load_dwordx4 v[130:133], v[140:141], off offset:1408
	s_waitcnt vmcnt(7)
	ds_write_b128 v128, v[158:161] offset:46080
	global_load_dwordx4 v[158:161], v[138:139], off offset:1408
	s_waitcnt lgkmcnt(4)
	v_mfma_f32_32x32x16_bf16 v[80:95], v[230:233], v[182:185], v[80:95]
	v_mfma_f32_32x32x16_bf16 v[64:79], v[230:233], v[214:217], v[64:79]
	s_waitcnt lgkmcnt(3)
	v_mfma_f32_32x32x16_bf16 v[48:63], v[238:241], v[182:185], v[48:63]
	v_mfma_f32_32x32x16_bf16 v[32:47], v[238:241], v[214:217], v[32:47]
	s_waitcnt lgkmcnt(2)
	v_mfma_f32_32x32x16_bf16 v[16:31], v[246:249], v[182:185], v[16:31]
	v_mfma_f32_32x32x16_bf16 v[0:15], v[246:249], v[214:217], v[0:15]
	v_mfma_f32_32x32x16_bf16 v[112:127], v[222:225], v[182:185], v[112:127]
	v_mfma_f32_32x32x16_bf16 v[96:111], v[222:225], v[214:217], v[96:111]
	global_load_dwordx4 v[172:175], v[134:135], off offset:1408
	global_load_dwordx4 v[182:185], v[136:137], off offset:1408
	s_waitcnt vmcnt(9)
	ds_write_b128 v128, v[186:189] offset:55296
	s_waitcnt vmcnt(8)
	ds_write_b128 v128, v[190:193] offset:64512
	s_waitcnt lgkmcnt(0)
	s_barrier
	ds_read_b128 v[186:189], v163 offset:36864
	ds_read_b128 v[190:193], v163 offset:36896
	ds_read_b128 v[210:213], v163 offset:41472
	ds_read_b128 v[214:217], v163 offset:41504
	ds_read_b128 v[218:221], v154
	ds_read_b128 v[222:225], v154 offset:32
	ds_read_b128 v[226:229], v154 offset:4608
	ds_read_b128 v[230:233], v154 offset:4640
	ds_read_b128 v[234:237], v154 offset:9216
	ds_read_b128 v[238:241], v154 offset:9248
	ds_read_b128 v[242:245], v154 offset:13824
	ds_read_b128 v[246:249], v154 offset:13856
	s_waitcnt lgkmcnt(5)
	v_mfma_f32_32x32x16_bf16 v[80:95], v[226:229], v[186:189], v[80:95]
	v_mfma_f32_32x32x16_bf16 v[64:79], v[226:229], v[210:213], v[64:79]
	s_waitcnt lgkmcnt(3)
	v_mfma_f32_32x32x16_bf16 v[48:63], v[234:237], v[186:189], v[48:63]
	v_mfma_f32_32x32x16_bf16 v[32:47], v[234:237], v[210:213], v[32:47]
	s_waitcnt lgkmcnt(1)
	v_mfma_f32_32x32x16_bf16 v[16:31], v[242:245], v[186:189], v[16:31]
	v_mfma_f32_32x32x16_bf16 v[0:15], v[242:245], v[210:213], v[0:15]
	v_mfma_f32_32x32x16_bf16 v[112:127], v[218:221], v[186:189], v[112:127]
	v_mfma_f32_32x32x16_bf16 v[96:111], v[218:221], v[210:213], v[96:111]
	global_load_dwordx4 v[186:189], v[148:149], off offset:1536
	global_load_dwordx4 v[210:213], v[150:151], off offset:1536
	s_waitcnt vmcnt(9)
	ds_write_b128 v164, v[194:197]
	s_waitcnt vmcnt(8)
	ds_write_b128 v164, v[202:205] offset:9216
	ds_read_b128 v[194:197], v163 offset:36928
	ds_read_b128 v[202:205], v163 offset:41536
	ds_read_b128 v[218:221], v154 offset:64
	ds_read_b128 v[226:229], v154 offset:4672
	ds_read_b128 v[234:237], v154 offset:9280
	ds_read_b128 v[242:245], v154 offset:13888
	v_mfma_f32_32x32x16_bf16 v[80:95], v[230:233], v[190:193], v[80:95]
	v_mfma_f32_32x32x16_bf16 v[64:79], v[230:233], v[214:217], v[64:79]
	v_mfma_f32_32x32x16_bf16 v[48:63], v[238:241], v[190:193], v[48:63]
	v_mfma_f32_32x32x16_bf16 v[32:47], v[238:241], v[214:217], v[32:47]
	s_waitcnt lgkmcnt(8)
	v_mfma_f32_32x32x16_bf16 v[16:31], v[246:249], v[190:193], v[16:31]
	v_mfma_f32_32x32x16_bf16 v[0:15], v[246:249], v[214:217], v[0:15]
	v_mfma_f32_32x32x16_bf16 v[112:127], v[222:225], v[190:193], v[112:127]
	v_mfma_f32_32x32x16_bf16 v[96:111], v[222:225], v[214:217], v[96:111]
	global_load_dwordx4 v[190:193], v[144:145], off offset:1536
	global_load_dwordx4 v[214:217], v[146:147], off offset:1536
	s_waitcnt vmcnt(9)
	ds_write_b128 v164, v[198:201] offset:18432
	s_waitcnt vmcnt(8)
	ds_write_b128 v164, v[206:209] offset:27648
	ds_read_b128 v[198:201], v163 offset:36960
	ds_read_b128 v[206:209], v163 offset:41568
	ds_read_b128 v[222:225], v154 offset:96
	ds_read_b128 v[230:233], v154 offset:4704
	ds_read_b128 v[238:241], v154 offset:9312
	ds_read_b128 v[246:249], v154 offset:13920
	s_waitcnt lgkmcnt(10)
	v_mfma_f32_32x32x16_bf16 v[80:95], v[226:229], v[194:197], v[80:95]
	v_mfma_f32_32x32x16_bf16 v[64:79], v[226:229], v[202:205], v[64:79]
	s_waitcnt lgkmcnt(9)
	v_mfma_f32_32x32x16_bf16 v[48:63], v[234:237], v[194:197], v[48:63]
	v_mfma_f32_32x32x16_bf16 v[32:47], v[234:237], v[202:205], v[32:47]
	s_waitcnt lgkmcnt(8)
	v_mfma_f32_32x32x16_bf16 v[16:31], v[242:245], v[194:197], v[16:31]
	v_mfma_f32_32x32x16_bf16 v[0:15], v[242:245], v[202:205], v[0:15]
	v_mfma_f32_32x32x16_bf16 v[112:127], v[218:221], v[194:197], v[112:127]
	v_mfma_f32_32x32x16_bf16 v[96:111], v[218:221], v[202:205], v[96:111]
	s_waitcnt vmcnt(7)
	ds_write_b128 v165, v[130:133]
	global_load_dwordx4 v[130:133], v[140:141], off offset:1536
	s_waitcnt vmcnt(7)
	ds_write_b128 v166, v[158:161]
	global_load_dwordx4 v[158:161], v[138:139], off offset:1536
	s_waitcnt lgkmcnt(4)
	v_mfma_f32_32x32x16_bf16 v[80:95], v[230:233], v[198:201], v[80:95]
	v_mfma_f32_32x32x16_bf16 v[64:79], v[230:233], v[206:209], v[64:79]
	s_waitcnt lgkmcnt(3)
	v_mfma_f32_32x32x16_bf16 v[48:63], v[238:241], v[198:201], v[48:63]
	v_mfma_f32_32x32x16_bf16 v[32:47], v[238:241], v[206:209], v[32:47]
	s_waitcnt lgkmcnt(2)
	v_mfma_f32_32x32x16_bf16 v[16:31], v[246:249], v[198:201], v[16:31]
	v_mfma_f32_32x32x16_bf16 v[0:15], v[246:249], v[206:209], v[0:15]
	v_mfma_f32_32x32x16_bf16 v[112:127], v[222:225], v[198:201], v[112:127]
	v_mfma_f32_32x32x16_bf16 v[96:111], v[222:225], v[206:209], v[96:111]
	global_load_dwordx4 v[194:197], v[134:135], off offset:1536
	global_load_dwordx4 v[198:201], v[136:137], off offset:1536
	s_waitcnt vmcnt(9)
	ds_write_b128 v167, v[172:175]
	s_waitcnt vmcnt(8)
	ds_write_b128 v168, v[182:185]
	s_waitcnt lgkmcnt(0)
	s_barrier
	ds_read_b128 v[172:175], v169
	ds_read_b128 v[182:185], v169 offset:32
	ds_read_b128 v[202:205], v169 offset:4608
	ds_read_b128 v[206:209], v169 offset:4640
	ds_read_b128 v[218:221], v155
	ds_read_b128 v[222:225], v155 offset:32
	ds_read_b128 v[226:229], v155 offset:4608
	ds_read_b128 v[230:233], v155 offset:4640
	ds_read_b128 v[234:237], v155 offset:9216
	ds_read_b128 v[238:241], v155 offset:9248
	ds_read_b128 v[242:245], v155 offset:13824
	ds_read_b128 v[246:249], v155 offset:13856
	s_waitcnt lgkmcnt(5)
	v_mfma_f32_32x32x16_bf16 v[80:95], v[226:229], v[172:175], v[80:95]
	v_mfma_f32_32x32x16_bf16 v[64:79], v[226:229], v[202:205], v[64:79]
	s_waitcnt lgkmcnt(3)
	v_mfma_f32_32x32x16_bf16 v[48:63], v[234:237], v[172:175], v[48:63]
	v_mfma_f32_32x32x16_bf16 v[32:47], v[234:237], v[202:205], v[32:47]
	s_waitcnt lgkmcnt(1)
	v_mfma_f32_32x32x16_bf16 v[16:31], v[242:245], v[172:175], v[16:31]
	v_mfma_f32_32x32x16_bf16 v[0:15], v[242:245], v[202:205], v[0:15]
	v_mfma_f32_32x32x16_bf16 v[112:127], v[218:221], v[172:175], v[112:127]
	v_mfma_f32_32x32x16_bf16 v[96:111], v[218:221], v[202:205], v[96:111]
	global_load_dwordx4 v[172:175], v[148:149], off offset:1664
	global_load_dwordx4 v[202:205], v[150:151], off offset:1664
	s_waitcnt vmcnt(9)
	ds_write_b128 v128, v[186:189]
	s_waitcnt vmcnt(8)
	ds_write_b128 v128, v[210:213] offset:9216
	ds_read_b128 v[186:189], v169 offset:64
	ds_read_b128 v[210:213], v169 offset:4672
	ds_read_b128 v[218:221], v155 offset:64
	ds_read_b128 v[226:229], v155 offset:4672
	ds_read_b128 v[234:237], v155 offset:9280
	ds_read_b128 v[242:245], v155 offset:13888
	v_mfma_f32_32x32x16_bf16 v[80:95], v[230:233], v[182:185], v[80:95]
	v_mfma_f32_32x32x16_bf16 v[64:79], v[230:233], v[206:209], v[64:79]
	v_mfma_f32_32x32x16_bf16 v[48:63], v[238:241], v[182:185], v[48:63]
	v_mfma_f32_32x32x16_bf16 v[32:47], v[238:241], v[206:209], v[32:47]
	s_waitcnt lgkmcnt(8)
	v_mfma_f32_32x32x16_bf16 v[16:31], v[246:249], v[182:185], v[16:31]
	v_mfma_f32_32x32x16_bf16 v[0:15], v[246:249], v[206:209], v[0:15]
	v_mfma_f32_32x32x16_bf16 v[112:127], v[222:225], v[182:185], v[112:127]
	v_mfma_f32_32x32x16_bf16 v[96:111], v[222:225], v[206:209], v[96:111]
	global_load_dwordx4 v[182:185], v[144:145], off offset:1664
	global_load_dwordx4 v[206:209], v[146:147], off offset:1664
	s_waitcnt vmcnt(9)
	ds_write_b128 v128, v[190:193] offset:18432
	s_waitcnt vmcnt(8)
	ds_write_b128 v128, v[214:217] offset:27648
	ds_read_b128 v[190:193], v169 offset:96
	ds_read_b128 v[214:217], v169 offset:4704
	ds_read_b128 v[222:225], v155 offset:96
	ds_read_b128 v[230:233], v155 offset:4704
	ds_read_b128 v[238:241], v155 offset:9312
	ds_read_b128 v[246:249], v155 offset:13920
	s_waitcnt lgkmcnt(10)
	v_mfma_f32_32x32x16_bf16 v[80:95], v[226:229], v[186:189], v[80:95]
	v_mfma_f32_32x32x16_bf16 v[64:79], v[226:229], v[210:213], v[64:79]
	s_waitcnt lgkmcnt(9)
	v_mfma_f32_32x32x16_bf16 v[48:63], v[234:237], v[186:189], v[48:63]
	v_mfma_f32_32x32x16_bf16 v[32:47], v[234:237], v[210:213], v[32:47]
	s_waitcnt lgkmcnt(8)
	v_mfma_f32_32x32x16_bf16 v[16:31], v[242:245], v[186:189], v[16:31]
	v_mfma_f32_32x32x16_bf16 v[0:15], v[242:245], v[210:213], v[0:15]
	v_mfma_f32_32x32x16_bf16 v[112:127], v[218:221], v[186:189], v[112:127]
	v_mfma_f32_32x32x16_bf16 v[96:111], v[218:221], v[210:213], v[96:111]
	s_waitcnt vmcnt(7)
	ds_write_b128 v128, v[130:133] offset:36864
	global_load_dwordx4 v[130:133], v[140:141], off offset:1664
	s_waitcnt vmcnt(7)
	ds_write_b128 v128, v[158:161] offset:46080
	global_load_dwordx4 v[158:161], v[138:139], off offset:1664
	s_waitcnt lgkmcnt(4)
	v_mfma_f32_32x32x16_bf16 v[80:95], v[230:233], v[190:193], v[80:95]
	v_mfma_f32_32x32x16_bf16 v[64:79], v[230:233], v[214:217], v[64:79]
	s_waitcnt lgkmcnt(3)
	v_mfma_f32_32x32x16_bf16 v[48:63], v[238:241], v[190:193], v[48:63]
	v_mfma_f32_32x32x16_bf16 v[32:47], v[238:241], v[214:217], v[32:47]
	s_waitcnt lgkmcnt(2)
	v_mfma_f32_32x32x16_bf16 v[16:31], v[246:249], v[190:193], v[16:31]
	v_mfma_f32_32x32x16_bf16 v[0:15], v[246:249], v[214:217], v[0:15]
	v_mfma_f32_32x32x16_bf16 v[112:127], v[222:225], v[190:193], v[112:127]
	v_mfma_f32_32x32x16_bf16 v[96:111], v[222:225], v[214:217], v[96:111]
	global_load_dwordx4 v[186:189], v[134:135], off offset:1664
	global_load_dwordx4 v[190:193], v[136:137], off offset:1664
	s_waitcnt vmcnt(9)
	ds_write_b128 v128, v[194:197] offset:55296
	s_waitcnt vmcnt(8)
	ds_write_b128 v128, v[198:201] offset:64512
	s_waitcnt lgkmcnt(0)
	s_barrier
	ds_read_b128 v[194:197], v163 offset:36864
	ds_read_b128 v[198:201], v163 offset:36896
	ds_read_b128 v[210:213], v163 offset:41472
	ds_read_b128 v[214:217], v163 offset:41504
	ds_read_b128 v[218:221], v154
	ds_read_b128 v[222:225], v154 offset:32
	ds_read_b128 v[226:229], v154 offset:4608
	ds_read_b128 v[230:233], v154 offset:4640
	ds_read_b128 v[234:237], v154 offset:9216
	ds_read_b128 v[238:241], v154 offset:9248
	ds_read_b128 v[242:245], v154 offset:13824
	ds_read_b128 v[246:249], v154 offset:13856
	s_waitcnt lgkmcnt(5)
	v_mfma_f32_32x32x16_bf16 v[80:95], v[226:229], v[194:197], v[80:95]
	v_mfma_f32_32x32x16_bf16 v[64:79], v[226:229], v[210:213], v[64:79]
	s_waitcnt lgkmcnt(3)
	v_mfma_f32_32x32x16_bf16 v[48:63], v[234:237], v[194:197], v[48:63]
	v_mfma_f32_32x32x16_bf16 v[32:47], v[234:237], v[210:213], v[32:47]
	s_waitcnt lgkmcnt(1)
	v_mfma_f32_32x32x16_bf16 v[16:31], v[242:245], v[194:197], v[16:31]
	v_mfma_f32_32x32x16_bf16 v[0:15], v[242:245], v[210:213], v[0:15]
	v_mfma_f32_32x32x16_bf16 v[112:127], v[218:221], v[194:197], v[112:127]
	v_mfma_f32_32x32x16_bf16 v[96:111], v[218:221], v[210:213], v[96:111]
	global_load_dwordx4 v[194:197], v[148:149], off offset:1792
	global_load_dwordx4 v[210:213], v[150:151], off offset:1792
	s_waitcnt vmcnt(9)
	ds_write_b128 v164, v[172:175]
	s_waitcnt vmcnt(8)
	ds_write_b128 v164, v[202:205] offset:9216
	ds_read_b128 v[172:175], v163 offset:36928
	ds_read_b128 v[202:205], v163 offset:41536
	ds_read_b128 v[218:221], v154 offset:64
	ds_read_b128 v[226:229], v154 offset:4672
	ds_read_b128 v[234:237], v154 offset:9280
	ds_read_b128 v[242:245], v154 offset:13888
	v_mfma_f32_32x32x16_bf16 v[80:95], v[230:233], v[198:201], v[80:95]
	v_mfma_f32_32x32x16_bf16 v[64:79], v[230:233], v[214:217], v[64:79]
	v_mfma_f32_32x32x16_bf16 v[48:63], v[238:241], v[198:201], v[48:63]
	v_mfma_f32_32x32x16_bf16 v[32:47], v[238:241], v[214:217], v[32:47]
	s_waitcnt lgkmcnt(8)
	v_mfma_f32_32x32x16_bf16 v[16:31], v[246:249], v[198:201], v[16:31]
	v_mfma_f32_32x32x16_bf16 v[0:15], v[246:249], v[214:217], v[0:15]
	v_mfma_f32_32x32x16_bf16 v[112:127], v[222:225], v[198:201], v[112:127]
	v_mfma_f32_32x32x16_bf16 v[96:111], v[222:225], v[214:217], v[96:111]
	global_load_dwordx4 v[198:201], v[144:145], off offset:1792
	global_load_dwordx4 v[214:217], v[146:147], off offset:1792
	s_waitcnt vmcnt(9)
	ds_write_b128 v164, v[182:185] offset:18432
	s_waitcnt vmcnt(8)
	ds_write_b128 v164, v[206:209] offset:27648
	ds_read_b128 v[182:185], v163 offset:36960
	ds_read_b128 v[206:209], v163 offset:41568
	ds_read_b128 v[222:225], v154 offset:96
	ds_read_b128 v[230:233], v154 offset:4704
	ds_read_b128 v[238:241], v154 offset:9312
	ds_read_b128 v[246:249], v154 offset:13920
	s_waitcnt lgkmcnt(10)
	v_mfma_f32_32x32x16_bf16 v[80:95], v[226:229], v[172:175], v[80:95]
	v_mfma_f32_32x32x16_bf16 v[64:79], v[226:229], v[202:205], v[64:79]
	s_waitcnt lgkmcnt(9)
	v_mfma_f32_32x32x16_bf16 v[48:63], v[234:237], v[172:175], v[48:63]
	v_mfma_f32_32x32x16_bf16 v[32:47], v[234:237], v[202:205], v[32:47]
	s_waitcnt lgkmcnt(8)
	v_mfma_f32_32x32x16_bf16 v[16:31], v[242:245], v[172:175], v[16:31]
	v_mfma_f32_32x32x16_bf16 v[0:15], v[242:245], v[202:205], v[0:15]
	v_mfma_f32_32x32x16_bf16 v[112:127], v[218:221], v[172:175], v[112:127]
	v_mfma_f32_32x32x16_bf16 v[96:111], v[218:221], v[202:205], v[96:111]
	s_waitcnt vmcnt(7)
	ds_write_b128 v165, v[130:133]
	global_load_dwordx4 v[130:133], v[140:141], off offset:1792
	s_waitcnt vmcnt(7)
	ds_write_b128 v166, v[158:161]
	global_load_dwordx4 v[158:161], v[138:139], off offset:1792
	s_waitcnt lgkmcnt(4)
	v_mfma_f32_32x32x16_bf16 v[80:95], v[230:233], v[182:185], v[80:95]
	v_mfma_f32_32x32x16_bf16 v[64:79], v[230:233], v[206:209], v[64:79]
	s_waitcnt lgkmcnt(3)
	v_mfma_f32_32x32x16_bf16 v[48:63], v[238:241], v[182:185], v[48:63]
	v_mfma_f32_32x32x16_bf16 v[32:47], v[238:241], v[206:209], v[32:47]
	s_waitcnt lgkmcnt(2)
	v_mfma_f32_32x32x16_bf16 v[16:31], v[246:249], v[182:185], v[16:31]
	v_mfma_f32_32x32x16_bf16 v[0:15], v[246:249], v[206:209], v[0:15]
	v_mfma_f32_32x32x16_bf16 v[112:127], v[222:225], v[182:185], v[112:127]
	v_mfma_f32_32x32x16_bf16 v[96:111], v[222:225], v[206:209], v[96:111]
	global_load_dwordx4 v[172:175], v[134:135], off offset:1792
	global_load_dwordx4 v[182:185], v[136:137], off offset:1792
	s_waitcnt vmcnt(9)
	ds_write_b128 v167, v[186:189]
	s_waitcnt vmcnt(8)
	ds_write_b128 v168, v[190:193]
	s_waitcnt lgkmcnt(0)
	s_barrier
	ds_read_b128 v[186:189], v169
	ds_read_b128 v[190:193], v169 offset:32
	ds_read_b128 v[202:205], v169 offset:4608
	ds_read_b128 v[206:209], v169 offset:4640
	ds_read_b128 v[218:221], v155
	ds_read_b128 v[222:225], v155 offset:32
	ds_read_b128 v[226:229], v155 offset:4608
	ds_read_b128 v[230:233], v155 offset:4640
	ds_read_b128 v[234:237], v155 offset:9216
	ds_read_b128 v[238:241], v155 offset:9248
	ds_read_b128 v[242:245], v155 offset:13824
	ds_read_b128 v[246:249], v155 offset:13856
	s_waitcnt lgkmcnt(5)
	v_mfma_f32_32x32x16_bf16 v[80:95], v[226:229], v[186:189], v[80:95]
	v_mfma_f32_32x32x16_bf16 v[64:79], v[226:229], v[202:205], v[64:79]
	s_waitcnt lgkmcnt(3)
	v_mfma_f32_32x32x16_bf16 v[48:63], v[234:237], v[186:189], v[48:63]
	v_mfma_f32_32x32x16_bf16 v[32:47], v[234:237], v[202:205], v[32:47]
	s_waitcnt lgkmcnt(1)
	v_mfma_f32_32x32x16_bf16 v[16:31], v[242:245], v[186:189], v[16:31]
	v_mfma_f32_32x32x16_bf16 v[0:15], v[242:245], v[202:205], v[0:15]
	v_mfma_f32_32x32x16_bf16 v[112:127], v[218:221], v[186:189], v[112:127]
	v_mfma_f32_32x32x16_bf16 v[96:111], v[218:221], v[202:205], v[96:111]
	global_load_dwordx4 v[186:189], v[148:149], off offset:1920
	s_nop 0
	global_load_dwordx4 v[148:151], v[150:151], off offset:1920
	s_waitcnt vmcnt(9)
	ds_write_b128 v128, v[194:197]
	s_waitcnt vmcnt(8)
	ds_write_b128 v128, v[210:213] offset:9216
	ds_read_b128 v[194:197], v169 offset:64
	ds_read_b128 v[202:205], v169 offset:4672
	ds_read_b128 v[210:213], v155 offset:64
	ds_read_b128 v[218:221], v155 offset:4672
	ds_read_b128 v[226:229], v155 offset:9280
	ds_read_b128 v[234:237], v155 offset:13888
	v_mfma_f32_32x32x16_bf16 v[80:95], v[230:233], v[190:193], v[80:95]
	v_mfma_f32_32x32x16_bf16 v[64:79], v[230:233], v[206:209], v[64:79]
	v_mfma_f32_32x32x16_bf16 v[48:63], v[238:241], v[190:193], v[48:63]
	v_mfma_f32_32x32x16_bf16 v[32:47], v[238:241], v[206:209], v[32:47]
	s_waitcnt lgkmcnt(8)
	v_mfma_f32_32x32x16_bf16 v[16:31], v[246:249], v[190:193], v[16:31]
	v_mfma_f32_32x32x16_bf16 v[0:15], v[246:249], v[206:209], v[0:15]
	v_mfma_f32_32x32x16_bf16 v[112:127], v[222:225], v[190:193], v[112:127]
	v_mfma_f32_32x32x16_bf16 v[96:111], v[222:225], v[206:209], v[96:111]
	global_load_dwordx4 v[190:193], v[144:145], off offset:1920
	s_nop 0
	global_load_dwordx4 v[144:147], v[146:147], off offset:1920
	s_waitcnt vmcnt(9)
	ds_write_b128 v128, v[198:201] offset:18432
	s_waitcnt vmcnt(8)
	ds_write_b128 v128, v[214:217] offset:27648
	ds_read_b128 v[198:201], v169 offset:96
	ds_read_b128 v[206:209], v169 offset:4704
	ds_read_b128 v[214:217], v155 offset:96
	ds_read_b128 v[222:225], v155 offset:4704
	ds_read_b128 v[230:233], v155 offset:9312
	ds_read_b128 v[238:241], v155 offset:13920
	s_waitcnt lgkmcnt(10)
	v_mfma_f32_32x32x16_bf16 v[80:95], v[218:221], v[194:197], v[80:95]
	v_mfma_f32_32x32x16_bf16 v[64:79], v[218:221], v[202:205], v[64:79]
	s_waitcnt lgkmcnt(9)
	v_mfma_f32_32x32x16_bf16 v[48:63], v[226:229], v[194:197], v[48:63]
	v_mfma_f32_32x32x16_bf16 v[32:47], v[226:229], v[202:205], v[32:47]
	s_waitcnt lgkmcnt(8)
	v_mfma_f32_32x32x16_bf16 v[16:31], v[234:237], v[194:197], v[16:31]
	v_mfma_f32_32x32x16_bf16 v[0:15], v[234:237], v[202:205], v[0:15]
	v_mfma_f32_32x32x16_bf16 v[112:127], v[210:213], v[194:197], v[112:127]
	v_mfma_f32_32x32x16_bf16 v[96:111], v[210:213], v[202:205], v[96:111]
	s_waitcnt vmcnt(7)
	ds_write_b128 v128, v[130:133] offset:36864
	global_load_dwordx4 v[130:133], v[140:141], off offset:1920
	s_waitcnt vmcnt(7)
	ds_write_b128 v128, v[158:161] offset:46080
	global_load_dwordx4 v[138:141], v[138:139], off offset:1920
	s_waitcnt lgkmcnt(4)
	v_mfma_f32_32x32x16_bf16 v[80:95], v[222:225], v[198:201], v[80:95]
	v_mfma_f32_32x32x16_bf16 v[64:79], v[222:225], v[206:209], v[64:79]
	s_waitcnt lgkmcnt(3)
	v_mfma_f32_32x32x16_bf16 v[48:63], v[230:233], v[198:201], v[48:63]
	v_mfma_f32_32x32x16_bf16 v[32:47], v[230:233], v[206:209], v[32:47]
	s_waitcnt lgkmcnt(2)
	v_mfma_f32_32x32x16_bf16 v[16:31], v[238:241], v[198:201], v[16:31]
	v_mfma_f32_32x32x16_bf16 v[0:15], v[238:241], v[206:209], v[0:15]
	v_mfma_f32_32x32x16_bf16 v[112:127], v[214:217], v[198:201], v[112:127]
	v_mfma_f32_32x32x16_bf16 v[96:111], v[214:217], v[206:209], v[96:111]
	global_load_dwordx4 v[158:161], v[134:135], off offset:1920
	s_nop 0
	global_load_dwordx4 v[134:137], v[136:137], off offset:1920
	s_waitcnt vmcnt(9)
	ds_write_b128 v128, v[172:175] offset:55296
	s_waitcnt vmcnt(8)
	ds_write_b128 v128, v[182:185] offset:64512
	s_waitcnt lgkmcnt(0)
	s_barrier
	ds_read_b128 v[172:175], v163 offset:36864
	ds_read_b128 v[182:185], v163 offset:36896
	ds_read_b128 v[194:197], v163 offset:41472
	ds_read_b128 v[198:201], v163 offset:41504
	ds_read_b128 v[202:205], v154
	ds_read_b128 v[206:209], v154 offset:32
	ds_read_b128 v[210:213], v154 offset:4608
	ds_read_b128 v[214:217], v154 offset:4640
	ds_read_b128 v[218:221], v154 offset:9216
	ds_read_b128 v[222:225], v154 offset:9248
	ds_read_b128 v[226:229], v154 offset:13824
	ds_read_b128 v[230:233], v154 offset:13856
	s_waitcnt lgkmcnt(5)
	v_mfma_f32_32x32x16_bf16 v[80:95], v[210:213], v[172:175], v[80:95]
	v_mfma_f32_32x32x16_bf16 v[64:79], v[210:213], v[194:197], v[64:79]
	s_waitcnt lgkmcnt(3)
	v_mfma_f32_32x32x16_bf16 v[48:63], v[218:221], v[172:175], v[48:63]
	v_mfma_f32_32x32x16_bf16 v[32:47], v[218:221], v[194:197], v[32:47]
	s_waitcnt lgkmcnt(1)
	v_mfma_f32_32x32x16_bf16 v[16:31], v[226:229], v[172:175], v[16:31]
	v_mfma_f32_32x32x16_bf16 v[0:15], v[226:229], v[194:197], v[0:15]
	v_mfma_f32_32x32x16_bf16 v[112:127], v[202:205], v[172:175], v[112:127]
	v_mfma_f32_32x32x16_bf16 v[96:111], v[202:205], v[194:197], v[96:111]
	s_waitcnt vmcnt(7)
	ds_write_b128 v164, v[186:189]
	s_waitcnt vmcnt(6)
	ds_write_b128 v164, v[148:151] offset:9216
	ds_read_b128 v[148:151], v163 offset:36928
	ds_read_b128 v[172:175], v163 offset:41536
	ds_read_b128 v[186:189], v154 offset:64
	ds_read_b128 v[194:197], v154 offset:4672
	ds_read_b128 v[202:205], v154 offset:9280
	ds_read_b128 v[210:213], v154 offset:13888
	v_mfma_f32_32x32x16_bf16 v[80:95], v[214:217], v[182:185], v[80:95]
	v_mfma_f32_32x32x16_bf16 v[64:79], v[214:217], v[198:201], v[64:79]
	v_mfma_f32_32x32x16_bf16 v[48:63], v[222:225], v[182:185], v[48:63]
	v_mfma_f32_32x32x16_bf16 v[32:47], v[222:225], v[198:201], v[32:47]
	s_waitcnt lgkmcnt(8)
	v_mfma_f32_32x32x16_bf16 v[16:31], v[230:233], v[182:185], v[16:31]
	v_mfma_f32_32x32x16_bf16 v[0:15], v[230:233], v[198:201], v[0:15]
	v_mfma_f32_32x32x16_bf16 v[112:127], v[206:209], v[182:185], v[112:127]
	v_mfma_f32_32x32x16_bf16 v[96:111], v[206:209], v[198:201], v[96:111]
	s_waitcnt vmcnt(5)
	ds_write_b128 v164, v[190:193] offset:18432
	s_waitcnt vmcnt(4)
	ds_write_b128 v164, v[144:147] offset:27648
	ds_read_b128 v[144:147], v163 offset:36960
	ds_read_b128 v[182:185], v163 offset:41568
	ds_read_b128 v[190:193], v154 offset:96
	ds_read_b128 v[198:201], v154 offset:4704
	ds_read_b128 v[206:209], v154 offset:9312
	ds_read_b128 v[214:217], v154 offset:13920
	s_waitcnt lgkmcnt(10)
	v_mfma_f32_32x32x16_bf16 v[80:95], v[194:197], v[148:151], v[80:95]
	v_mfma_f32_32x32x16_bf16 v[64:79], v[194:197], v[172:175], v[64:79]
	s_waitcnt lgkmcnt(9)
	v_mfma_f32_32x32x16_bf16 v[48:63], v[202:205], v[148:151], v[48:63]
	v_mfma_f32_32x32x16_bf16 v[32:47], v[202:205], v[172:175], v[32:47]
	s_waitcnt lgkmcnt(8)
	v_mfma_f32_32x32x16_bf16 v[16:31], v[210:213], v[148:151], v[16:31]
	v_mfma_f32_32x32x16_bf16 v[0:15], v[210:213], v[172:175], v[0:15]
	v_mfma_f32_32x32x16_bf16 v[112:127], v[186:189], v[148:151], v[112:127]
	v_mfma_f32_32x32x16_bf16 v[96:111], v[186:189], v[172:175], v[96:111]
	s_waitcnt vmcnt(3)
	ds_write_b128 v165, v[130:133]
	s_waitcnt vmcnt(2)
	ds_write_b128 v166, v[138:141]
	s_waitcnt lgkmcnt(4)
	v_mfma_f32_32x32x16_bf16 v[80:95], v[198:201], v[144:147], v[80:95]
	v_mfma_f32_32x32x16_bf16 v[64:79], v[198:201], v[182:185], v[64:79]
	s_waitcnt lgkmcnt(3)
	v_mfma_f32_32x32x16_bf16 v[48:63], v[206:209], v[144:147], v[48:63]
	v_mfma_f32_32x32x16_bf16 v[32:47], v[206:209], v[182:185], v[32:47]
	s_waitcnt lgkmcnt(2)
	v_mfma_f32_32x32x16_bf16 v[16:31], v[214:217], v[144:147], v[16:31]
	v_mfma_f32_32x32x16_bf16 v[0:15], v[214:217], v[182:185], v[0:15]
	v_mfma_f32_32x32x16_bf16 v[112:127], v[190:193], v[144:147], v[112:127]
	v_mfma_f32_32x32x16_bf16 v[96:111], v[190:193], v[182:185], v[96:111]
	s_waitcnt vmcnt(1)
	ds_write_b128 v167, v[158:161]
	s_waitcnt vmcnt(0)
	ds_write_b128 v168, v[134:137]
	s_waitcnt lgkmcnt(0)
	s_barrier
	ds_read_b128 v[130:133], v169
	ds_read_b128 v[134:137], v169 offset:32
	ds_read_b128 v[138:141], v169 offset:4608
	ds_read_b128 v[144:147], v169 offset:4640
	ds_read_b128 v[148:151], v155
	ds_read_b128 v[158:161], v155 offset:32
	ds_read_b128 v[172:175], v155 offset:4608
	ds_read_b128 v[182:185], v155 offset:4640
	ds_read_b128 v[186:189], v155 offset:9216
	ds_read_b128 v[190:193], v155 offset:9248
	ds_read_b128 v[194:197], v155 offset:13824
	ds_read_b128 v[198:201], v155 offset:13856
	s_waitcnt lgkmcnt(5)
	v_mfma_f32_32x32x16_bf16 v[80:95], v[172:175], v[130:133], v[80:95]
	v_mfma_f32_32x32x16_bf16 v[64:79], v[172:175], v[138:141], v[64:79]
	s_waitcnt lgkmcnt(3)
	v_mfma_f32_32x32x16_bf16 v[48:63], v[186:189], v[130:133], v[48:63]
	v_mfma_f32_32x32x16_bf16 v[32:47], v[186:189], v[138:141], v[32:47]
	s_waitcnt lgkmcnt(1)
	v_mfma_f32_32x32x16_bf16 v[16:31], v[194:197], v[130:133], v[16:31]
	v_mfma_f32_32x32x16_bf16 v[0:15], v[194:197], v[138:141], v[0:15]
	v_mfma_f32_32x32x16_bf16 v[112:127], v[148:151], v[130:133], v[112:127]
	v_mfma_f32_32x32x16_bf16 v[96:111], v[148:151], v[138:141], v[96:111]
	ds_read_b128 v[130:133], v169 offset:64
	ds_read_b128 v[138:141], v169 offset:4672
	ds_read_b128 v[148:151], v155 offset:64
	ds_read_b128 v[172:175], v155 offset:4672
	ds_read_b128 v[186:189], v155 offset:9280
	ds_read_b128 v[194:197], v155 offset:13888
	v_mfma_f32_32x32x16_bf16 v[80:95], v[182:185], v[134:137], v[80:95]
	v_mfma_f32_32x32x16_bf16 v[64:79], v[182:185], v[144:147], v[64:79]
	v_mfma_f32_32x32x16_bf16 v[48:63], v[190:193], v[134:137], v[48:63]
	v_mfma_f32_32x32x16_bf16 v[32:47], v[190:193], v[144:147], v[32:47]
	s_waitcnt lgkmcnt(6)
	v_mfma_f32_32x32x16_bf16 v[16:31], v[198:201], v[134:137], v[16:31]
	v_mfma_f32_32x32x16_bf16 v[0:15], v[198:201], v[144:147], v[0:15]
	v_mfma_f32_32x32x16_bf16 v[112:127], v[158:161], v[134:137], v[112:127]
	v_mfma_f32_32x32x16_bf16 v[96:111], v[158:161], v[144:147], v[96:111]
	ds_read_b128 v[134:137], v169 offset:96
	ds_read_b128 v[144:147], v169 offset:4704
	ds_read_b128 v[158:161], v155 offset:96
	ds_read_b128 v[182:185], v155 offset:4704
	ds_read_b128 v[190:193], v155 offset:9312
	ds_read_b128 v[198:201], v155 offset:13920
	s_waitcnt lgkmcnt(8)
	v_mfma_f32_32x32x16_bf16 v[80:95], v[172:175], v[130:133], v[80:95]
	v_mfma_f32_32x32x16_bf16 v[64:79], v[172:175], v[138:141], v[64:79]
	s_waitcnt lgkmcnt(7)
	v_mfma_f32_32x32x16_bf16 v[48:63], v[186:189], v[130:133], v[48:63]
	v_mfma_f32_32x32x16_bf16 v[32:47], v[186:189], v[138:141], v[32:47]
	s_waitcnt lgkmcnt(6)
	v_mfma_f32_32x32x16_bf16 v[16:31], v[194:197], v[130:133], v[16:31]
	v_mfma_f32_32x32x16_bf16 v[0:15], v[194:197], v[138:141], v[0:15]
	v_mfma_f32_32x32x16_bf16 v[112:127], v[148:151], v[130:133], v[112:127]
	v_mfma_f32_32x32x16_bf16 v[96:111], v[148:151], v[138:141], v[96:111]
	s_waitcnt lgkmcnt(2)
	v_mfma_f32_32x32x16_bf16 v[80:95], v[182:185], v[134:137], v[80:95]
	v_mfma_f32_32x32x16_bf16 v[64:79], v[182:185], v[144:147], v[64:79]
	s_waitcnt lgkmcnt(1)
	v_mfma_f32_32x32x16_bf16 v[48:63], v[190:193], v[134:137], v[48:63]
	v_mfma_f32_32x32x16_bf16 v[32:47], v[190:193], v[144:147], v[32:47]
	s_waitcnt lgkmcnt(0)
	v_mfma_f32_32x32x16_bf16 v[16:31], v[198:201], v[134:137], v[16:31]
	v_mfma_f32_32x32x16_bf16 v[0:15], v[198:201], v[144:147], v[0:15]
	v_mfma_f32_32x32x16_bf16 v[112:127], v[158:161], v[134:137], v[112:127]
	v_mfma_f32_32x32x16_bf16 v[96:111], v[158:161], v[144:147], v[96:111]
	v_add_u32_e32 v130, s1, v179
	s_movk_i32 s1, 0xa20
	v_ashrrev_i32_e32 v131, 31, v130
	v_cmp_gt_i32_e32 vcc, s1, v130
	v_lshl_add_u64 v[134:135], v[130:131], 1, s[60:61]
	s_nop 5
	v_bfe_u32 v130, v112, 16, 1
	v_add3_u32 v112, v112, v130, s24
	s_barrier
	ds_write_b16_d16_hi v156, v112
	v_bfe_u32 v112, v113, 16, 1
	v_add3_u32 v112, v113, v112, s24
	ds_write_b16_d16_hi v156, v112 offset:144
	v_bfe_u32 v112, v114, 16, 1
	v_add3_u32 v112, v114, v112, s24
	ds_write_b16_d16_hi v156, v112 offset:288
	v_bfe_u32 v112, v115, 16, 1
	v_add3_u32 v112, v115, v112, s24
	ds_write_b16_d16_hi v156, v112 offset:432
	v_bfe_u32 v112, v116, 16, 1
	v_add3_u32 v112, v116, v112, s24
	ds_write_b16_d16_hi v156, v112 offset:1152
	v_bfe_u32 v112, v117, 16, 1
	v_add3_u32 v112, v117, v112, s24
	ds_write_b16_d16_hi v156, v112 offset:1296
	v_bfe_u32 v112, v118, 16, 1
	v_add3_u32 v112, v118, v112, s24
	ds_write_b16_d16_hi v156, v112 offset:1440
	v_bfe_u32 v112, v119, 16, 1
	v_add3_u32 v112, v119, v112, s24
	ds_write_b16_d16_hi v156, v112 offset:1584
	v_bfe_u32 v112, v120, 16, 1
	v_add3_u32 v112, v120, v112, s24
	ds_write_b16_d16_hi v156, v112 offset:2304
	v_bfe_u32 v112, v121, 16, 1
	v_add3_u32 v112, v121, v112, s24
	ds_write_b16_d16_hi v156, v112 offset:2448
	v_bfe_u32 v112, v122, 16, 1
	v_add3_u32 v112, v122, v112, s24
	ds_write_b16_d16_hi v156, v112 offset:2592
	v_bfe_u32 v112, v123, 16, 1
	v_add3_u32 v112, v123, v112, s24
	ds_write_b16_d16_hi v156, v112 offset:2736
	v_bfe_u32 v112, v124, 16, 1
	v_add3_u32 v112, v124, v112, s24
	ds_write_b16_d16_hi v156, v112 offset:3456
	v_bfe_u32 v112, v125, 16, 1
	v_add3_u32 v112, v125, v112, s24
	ds_write_b16_d16_hi v156, v112 offset:3600
	v_bfe_u32 v112, v126, 16, 1
	v_add3_u32 v112, v126, v112, s24
	ds_write_b16_d16_hi v156, v112 offset:3744
	v_bfe_u32 v112, v127, 16, 1
	v_add3_u32 v112, v127, v112, s24
	ds_write_b16_d16_hi v156, v112 offset:3888
	v_bfe_u32 v112, v96, 16, 1
	v_add3_u32 v96, v96, v112, s24
	ds_write_b16_d16_hi v156, v96 offset:64
	v_bfe_u32 v96, v97, 16, 1
	v_add3_u32 v96, v97, v96, s24
	ds_write_b16_d16_hi v156, v96 offset:208
	v_bfe_u32 v96, v98, 16, 1
	v_add3_u32 v96, v98, v96, s24
	ds_write_b16_d16_hi v156, v96 offset:352
	v_bfe_u32 v96, v99, 16, 1
	v_add3_u32 v96, v99, v96, s24
	ds_write_b16_d16_hi v156, v96 offset:496
	v_bfe_u32 v96, v100, 16, 1
	v_add3_u32 v96, v100, v96, s24
	ds_write_b16_d16_hi v156, v96 offset:1216
	v_bfe_u32 v96, v101, 16, 1
	v_add3_u32 v96, v101, v96, s24
	ds_write_b16_d16_hi v156, v96 offset:1360
	v_bfe_u32 v96, v102, 16, 1
	v_add3_u32 v96, v102, v96, s24
	ds_write_b16_d16_hi v156, v96 offset:1504
	v_bfe_u32 v96, v103, 16, 1
	v_add3_u32 v96, v103, v96, s24
	ds_write_b16_d16_hi v156, v96 offset:1648
	v_bfe_u32 v96, v104, 16, 1
	v_add3_u32 v96, v104, v96, s24
	ds_write_b16_d16_hi v156, v96 offset:2368
	v_bfe_u32 v96, v105, 16, 1
	v_add3_u32 v96, v105, v96, s24
	ds_write_b16_d16_hi v156, v96 offset:2512
	v_bfe_u32 v96, v106, 16, 1
	v_add3_u32 v96, v106, v96, s24
	ds_write_b16_d16_hi v156, v96 offset:2656
	v_bfe_u32 v96, v107, 16, 1
	v_add3_u32 v96, v107, v96, s24
	ds_write_b16_d16_hi v156, v96 offset:2800
	v_bfe_u32 v96, v108, 16, 1
	v_add3_u32 v96, v108, v96, s24
	ds_write_b16_d16_hi v156, v96 offset:3520
	v_bfe_u32 v96, v109, 16, 1
	v_add3_u32 v96, v109, v96, s24
	ds_write_b16_d16_hi v156, v96 offset:3664
	v_bfe_u32 v96, v110, 16, 1
	v_add3_u32 v96, v110, v96, s24
	ds_write_b16_d16_hi v156, v96 offset:3808
	v_bfe_u32 v96, v111, 16, 1
	v_add_u32_e32 v136, s0, v153
	v_add3_u32 v96, v111, v96, s24
	ds_write_b16_d16_hi v156, v96 offset:3952
	s_and_saveexec_b64 s[0:1], vcc
	s_cbranch_execz .LBB0_242
	ds_read_b128 v[186:189], v170
	ds_read_b128 v[190:193], v170 offset:1152
	ds_read_b128 v[194:197], v170 offset:2304
	ds_read_b128 v[198:201], v170 offset:3456
	v_or_b32_e32 v202, v136, v157
	v_mad_i64_i32 v[202:203], s[10:11], v202, s33, v[134:135]
	v_or_b32_e32 v204, v136, v171
	v_mad_i64_i32 v[204:205], s[10:11], v204, s33, v[134:135]
	v_or_b32_e32 v206, v136, v252
	v_mad_i64_i32 v[206:207], s[10:11], v206, s33, v[134:135]
	v_or_b32_e32 v208, v136, v181
	v_mad_i64_i32 v[208:209], s[10:11], v208, s33, v[134:135]
	s_waitcnt lgkmcnt(3)
	global_store_dwordx4 v[202:203], v[186:189], off
	s_waitcnt lgkmcnt(2)
	global_store_dwordx4 v[204:205], v[190:193], off
	s_waitcnt lgkmcnt(1)
	global_store_dwordx4 v[206:207], v[194:197], off
	s_waitcnt lgkmcnt(0)
	global_store_dwordx4 v[208:209], v[198:201], off
.LBB0_242:
	s_or_b64 exec, exec, s[0:1]
	s_nop 0
	v_bfe_u32 v96, v80, 16, 1
	v_add3_u32 v80, v80, v96, s24
	ds_write_b16_d16_hi v156, v80
	v_bfe_u32 v80, v81, 16, 1
	v_add3_u32 v80, v81, v80, s24
	ds_write_b16_d16_hi v156, v80 offset:144
	v_bfe_u32 v80, v82, 16, 1
	v_add3_u32 v80, v82, v80, s24
	ds_write_b16_d16_hi v156, v80 offset:288
	v_bfe_u32 v80, v83, 16, 1
	v_add3_u32 v80, v83, v80, s24
	ds_write_b16_d16_hi v156, v80 offset:432
	v_bfe_u32 v80, v84, 16, 1
	v_add3_u32 v80, v84, v80, s24
	ds_write_b16_d16_hi v156, v80 offset:1152
	v_bfe_u32 v80, v85, 16, 1
	v_add3_u32 v80, v85, v80, s24
	ds_write_b16_d16_hi v156, v80 offset:1296
	v_bfe_u32 v80, v86, 16, 1
	v_add3_u32 v80, v86, v80, s24
	ds_write_b16_d16_hi v156, v80 offset:1440
	v_bfe_u32 v80, v87, 16, 1
	v_add3_u32 v80, v87, v80, s24
	ds_write_b16_d16_hi v156, v80 offset:1584
	v_bfe_u32 v80, v88, 16, 1
	v_add3_u32 v80, v88, v80, s24
	ds_write_b16_d16_hi v156, v80 offset:2304
	v_bfe_u32 v80, v89, 16, 1
	v_add3_u32 v80, v89, v80, s24
	ds_write_b16_d16_hi v156, v80 offset:2448
	v_bfe_u32 v80, v90, 16, 1
	v_add3_u32 v80, v90, v80, s24
	ds_write_b16_d16_hi v156, v80 offset:2592
	v_bfe_u32 v80, v91, 16, 1
	v_add3_u32 v80, v91, v80, s24
	ds_write_b16_d16_hi v156, v80 offset:2736
	v_bfe_u32 v80, v92, 16, 1
	v_add3_u32 v80, v92, v80, s24
	ds_write_b16_d16_hi v156, v80 offset:3456
	v_bfe_u32 v80, v93, 16, 1
	v_add3_u32 v80, v93, v80, s24
	ds_write_b16_d16_hi v156, v80 offset:3600
	v_bfe_u32 v80, v94, 16, 1
	v_add3_u32 v80, v94, v80, s24
	ds_write_b16_d16_hi v156, v80 offset:3744
	v_bfe_u32 v80, v95, 16, 1
	v_add3_u32 v80, v95, v80, s24
	ds_write_b16_d16_hi v156, v80 offset:3888
	v_bfe_u32 v80, v64, 16, 1
	v_add3_u32 v64, v64, v80, s24
	ds_write_b16_d16_hi v156, v64 offset:64
	v_bfe_u32 v64, v65, 16, 1
	v_add3_u32 v64, v65, v64, s24
	ds_write_b16_d16_hi v156, v64 offset:208
	v_bfe_u32 v64, v66, 16, 1
	v_add3_u32 v64, v66, v64, s24
	ds_write_b16_d16_hi v156, v64 offset:352
	v_bfe_u32 v64, v67, 16, 1
	v_add3_u32 v64, v67, v64, s24
	ds_write_b16_d16_hi v156, v64 offset:496
	v_bfe_u32 v64, v68, 16, 1
	v_add3_u32 v64, v68, v64, s24
	ds_write_b16_d16_hi v156, v64 offset:1216
	v_bfe_u32 v64, v69, 16, 1
	v_add3_u32 v64, v69, v64, s24
	ds_write_b16_d16_hi v156, v64 offset:1360
	v_bfe_u32 v64, v70, 16, 1
	v_add3_u32 v64, v70, v64, s24
	ds_write_b16_d16_hi v156, v64 offset:1504
	v_bfe_u32 v64, v71, 16, 1
	v_add3_u32 v64, v71, v64, s24
	ds_write_b16_d16_hi v156, v64 offset:1648
	v_bfe_u32 v64, v72, 16, 1
	v_add3_u32 v64, v72, v64, s24
	ds_write_b16_d16_hi v156, v64 offset:2368
	v_bfe_u32 v64, v73, 16, 1
	v_add3_u32 v64, v73, v64, s24
	ds_write_b16_d16_hi v156, v64 offset:2512
	v_bfe_u32 v64, v74, 16, 1
	v_add3_u32 v64, v74, v64, s24
	ds_write_b16_d16_hi v156, v64 offset:2656
	v_bfe_u32 v64, v75, 16, 1
	v_add3_u32 v64, v75, v64, s24
	ds_write_b16_d16_hi v156, v64 offset:2800
	v_bfe_u32 v64, v76, 16, 1
	v_add3_u32 v64, v76, v64, s24
	ds_write_b16_d16_hi v156, v64 offset:3520
	v_bfe_u32 v64, v77, 16, 1
	v_add3_u32 v64, v77, v64, s24
	ds_write_b16_d16_hi v156, v64 offset:3664
	v_bfe_u32 v64, v78, 16, 1
	v_add3_u32 v64, v78, v64, s24
	ds_write_b16_d16_hi v156, v64 offset:3808
	v_bfe_u32 v64, v79, 16, 1
	v_add3_u32 v64, v79, v64, s24
	ds_write_b16_d16_hi v156, v64 offset:3952
	s_and_saveexec_b64 s[0:1], vcc
	s_cbranch_execz .LBB0_244
	ds_read_b128 v[186:189], v170
	ds_read_b128 v[190:193], v170 offset:1152
	ds_read_b128 v[194:197], v170 offset:2304
	ds_read_b128 v[198:201], v170 offset:3456
	v_or_b32_e32 v70, 32, v136
	v_or_b32_e32 v202, v70, v157
	v_mad_i64_i32 v[202:203], s[10:11], v202, s33, v[134:135]
	v_or_b32_e32 v204, v70, v171
	v_mad_i64_i32 v[204:205], s[10:11], v204, s33, v[134:135]
	v_or_b32_e32 v206, v70, v252
	v_mad_i64_i32 v[206:207], s[10:11], v206, s33, v[134:135]
	v_or_b32_e32 v208, v70, v181
	v_mad_i64_i32 v[208:209], s[10:11], v208, s33, v[134:135]
	s_waitcnt lgkmcnt(3)
	global_store_dwordx4 v[202:203], v[186:189], off
	s_waitcnt lgkmcnt(2)
	global_store_dwordx4 v[204:205], v[190:193], off
	s_waitcnt lgkmcnt(1)
	global_store_dwordx4 v[206:207], v[194:197], off
	s_waitcnt lgkmcnt(0)
	global_store_dwordx4 v[208:209], v[198:201], off
.LBB0_244:
	s_or_b64 exec, exec, s[0:1]
	s_nop 0
	v_bfe_u32 v64, v48, 16, 1
	v_add3_u32 v48, v48, v64, s24
	ds_write_b16_d16_hi v156, v48
	v_bfe_u32 v48, v49, 16, 1
	v_add3_u32 v48, v49, v48, s24
	ds_write_b16_d16_hi v156, v48 offset:144
	v_bfe_u32 v48, v50, 16, 1
	v_add3_u32 v48, v50, v48, s24
	ds_write_b16_d16_hi v156, v48 offset:288
	v_bfe_u32 v48, v51, 16, 1
	v_add3_u32 v48, v51, v48, s24
	ds_write_b16_d16_hi v156, v48 offset:432
	v_bfe_u32 v48, v52, 16, 1
	v_add3_u32 v48, v52, v48, s24
	ds_write_b16_d16_hi v156, v48 offset:1152
	v_bfe_u32 v48, v53, 16, 1
	v_add3_u32 v48, v53, v48, s24
	ds_write_b16_d16_hi v156, v48 offset:1296
	v_bfe_u32 v48, v54, 16, 1
	v_add3_u32 v48, v54, v48, s24
	ds_write_b16_d16_hi v156, v48 offset:1440
	v_bfe_u32 v48, v55, 16, 1
	v_add3_u32 v48, v55, v48, s24
	ds_write_b16_d16_hi v156, v48 offset:1584
	v_bfe_u32 v48, v56, 16, 1
	v_add3_u32 v48, v56, v48, s24
	ds_write_b16_d16_hi v156, v48 offset:2304
	v_bfe_u32 v48, v57, 16, 1
	v_add3_u32 v48, v57, v48, s24
	ds_write_b16_d16_hi v156, v48 offset:2448
	v_bfe_u32 v48, v58, 16, 1
	v_add3_u32 v48, v58, v48, s24
	ds_write_b16_d16_hi v156, v48 offset:2592
	v_bfe_u32 v48, v59, 16, 1
	v_add3_u32 v48, v59, v48, s24
	ds_write_b16_d16_hi v156, v48 offset:2736
	v_bfe_u32 v48, v60, 16, 1
	v_add3_u32 v48, v60, v48, s24
	ds_write_b16_d16_hi v156, v48 offset:3456
	v_bfe_u32 v48, v61, 16, 1
	v_add3_u32 v48, v61, v48, s24
	ds_write_b16_d16_hi v156, v48 offset:3600
	v_bfe_u32 v48, v62, 16, 1
	v_add3_u32 v48, v62, v48, s24
	ds_write_b16_d16_hi v156, v48 offset:3744
	v_bfe_u32 v48, v63, 16, 1
	v_add3_u32 v48, v63, v48, s24
	ds_write_b16_d16_hi v156, v48 offset:3888
	v_bfe_u32 v48, v32, 16, 1
	v_add3_u32 v32, v32, v48, s24
	ds_write_b16_d16_hi v156, v32 offset:64
	v_bfe_u32 v32, v33, 16, 1
	v_add3_u32 v32, v33, v32, s24
	ds_write_b16_d16_hi v156, v32 offset:208
	v_bfe_u32 v32, v34, 16, 1
	v_add3_u32 v32, v34, v32, s24
	ds_write_b16_d16_hi v156, v32 offset:352
	v_bfe_u32 v32, v35, 16, 1
	v_add3_u32 v32, v35, v32, s24
	ds_write_b16_d16_hi v156, v32 offset:496
	v_bfe_u32 v32, v36, 16, 1
	v_add3_u32 v32, v36, v32, s24
	ds_write_b16_d16_hi v156, v32 offset:1216
	v_bfe_u32 v32, v37, 16, 1
	v_add3_u32 v32, v37, v32, s24
	ds_write_b16_d16_hi v156, v32 offset:1360
	v_bfe_u32 v32, v38, 16, 1
	v_add3_u32 v32, v38, v32, s24
	ds_write_b16_d16_hi v156, v32 offset:1504
	v_bfe_u32 v32, v39, 16, 1
	v_add3_u32 v32, v39, v32, s24
	ds_write_b16_d16_hi v156, v32 offset:1648
	v_bfe_u32 v32, v40, 16, 1
	v_add3_u32 v32, v40, v32, s24
	ds_write_b16_d16_hi v156, v32 offset:2368
	v_bfe_u32 v32, v41, 16, 1
	v_add3_u32 v32, v41, v32, s24
	ds_write_b16_d16_hi v156, v32 offset:2512
	v_bfe_u32 v32, v42, 16, 1
	v_add3_u32 v32, v42, v32, s24
	ds_write_b16_d16_hi v156, v32 offset:2656
	v_bfe_u32 v32, v43, 16, 1
	v_add3_u32 v32, v43, v32, s24
	ds_write_b16_d16_hi v156, v32 offset:2800
	v_bfe_u32 v32, v44, 16, 1
	v_add3_u32 v32, v44, v32, s24
	ds_write_b16_d16_hi v156, v32 offset:3520
	v_bfe_u32 v32, v45, 16, 1
	v_add3_u32 v32, v45, v32, s24
	ds_write_b16_d16_hi v156, v32 offset:3664
	v_bfe_u32 v32, v46, 16, 1
	v_add3_u32 v32, v46, v32, s24
	ds_write_b16_d16_hi v156, v32 offset:3808
	v_bfe_u32 v32, v47, 16, 1
	v_add3_u32 v32, v47, v32, s24
	ds_write_b16_d16_hi v156, v32 offset:3952
	s_and_saveexec_b64 s[0:1], vcc
	s_cbranch_execz .LBB0_246
	ds_read_b128 v[186:189], v170
	ds_read_b128 v[190:193], v170 offset:1152
	ds_read_b128 v[194:197], v170 offset:2304
	ds_read_b128 v[198:201], v170 offset:3456
	v_or_b32_e32 v38, 64, v136
	v_or_b32_e32 v202, v38, v157
	v_mad_i64_i32 v[202:203], s[10:11], v202, s33, v[134:135]
	v_or_b32_e32 v204, v38, v171
	v_mad_i64_i32 v[204:205], s[10:11], v204, s33, v[134:135]
	v_or_b32_e32 v206, v38, v252
	v_mad_i64_i32 v[206:207], s[10:11], v206, s33, v[134:135]
	v_or_b32_e32 v208, v38, v181
	v_mad_i64_i32 v[208:209], s[10:11], v208, s33, v[134:135]
	s_waitcnt lgkmcnt(3)
	global_store_dwordx4 v[202:203], v[186:189], off
	s_waitcnt lgkmcnt(2)
	global_store_dwordx4 v[204:205], v[190:193], off
	s_waitcnt lgkmcnt(1)
	global_store_dwordx4 v[206:207], v[194:197], off
	s_waitcnt lgkmcnt(0)
	global_store_dwordx4 v[208:209], v[198:201], off
.LBB0_246:
	s_or_b64 exec, exec, s[0:1]
	s_nop 0
	v_bfe_u32 v32, v16, 16, 1
	v_add3_u32 v16, v16, v32, s24
	ds_write_b16_d16_hi v156, v16
	v_bfe_u32 v16, v17, 16, 1
	v_add3_u32 v16, v17, v16, s24
	ds_write_b16_d16_hi v156, v16 offset:144
	v_bfe_u32 v16, v18, 16, 1
	v_add3_u32 v16, v18, v16, s24
	ds_write_b16_d16_hi v156, v16 offset:288
	v_bfe_u32 v16, v19, 16, 1
	v_add3_u32 v16, v19, v16, s24
	ds_write_b16_d16_hi v156, v16 offset:432
	v_bfe_u32 v16, v20, 16, 1
	v_add3_u32 v16, v20, v16, s24
	ds_write_b16_d16_hi v156, v16 offset:1152
	v_bfe_u32 v16, v21, 16, 1
	v_add3_u32 v16, v21, v16, s24
	ds_write_b16_d16_hi v156, v16 offset:1296
	v_bfe_u32 v16, v22, 16, 1
	v_add3_u32 v16, v22, v16, s24
	ds_write_b16_d16_hi v156, v16 offset:1440
	v_bfe_u32 v16, v23, 16, 1
	v_add3_u32 v16, v23, v16, s24
	ds_write_b16_d16_hi v156, v16 offset:1584
	v_bfe_u32 v16, v24, 16, 1
	v_add3_u32 v16, v24, v16, s24
	ds_write_b16_d16_hi v156, v16 offset:2304
	v_bfe_u32 v16, v25, 16, 1
	v_add3_u32 v16, v25, v16, s24
	ds_write_b16_d16_hi v156, v16 offset:2448
	v_bfe_u32 v16, v26, 16, 1
	v_add3_u32 v16, v26, v16, s24
	ds_write_b16_d16_hi v156, v16 offset:2592
	v_bfe_u32 v16, v27, 16, 1
	v_add3_u32 v16, v27, v16, s24
	ds_write_b16_d16_hi v156, v16 offset:2736
	v_bfe_u32 v16, v28, 16, 1
	v_add3_u32 v16, v28, v16, s24
	ds_write_b16_d16_hi v156, v16 offset:3456
	v_bfe_u32 v16, v29, 16, 1
	v_add3_u32 v16, v29, v16, s24
	ds_write_b16_d16_hi v156, v16 offset:3600
	v_bfe_u32 v16, v30, 16, 1
	v_add3_u32 v16, v30, v16, s24
	ds_write_b16_d16_hi v156, v16 offset:3744
	v_bfe_u32 v16, v31, 16, 1
	v_add3_u32 v16, v31, v16, s24
	ds_write_b16_d16_hi v156, v16 offset:3888
	v_bfe_u32 v16, v0, 16, 1
	v_add3_u32 v0, v0, v16, s24
	ds_write_b16_d16_hi v156, v0 offset:64
	v_bfe_u32 v0, v1, 16, 1
	v_add3_u32 v0, v1, v0, s24
	ds_write_b16_d16_hi v156, v0 offset:208
	v_bfe_u32 v0, v2, 16, 1
	v_add3_u32 v0, v2, v0, s24
	ds_write_b16_d16_hi v156, v0 offset:352
	v_bfe_u32 v0, v3, 16, 1
	v_add3_u32 v0, v3, v0, s24
	ds_write_b16_d16_hi v156, v0 offset:496
	v_bfe_u32 v0, v4, 16, 1
	v_add3_u32 v0, v4, v0, s24
	ds_write_b16_d16_hi v156, v0 offset:1216
	v_bfe_u32 v0, v5, 16, 1
	v_add3_u32 v0, v5, v0, s24
	ds_write_b16_d16_hi v156, v0 offset:1360
	v_bfe_u32 v0, v6, 16, 1
	v_add3_u32 v0, v6, v0, s24
	ds_write_b16_d16_hi v156, v0 offset:1504
	v_bfe_u32 v0, v7, 16, 1
	v_add3_u32 v0, v7, v0, s24
	ds_write_b16_d16_hi v156, v0 offset:1648
	v_bfe_u32 v0, v8, 16, 1
	v_add3_u32 v0, v8, v0, s24
	ds_write_b16_d16_hi v156, v0 offset:2368
	v_bfe_u32 v0, v9, 16, 1
	v_add3_u32 v0, v9, v0, s24
	ds_write_b16_d16_hi v156, v0 offset:2512
	v_bfe_u32 v0, v10, 16, 1
	v_add3_u32 v0, v10, v0, s24
	ds_write_b16_d16_hi v156, v0 offset:2656
	v_bfe_u32 v0, v11, 16, 1
	v_add3_u32 v0, v11, v0, s24
	ds_write_b16_d16_hi v156, v0 offset:2800
	v_bfe_u32 v0, v12, 16, 1
	v_add3_u32 v0, v12, v0, s24
	ds_write_b16_d16_hi v156, v0 offset:3520
	v_bfe_u32 v0, v13, 16, 1
	v_add3_u32 v0, v13, v0, s24
	ds_write_b16_d16_hi v156, v0 offset:3664
	v_bfe_u32 v0, v14, 16, 1
	v_add3_u32 v0, v14, v0, s24
	ds_write_b16_d16_hi v156, v0 offset:3808
	v_bfe_u32 v0, v15, 16, 1
	v_add3_u32 v0, v15, v0, s24
	ds_write_b16_d16_hi v156, v0 offset:3952
	s_and_saveexec_b64 s[0:1], vcc
	s_cbranch_execz .LBB0_237
	ds_read_b128 v[186:189], v170
	ds_read_b128 v[190:193], v170 offset:1152
	ds_read_b128 v[194:197], v170 offset:2304
	ds_read_b128 v[198:201], v170 offset:3456
	v_or_b32_e32 v6, 0x60, v136
	v_or_b32_e32 v202, v6, v157
	v_mad_i64_i32 v[202:203], s[10:11], v202, s33, v[134:135]
	v_or_b32_e32 v204, v6, v171
	v_mad_i64_i32 v[204:205], s[10:11], v204, s33, v[134:135]
	v_or_b32_e32 v206, v6, v252
	v_mad_i64_i32 v[206:207], s[10:11], v206, s33, v[134:135]
	v_or_b32_e32 v208, v6, v181
	v_mad_i64_i32 v[208:209], s[10:11], v208, s33, v[134:135]
	s_waitcnt lgkmcnt(3)
	global_store_dwordx4 v[202:203], v[186:189], off
	s_waitcnt lgkmcnt(2)
	global_store_dwordx4 v[204:205], v[190:193], off
	s_waitcnt lgkmcnt(1)
	global_store_dwordx4 v[206:207], v[194:197], off
	s_waitcnt lgkmcnt(0)
	global_store_dwordx4 v[208:209], v[198:201], off
	s_branch .LBB0_237

.Lgo_239:
	s_ashr_i32 s1, s4, 2
	s_add_i32 s0, s1, s7
	s_lshl_b32 s0, s0, 8
	v_add_u32_e32 v0, s0, v152
	v_ashrrev_i32_e32 v1, 31, v0
	v_lshlrev_b64 v[0:1], 11, v[0:1]
	s_mulk_i32 s1, 0xfc00
	v_lshl_add_u64 v[148:149], v[250:251], 0, v[0:1]
	s_add_i32 s1, s1, s8
	v_add_co_u32_e32 v150, vcc, 0x20000, v148
	v_add_u32_e32 v2, s1, v152
	s_nop 0
	v_addc_co_u32_e32 v151, vcc, 0, v149, vcc
	v_ashrrev_i32_e32 v3, 31, v2
	v_add_co_u32_e32 v144, vcc, 0x40000, v148
	v_lshlrev_b64 v[16:17], 11, v[2:3]
	s_nop 0
	v_addc_co_u32_e32 v145, vcc, 0, v149, vcc
	global_load_dwordx4 v[0:3], v[148:149], off
	v_add_co_u32_e32 v146, vcc, 0x60000, v148
	v_lshl_add_u64 v[140:141], v[176:177], 0, v[16:17]
	global_load_dwordx4 v[8:11], v[144:145], off
	global_load_dwordx4 v[16:19], v[140:141], off
	v_addc_co_u32_e32 v147, vcc, 0, v149, vcc
	global_load_dwordx4 v[4:7], v[150:151], off
	v_add_co_u32_e32 v138, vcc, s94, v140
	global_load_dwordx4 v[12:15], v[146:147], off
	s_nop 0
	v_addc_co_u32_e32 v139, vcc, 0, v141, vcc
	v_add_co_u32_e32 v134, vcc, 0x40000, v140
	global_load_dwordx4 v[20:23], v[138:139], off
	s_nop 0
	v_addc_co_u32_e32 v135, vcc, 0, v141, vcc
	global_load_dwordx4 v[24:27], v[134:135], off
	v_add_co_u32_e32 v136, vcc, s95, v140
	s_nop 1
	v_addc_co_u32_e32 v137, vcc, 0, v141, vcc
	global_load_dwordx4 v[28:31], v[136:137], off
	global_load_dwordx4 v[172:175], v[148:149], off offset:128
	global_load_dwordx4 v[182:185], v[150:151], off offset:128
	global_load_dwordx4 v[186:189], v[144:145], off offset:128
	global_load_dwordx4 v[190:193], v[146:147], off offset:128
	global_load_dwordx4 v[194:197], v[140:141], off offset:128
	global_load_dwordx4 v[198:201], v[138:139], off offset:128
	global_load_dwordx4 v[202:205], v[134:135], off offset:128
	global_load_dwordx4 v[206:209], v[136:137], off offset:128
	s_waitcnt vmcnt(15)
	ds_write_b128 v162, v[0:3]
	s_waitcnt vmcnt(13)
	ds_write_b128 v162, v[16:19] offset:36864
	s_waitcnt vmcnt(12)
	ds_write_b128 v162, v[4:7] offset:9216
	ds_write_b128 v162, v[8:11] offset:18432
	s_waitcnt vmcnt(11)
	ds_write_b128 v162, v[12:15] offset:27648
	s_waitcnt vmcnt(10)
	ds_write_b128 v162, v[20:23] offset:46080
	s_waitcnt vmcnt(9)
	ds_write_b128 v162, v[24:27] offset:55296
	s_waitcnt vmcnt(8)
	ds_write_b128 v162, v[28:31] offset:64512
	s_waitcnt lgkmcnt(0)
	s_barrier
	ds_read_b128 v[0:3], v163 offset:36864
	ds_read_b128 v[210:213], v163 offset:36896
	ds_read_b128 v[4:7], v163 offset:41472
	ds_read_b128 v[214:217], v163 offset:41504
	ds_read_b128 v[8:11], v154
	ds_read_b128 v[218:221], v154 offset:32
	ds_read_b128 v[12:15], v154 offset:4608
	ds_read_b128 v[222:225], v154 offset:4640
	ds_read_b128 v[16:19], v154 offset:9216
	ds_read_b128 v[226:229], v154 offset:9248
	ds_read_b128 v[230:233], v154 offset:13824
	ds_read_b128 v[234:237], v154 offset:13856
	s_waitcnt lgkmcnt(7)
	v_mfma_f32_32x32x16_bf16 v[112:127], v[8:11], v[0:3], 0
	v_mfma_f32_32x32x16_bf16 v[96:111], v[8:11], v[4:7], 0
	s_waitcnt lgkmcnt(5)
	v_mfma_f32_32x32x16_bf16 v[80:95], v[12:15], v[0:3], 0
	v_mfma_f32_32x32x16_bf16 v[64:79], v[12:15], v[4:7], 0
	s_waitcnt lgkmcnt(3)
	v_mfma_f32_32x32x16_bf16 v[48:63], v[16:19], v[0:3], 0
	v_mfma_f32_32x32x16_bf16 v[32:47], v[16:19], v[4:7], 0
	s_waitcnt lgkmcnt(1)
	v_mfma_f32_32x32x16_bf16 v[16:31], v[230:233], v[0:3], 0
	v_mfma_f32_32x32x16_bf16 v[0:15], v[230:233], v[4:7], 0
	global_load_dwordx4 v[230:233], v[148:149], off offset:256
	global_load_dwordx4 v[238:241], v[150:151], off offset:256
	s_waitcnt vmcnt(9)
	ds_write_b128 v164, v[172:175]
	s_waitcnt vmcnt(8)
	ds_write_b128 v164, v[182:185] offset:9216
	ds_read_b128 v[172:175], v163 offset:36928
	ds_read_b128 v[182:185], v163 offset:41536
	ds_read_b128 v[242:245], v154 offset:64
	ds_read_b128 v[246:249], v154 offset:4672
	ds_read_b128 v[130:133], v154 offset:9280
	ds_read_b128 v[158:161], v154 offset:13888
	v_mfma_f32_32x32x16_bf16 v[80:95], v[222:225], v[210:213], v[80:95]
	v_mfma_f32_32x32x16_bf16 v[64:79], v[222:225], v[214:217], v[64:79]
	v_mfma_f32_32x32x16_bf16 v[48:63], v[226:229], v[210:213], v[48:63]
	v_mfma_f32_32x32x16_bf16 v[32:47], v[226:229], v[214:217], v[32:47]
	s_waitcnt lgkmcnt(8)
	v_mfma_f32_32x32x16_bf16 v[16:31], v[234:237], v[210:213], v[16:31]
	v_mfma_f32_32x32x16_bf16 v[0:15], v[234:237], v[214:217], v[0:15]
	v_mfma_f32_32x32x16_bf16 v[112:127], v[218:221], v[210:213], v[112:127]
	v_mfma_f32_32x32x16_bf16 v[96:111], v[218:221], v[214:217], v[96:111]
	global_load_dwordx4 v[210:213], v[144:145], off offset:256
	global_load_dwordx4 v[214:217], v[146:147], off offset:256
	s_waitcnt vmcnt(9)
	ds_write_b128 v164, v[186:189] offset:18432
	s_waitcnt vmcnt(8)
	ds_write_b128 v164, v[190:193] offset:27648
	ds_read_b128 v[186:189], v163 offset:36960
	ds_read_b128 v[190:193], v163 offset:41568
	ds_read_b128 v[218:221], v154 offset:96
	ds_read_b128 v[222:225], v154 offset:4704
	ds_read_b128 v[226:229], v154 offset:9312
	ds_read_b128 v[234:237], v154 offset:13920
	s_waitcnt lgkmcnt(10)
	v_mfma_f32_32x32x16_bf16 v[80:95], v[246:249], v[172:175], v[80:95]
	v_mfma_f32_32x32x16_bf16 v[64:79], v[246:249], v[182:185], v[64:79]
	s_waitcnt lgkmcnt(9)
	v_mfma_f32_32x32x16_bf16 v[48:63], v[130:133], v[172:175], v[48:63]
	v_mfma_f32_32x32x16_bf16 v[32:47], v[130:133], v[182:185], v[32:47]
	s_waitcnt lgkmcnt(8)
	v_mfma_f32_32x32x16_bf16 v[16:31], v[158:161], v[172:175], v[16:31]
	v_mfma_f32_32x32x16_bf16 v[0:15], v[158:161], v[182:185], v[0:15]
	v_mfma_f32_32x32x16_bf16 v[112:127], v[242:245], v[172:175], v[112:127]
	v_mfma_f32_32x32x16_bf16 v[96:111], v[242:245], v[182:185], v[96:111]
	global_load_dwordx4 v[130:133], v[140:141], off offset:256
	global_load_dwordx4 v[158:161], v[138:139], off offset:256
	s_waitcnt vmcnt(9)
	ds_write_b128 v165, v[194:197]
	s_waitcnt vmcnt(8)
	ds_write_b128 v166, v[198:201]
	s_waitcnt lgkmcnt(4)
	v_mfma_f32_32x32x16_bf16 v[80:95], v[222:225], v[186:189], v[80:95]
	v_mfma_f32_32x32x16_bf16 v[64:79], v[222:225], v[190:193], v[64:79]
	s_waitcnt lgkmcnt(3)
	v_mfma_f32_32x32x16_bf16 v[48:63], v[226:229], v[186:189], v[48:63]
	v_mfma_f32_32x32x16_bf16 v[32:47], v[226:229], v[190:193], v[32:47]
	s_waitcnt lgkmcnt(2)
	v_mfma_f32_32x32x16_bf16 v[16:31], v[234:237], v[186:189], v[16:31]
	v_mfma_f32_32x32x16_bf16 v[0:15], v[234:237], v[190:193], v[0:15]
	v_mfma_f32_32x32x16_bf16 v[112:127], v[218:221], v[186:189], v[112:127]
	v_mfma_f32_32x32x16_bf16 v[96:111], v[218:221], v[190:193], v[96:111]
	global_load_dwordx4 v[172:175], v[134:135], off offset:256
	global_load_dwordx4 v[182:185], v[136:137], off offset:256
	s_waitcnt vmcnt(9)
	ds_write_b128 v167, v[202:205]
	s_waitcnt vmcnt(8)
	ds_write_b128 v168, v[206:209]
	s_waitcnt lgkmcnt(0)
	s_barrier
	ds_read_b128 v[186:189], v169
	ds_read_b128 v[190:193], v169 offset:32
	ds_read_b128 v[194:197], v169 offset:4608
	ds_read_b128 v[198:201], v169 offset:4640
	ds_read_b128 v[202:205], v155
	ds_read_b128 v[206:209], v155 offset:32
	ds_read_b128 v[218:221], v155 offset:4608
	ds_read_b128 v[222:225], v155 offset:4640
	ds_read_b128 v[226:229], v155 offset:9216
	ds_read_b128 v[234:237], v155 offset:9248
	ds_read_b128 v[242:245], v155 offset:13824
	ds_read_b128 v[246:249], v155 offset:13856
	s_waitcnt lgkmcnt(5)
	v_mfma_f32_32x32x16_bf16 v[80:95], v[218:221], v[186:189], v[80:95]
	v_mfma_f32_32x32x16_bf16 v[64:79], v[218:221], v[194:197], v[64:79]
	s_waitcnt lgkmcnt(3)
	v_mfma_f32_32x32x16_bf16 v[48:63], v[226:229], v[186:189], v[48:63]
	v_mfma_f32_32x32x16_bf16 v[32:47], v[226:229], v[194:197], v[32:47]
	s_waitcnt lgkmcnt(1)
	v_mfma_f32_32x32x16_bf16 v[16:31], v[242:245], v[186:189], v[16:31]
	v_mfma_f32_32x32x16_bf16 v[0:15], v[242:245], v[194:197], v[0:15]
	v_mfma_f32_32x32x16_bf16 v[112:127], v[202:205], v[186:189], v[112:127]
	v_mfma_f32_32x32x16_bf16 v[96:111], v[202:205], v[194:197], v[96:111]
	global_load_dwordx4 v[186:189], v[148:149], off offset:384
	global_load_dwordx4 v[194:197], v[150:151], off offset:384
	s_waitcnt vmcnt(9)
	ds_write_b128 v128, v[230:233]
	s_waitcnt vmcnt(8)
	ds_write_b128 v128, v[238:241] offset:9216
	ds_read_b128 v[202:205], v169 offset:64
	ds_read_b128 v[218:221], v169 offset:4672
	ds_read_b128 v[226:229], v155 offset:64
	ds_read_b128 v[230:233], v155 offset:4672
	ds_read_b128 v[238:241], v155 offset:9280
	ds_read_b128 v[242:245], v155 offset:13888
	v_mfma_f32_32x32x16_bf16 v[80:95], v[222:225], v[190:193], v[80:95]
	v_mfma_f32_32x32x16_bf16 v[64:79], v[222:225], v[198:201], v[64:79]
	v_mfma_f32_32x32x16_bf16 v[48:63], v[234:237], v[190:193], v[48:63]
	v_mfma_f32_32x32x16_bf16 v[32:47], v[234:237], v[198:201], v[32:47]
	s_waitcnt lgkmcnt(8)
	v_mfma_f32_32x32x16_bf16 v[16:31], v[246:249], v[190:193], v[16:31]
	v_mfma_f32_32x32x16_bf16 v[0:15], v[246:249], v[198:201], v[0:15]
	v_mfma_f32_32x32x16_bf16 v[112:127], v[206:209], v[190:193], v[112:127]
	v_mfma_f32_32x32x16_bf16 v[96:111], v[206:209], v[198:201], v[96:111]
	global_load_dwordx4 v[190:193], v[144:145], off offset:384
	global_load_dwordx4 v[198:201], v[146:147], off offset:384
	s_waitcnt vmcnt(9)
	ds_write_b128 v128, v[210:213] offset:18432
	s_waitcnt vmcnt(8)
	ds_write_b128 v128, v[214:217] offset:27648
	ds_read_b128 v[206:209], v169 offset:96
	ds_read_b128 v[210:213], v169 offset:4704
	ds_read_b128 v[214:217], v155 offset:96
	ds_read_b128 v[222:225], v155 offset:4704
	ds_read_b128 v[234:237], v155 offset:9312
	ds_read_b128 v[246:249], v155 offset:13920
	s_waitcnt lgkmcnt(10)
	v_mfma_f32_32x32x16_bf16 v[80:95], v[230:233], v[202:205], v[80:95]
	v_mfma_f32_32x32x16_bf16 v[64:79], v[230:233], v[218:221], v[64:79]
	s_waitcnt lgkmcnt(9)
	v_mfma_f32_32x32x16_bf16 v[48:63], v[238:241], v[202:205], v[48:63]
	v_mfma_f32_32x32x16_bf16 v[32:47], v[238:241], v[218:221], v[32:47]
	s_waitcnt lgkmcnt(8)
	v_mfma_f32_32x32x16_bf16 v[16:31], v[242:245], v[202:205], v[16:31]
	v_mfma_f32_32x32x16_bf16 v[0:15], v[242:245], v[218:221], v[0:15]
	v_mfma_f32_32x32x16_bf16 v[112:127], v[226:229], v[202:205], v[112:127]
	v_mfma_f32_32x32x16_bf16 v[96:111], v[226:229], v[218:221], v[96:111]
	s_waitcnt vmcnt(7)
	ds_write_b128 v128, v[130:133] offset:36864
	global_load_dwordx4 v[130:133], v[140:141], off offset:384
	s_waitcnt vmcnt(7)
	ds_write_b128 v128, v[158:161] offset:46080
	global_load_dwordx4 v[158:161], v[138:139], off offset:384
	s_waitcnt lgkmcnt(4)
	v_mfma_f32_32x32x16_bf16 v[80:95], v[222:225], v[206:209], v[80:95]
	v_mfma_f32_32x32x16_bf16 v[64:79], v[222:225], v[210:213], v[64:79]
	s_waitcnt lgkmcnt(3)
	v_mfma_f32_32x32x16_bf16 v[48:63], v[234:237], v[206:209], v[48:63]
	v_mfma_f32_32x32x16_bf16 v[32:47], v[234:237], v[210:213], v[32:47]
	s_waitcnt lgkmcnt(2)
	v_mfma_f32_32x32x16_bf16 v[16:31], v[246:249], v[206:209], v[16:31]
	v_mfma_f32_32x32x16_bf16 v[0:15], v[246:249], v[210:213], v[0:15]
	v_mfma_f32_32x32x16_bf16 v[112:127], v[214:217], v[206:209], v[112:127]
	v_mfma_f32_32x32x16_bf16 v[96:111], v[214:217], v[210:213], v[96:111]
	global_load_dwordx4 v[202:205], v[134:135], off offset:384
	global_load_dwordx4 v[206:209], v[136:137], off offset:384
	s_waitcnt vmcnt(9)
	ds_write_b128 v128, v[172:175] offset:55296
	s_waitcnt vmcnt(8)
	ds_write_b128 v128, v[182:185] offset:64512
	s_waitcnt lgkmcnt(0)
	s_barrier
	ds_read_b128 v[172:175], v163 offset:36864
	ds_read_b128 v[182:185], v163 offset:36896
	ds_read_b128 v[210:213], v163 offset:41472
	ds_read_b128 v[214:217], v163 offset:41504
	ds_read_b128 v[218:221], v154
	ds_read_b128 v[222:225], v154 offset:32
	ds_read_b128 v[226:229], v154 offset:4608
	ds_read_b128 v[230:233], v154 offset:4640
	ds_read_b128 v[234:237], v154 offset:9216
	ds_read_b128 v[238:241], v154 offset:9248
	ds_read_b128 v[242:245], v154 offset:13824
	ds_read_b128 v[246:249], v154 offset:13856
	s_waitcnt lgkmcnt(5)
	v_mfma_f32_32x32x16_bf16 v[80:95], v[226:229], v[172:175], v[80:95]
	v_mfma_f32_32x32x16_bf16 v[64:79], v[226:229], v[210:213], v[64:79]
	s_waitcnt lgkmcnt(3)
	v_mfma_f32_32x32x16_bf16 v[48:63], v[234:237], v[172:175], v[48:63]
	v_mfma_f32_32x32x16_bf16 v[32:47], v[234:237], v[210:213], v[32:47]
	s_waitcnt lgkmcnt(1)
	v_mfma_f32_32x32x16_bf16 v[16:31], v[242:245], v[172:175], v[16:31]
	v_mfma_f32_32x32x16_bf16 v[0:15], v[242:245], v[210:213], v[0:15]
	v_mfma_f32_32x32x16_bf16 v[112:127], v[218:221], v[172:175], v[112:127]
	v_mfma_f32_32x32x16_bf16 v[96:111], v[218:221], v[210:213], v[96:111]
	global_load_dwordx4 v[172:175], v[148:149], off offset:512
	global_load_dwordx4 v[210:213], v[150:151], off offset:512
	s_waitcnt vmcnt(9)
	ds_write_b128 v164, v[186:189]
	s_waitcnt vmcnt(8)
	ds_write_b128 v164, v[194:197] offset:9216
	ds_read_b128 v[186:189], v163 offset:36928
	ds_read_b128 v[194:197], v163 offset:41536
	ds_read_b128 v[218:221], v154 offset:64
	ds_read_b128 v[226:229], v154 offset:4672
	ds_read_b128 v[234:237], v154 offset:9280
	ds_read_b128 v[242:245], v154 offset:13888
	v_mfma_f32_32x32x16_bf16 v[80:95], v[230:233], v[182:185], v[80:95]
	v_mfma_f32_32x32x16_bf16 v[64:79], v[230:233], v[214:217], v[64:79]
	v_mfma_f32_32x32x16_bf16 v[48:63], v[238:241], v[182:185], v[48:63]
	v_mfma_f32_32x32x16_bf16 v[32:47], v[238:241], v[214:217], v[32:47]
	s_waitcnt lgkmcnt(8)
	v_mfma_f32_32x32x16_bf16 v[16:31], v[246:249], v[182:185], v[16:31]
	v_mfma_f32_32x32x16_bf16 v[0:15], v[246:249], v[214:217], v[0:15]
	v_mfma_f32_32x32x16_bf16 v[112:127], v[222:225], v[182:185], v[112:127]
	v_mfma_f32_32x32x16_bf16 v[96:111], v[222:225], v[214:217], v[96:111]
	global_load_dwordx4 v[182:185], v[144:145], off offset:512
	global_load_dwordx4 v[214:217], v[146:147], off offset:512
	s_waitcnt vmcnt(9)
	ds_write_b128 v164, v[190:193] offset:18432
	s_waitcnt vmcnt(8)
	ds_write_b128 v164, v[198:201] offset:27648
	ds_read_b128 v[190:193], v163 offset:36960
	ds_read_b128 v[198:201], v163 offset:41568
	ds_read_b128 v[222:225], v154 offset:96
	ds_read_b128 v[230:233], v154 offset:4704
	ds_read_b128 v[238:241], v154 offset:9312
	ds_read_b128 v[246:249], v154 offset:13920
	s_waitcnt lgkmcnt(10)
	v_mfma_f32_32x32x16_bf16 v[80:95], v[226:229], v[186:189], v[80:95]
	v_mfma_f32_32x32x16_bf16 v[64:79], v[226:229], v[194:197], v[64:79]
	s_waitcnt lgkmcnt(9)
	v_mfma_f32_32x32x16_bf16 v[48:63], v[234:237], v[186:189], v[48:63]
	v_mfma_f32_32x32x16_bf16 v[32:47], v[234:237], v[194:197], v[32:47]
	s_waitcnt lgkmcnt(8)
	v_mfma_f32_32x32x16_bf16 v[16:31], v[242:245], v[186:189], v[16:31]
	v_mfma_f32_32x32x16_bf16 v[0:15], v[242:245], v[194:197], v[0:15]
	v_mfma_f32_32x32x16_bf16 v[112:127], v[218:221], v[186:189], v[112:127]
	v_mfma_f32_32x32x16_bf16 v[96:111], v[218:221], v[194:197], v[96:111]
	s_waitcnt vmcnt(7)
	ds_write_b128 v165, v[130:133]
	global_load_dwordx4 v[130:133], v[140:141], off offset:512
	s_waitcnt vmcnt(7)
	ds_write_b128 v166, v[158:161]
	global_load_dwordx4 v[158:161], v[138:139], off offset:512
	s_waitcnt lgkmcnt(4)
	v_mfma_f32_32x32x16_bf16 v[80:95], v[230:233], v[190:193], v[80:95]
	v_mfma_f32_32x32x16_bf16 v[64:79], v[230:233], v[198:201], v[64:79]
	s_waitcnt lgkmcnt(3)
	v_mfma_f32_32x32x16_bf16 v[48:63], v[238:241], v[190:193], v[48:63]
	v_mfma_f32_32x32x16_bf16 v[32:47], v[238:241], v[198:201], v[32:47]
	s_waitcnt lgkmcnt(2)
	v_mfma_f32_32x32x16_bf16 v[16:31], v[246:249], v[190:193], v[16:31]
	v_mfma_f32_32x32x16_bf16 v[0:15], v[246:249], v[198:201], v[0:15]
	v_mfma_f32_32x32x16_bf16 v[112:127], v[222:225], v[190:193], v[112:127]
	v_mfma_f32_32x32x16_bf16 v[96:111], v[222:225], v[198:201], v[96:111]
	global_load_dwordx4 v[186:189], v[134:135], off offset:512
	global_load_dwordx4 v[190:193], v[136:137], off offset:512
	s_waitcnt vmcnt(9)
	ds_write_b128 v167, v[202:205]
	s_waitcnt vmcnt(8)
	ds_write_b128 v168, v[206:209]
	s_waitcnt lgkmcnt(0)
	s_barrier
	ds_read_b128 v[194:197], v169
	ds_read_b128 v[198:201], v169 offset:32
	ds_read_b128 v[202:205], v169 offset:4608
	ds_read_b128 v[206:209], v169 offset:4640
	ds_read_b128 v[218:221], v155
	ds_read_b128 v[222:225], v155 offset:32
	ds_read_b128 v[226:229], v155 offset:4608
	ds_read_b128 v[230:233], v155 offset:4640
	ds_read_b128 v[234:237], v155 offset:9216
	ds_read_b128 v[238:241], v155 offset:9248
	ds_read_b128 v[242:245], v155 offset:13824
	ds_read_b128 v[246:249], v155 offset:13856
	s_waitcnt lgkmcnt(5)
	v_mfma_f32_32x32x16_bf16 v[80:95], v[226:229], v[194:197], v[80:95]
	v_mfma_f32_32x32x16_bf16 v[64:79], v[226:229], v[202:205], v[64:79]
	s_waitcnt lgkmcnt(3)
	v_mfma_f32_32x32x16_bf16 v[48:63], v[234:237], v[194:197], v[48:63]
	v_mfma_f32_32x32x16_bf16 v[32:47], v[234:237], v[202:205], v[32:47]
	s_waitcnt lgkmcnt(1)
	v_mfma_f32_32x32x16_bf16 v[16:31], v[242:245], v[194:197], v[16:31]
	v_mfma_f32_32x32x16_bf16 v[0:15], v[242:245], v[202:205], v[0:15]
	v_mfma_f32_32x32x16_bf16 v[112:127], v[218:221], v[194:197], v[112:127]
	v_mfma_f32_32x32x16_bf16 v[96:111], v[218:221], v[202:205], v[96:111]
	global_load_dwordx4 v[194:197], v[148:149], off offset:640
	global_load_dwordx4 v[202:205], v[150:151], off offset:640
	s_waitcnt vmcnt(9)
	ds_write_b128 v128, v[172:175]
	s_waitcnt vmcnt(8)
	ds_write_b128 v128, v[210:213] offset:9216
	ds_read_b128 v[172:175], v169 offset:64
	ds_read_b128 v[210:213], v169 offset:4672
	ds_read_b128 v[218:221], v155 offset:64
	ds_read_b128 v[226:229], v155 offset:4672
	ds_read_b128 v[234:237], v155 offset:9280
	ds_read_b128 v[242:245], v155 offset:13888
	v_mfma_f32_32x32x16_bf16 v[80:95], v[230:233], v[198:201], v[80:95]
	v_mfma_f32_32x32x16_bf16 v[64:79], v[230:233], v[206:209], v[64:79]
	v_mfma_f32_32x32x16_bf16 v[48:63], v[238:241], v[198:201], v[48:63]
	v_mfma_f32_32x32x16_bf16 v[32:47], v[238:241], v[206:209], v[32:47]
	s_waitcnt lgkmcnt(8)
	v_mfma_f32_32x32x16_bf16 v[16:31], v[246:249], v[198:201], v[16:31]
	v_mfma_f32_32x32x16_bf16 v[0:15], v[246:249], v[206:209], v[0:15]
	v_mfma_f32_32x32x16_bf16 v[112:127], v[222:225], v[198:201], v[112:127]
	v_mfma_f32_32x32x16_bf16 v[96:111], v[222:225], v[206:209], v[96:111]
	global_load_dwordx4 v[198:201], v[144:145], off offset:640
	global_load_dwordx4 v[206:209], v[146:147], off offset:640
	s_waitcnt vmcnt(9)
	ds_write_b128 v128, v[182:185] offset:18432
	s_waitcnt vmcnt(8)
	ds_write_b128 v128, v[214:217] offset:27648
	ds_read_b128 v[182:185], v169 offset:96
	ds_read_b128 v[214:217], v169 offset:4704
	ds_read_b128 v[222:225], v155 offset:96
	ds_read_b128 v[230:233], v155 offset:4704
	ds_read_b128 v[238:241], v155 offset:9312
	ds_read_b128 v[246:249], v155 offset:13920
	s_waitcnt lgkmcnt(10)
	v_mfma_f32_32x32x16_bf16 v[80:95], v[226:229], v[172:175], v[80:95]
	v_mfma_f32_32x32x16_bf16 v[64:79], v[226:229], v[210:213], v[64:79]
	s_waitcnt lgkmcnt(9)
	v_mfma_f32_32x32x16_bf16 v[48:63], v[234:237], v[172:175], v[48:63]
	v_mfma_f32_32x32x16_bf16 v[32:47], v[234:237], v[210:213], v[32:47]
	s_waitcnt lgkmcnt(8)
	v_mfma_f32_32x32x16_bf16 v[16:31], v[242:245], v[172:175], v[16:31]
	v_mfma_f32_32x32x16_bf16 v[0:15], v[242:245], v[210:213], v[0:15]
	v_mfma_f32_32x32x16_bf16 v[112:127], v[218:221], v[172:175], v[112:127]
	v_mfma_f32_32x32x16_bf16 v[96:111], v[218:221], v[210:213], v[96:111]
	s_waitcnt vmcnt(7)
	ds_write_b128 v128, v[130:133] offset:36864
	global_load_dwordx4 v[130:133], v[140:141], off offset:640
	s_waitcnt vmcnt(7)
	ds_write_b128 v128, v[158:161] offset:46080
	global_load_dwordx4 v[158:161], v[138:139], off offset:640
	s_waitcnt lgkmcnt(4)
	v_mfma_f32_32x32x16_bf16 v[80:95], v[230:233], v[182:185], v[80:95]
	v_mfma_f32_32x32x16_bf16 v[64:79], v[230:233], v[214:217], v[64:79]
	s_waitcnt lgkmcnt(3)
	v_mfma_f32_32x32x16_bf16 v[48:63], v[238:241], v[182:185], v[48:63]
	v_mfma_f32_32x32x16_bf16 v[32:47], v[238:241], v[214:217], v[32:47]
	s_waitcnt lgkmcnt(2)
	v_mfma_f32_32x32x16_bf16 v[16:31], v[246:249], v[182:185], v[16:31]
	v_mfma_f32_32x32x16_bf16 v[0:15], v[246:249], v[214:217], v[0:15]
	v_mfma_f32_32x32x16_bf16 v[112:127], v[222:225], v[182:185], v[112:127]
	v_mfma_f32_32x32x16_bf16 v[96:111], v[222:225], v[214:217], v[96:111]
	global_load_dwordx4 v[172:175], v[134:135], off offset:640
	global_load_dwordx4 v[182:185], v[136:137], off offset:640
	s_waitcnt vmcnt(9)
	ds_write_b128 v128, v[186:189] offset:55296
	s_waitcnt vmcnt(8)
	ds_write_b128 v128, v[190:193] offset:64512
	s_waitcnt lgkmcnt(0)
	s_barrier
	ds_read_b128 v[186:189], v163 offset:36864
	ds_read_b128 v[190:193], v163 offset:36896
	ds_read_b128 v[210:213], v163 offset:41472
	ds_read_b128 v[214:217], v163 offset:41504
	ds_read_b128 v[218:221], v154
	ds_read_b128 v[222:225], v154 offset:32
	ds_read_b128 v[226:229], v154 offset:4608
	ds_read_b128 v[230:233], v154 offset:4640
	ds_read_b128 v[234:237], v154 offset:9216
	ds_read_b128 v[238:241], v154 offset:9248
	ds_read_b128 v[242:245], v154 offset:13824
	ds_read_b128 v[246:249], v154 offset:13856
	s_waitcnt lgkmcnt(5)
	v_mfma_f32_32x32x16_bf16 v[80:95], v[226:229], v[186:189], v[80:95]
	v_mfma_f32_32x32x16_bf16 v[64:79], v[226:229], v[210:213], v[64:79]
	s_waitcnt lgkmcnt(3)
	v_mfma_f32_32x32x16_bf16 v[48:63], v[234:237], v[186:189], v[48:63]
	v_mfma_f32_32x32x16_bf16 v[32:47], v[234:237], v[210:213], v[32:47]
	s_waitcnt lgkmcnt(1)
	v_mfma_f32_32x32x16_bf16 v[16:31], v[242:245], v[186:189], v[16:31]
	v_mfma_f32_32x32x16_bf16 v[0:15], v[242:245], v[210:213], v[0:15]
	v_mfma_f32_32x32x16_bf16 v[112:127], v[218:221], v[186:189], v[112:127]
	v_mfma_f32_32x32x16_bf16 v[96:111], v[218:221], v[210:213], v[96:111]
	global_load_dwordx4 v[186:189], v[148:149], off offset:768
	global_load_dwordx4 v[210:213], v[150:151], off offset:768
	s_waitcnt vmcnt(9)
	ds_write_b128 v164, v[194:197]
	s_waitcnt vmcnt(8)
	ds_write_b128 v164, v[202:205] offset:9216
	ds_read_b128 v[194:197], v163 offset:36928
	ds_read_b128 v[202:205], v163 offset:41536
	ds_read_b128 v[218:221], v154 offset:64
	ds_read_b128 v[226:229], v154 offset:4672
	ds_read_b128 v[234:237], v154 offset:9280
	ds_read_b128 v[242:245], v154 offset:13888
	v_mfma_f32_32x32x16_bf16 v[80:95], v[230:233], v[190:193], v[80:95]
	v_mfma_f32_32x32x16_bf16 v[64:79], v[230:233], v[214:217], v[64:79]
	v_mfma_f32_32x32x16_bf16 v[48:63], v[238:241], v[190:193], v[48:63]
	v_mfma_f32_32x32x16_bf16 v[32:47], v[238:241], v[214:217], v[32:47]
	s_waitcnt lgkmcnt(8)
	v_mfma_f32_32x32x16_bf16 v[16:31], v[246:249], v[190:193], v[16:31]
	v_mfma_f32_32x32x16_bf16 v[0:15], v[246:249], v[214:217], v[0:15]
	v_mfma_f32_32x32x16_bf16 v[112:127], v[222:225], v[190:193], v[112:127]
	v_mfma_f32_32x32x16_bf16 v[96:111], v[222:225], v[214:217], v[96:111]
	global_load_dwordx4 v[190:193], v[144:145], off offset:768
	global_load_dwordx4 v[214:217], v[146:147], off offset:768
	s_waitcnt vmcnt(9)
	ds_write_b128 v164, v[198:201] offset:18432
	s_waitcnt vmcnt(8)
	ds_write_b128 v164, v[206:209] offset:27648
	ds_read_b128 v[198:201], v163 offset:36960
	ds_read_b128 v[206:209], v163 offset:41568
	ds_read_b128 v[222:225], v154 offset:96
	ds_read_b128 v[230:233], v154 offset:4704
	ds_read_b128 v[238:241], v154 offset:9312
	ds_read_b128 v[246:249], v154 offset:13920
	s_waitcnt lgkmcnt(10)
	v_mfma_f32_32x32x16_bf16 v[80:95], v[226:229], v[194:197], v[80:95]
	v_mfma_f32_32x32x16_bf16 v[64:79], v[226:229], v[202:205], v[64:79]
	s_waitcnt lgkmcnt(9)
	v_mfma_f32_32x32x16_bf16 v[48:63], v[234:237], v[194:197], v[48:63]
	v_mfma_f32_32x32x16_bf16 v[32:47], v[234:237], v[202:205], v[32:47]
	s_waitcnt lgkmcnt(8)
	v_mfma_f32_32x32x16_bf16 v[16:31], v[242:245], v[194:197], v[16:31]
	v_mfma_f32_32x32x16_bf16 v[0:15], v[242:245], v[202:205], v[0:15]
	v_mfma_f32_32x32x16_bf16 v[112:127], v[218:221], v[194:197], v[112:127]
	v_mfma_f32_32x32x16_bf16 v[96:111], v[218:221], v[202:205], v[96:111]
	s_waitcnt vmcnt(7)
	ds_write_b128 v165, v[130:133]
	global_load_dwordx4 v[130:133], v[140:141], off offset:768
	s_waitcnt vmcnt(7)
	ds_write_b128 v166, v[158:161]
	global_load_dwordx4 v[158:161], v[138:139], off offset:768
	s_waitcnt lgkmcnt(4)
	v_mfma_f32_32x32x16_bf16 v[80:95], v[230:233], v[198:201], v[80:95]
	v_mfma_f32_32x32x16_bf16 v[64:79], v[230:233], v[206:209], v[64:79]
	s_waitcnt lgkmcnt(3)
	v_mfma_f32_32x32x16_bf16 v[48:63], v[238:241], v[198:201], v[48:63]
	v_mfma_f32_32x32x16_bf16 v[32:47], v[238:241], v[206:209], v[32:47]
	s_waitcnt lgkmcnt(2)
	v_mfma_f32_32x32x16_bf16 v[16:31], v[246:249], v[198:201], v[16:31]
	v_mfma_f32_32x32x16_bf16 v[0:15], v[246:249], v[206:209], v[0:15]
	v_mfma_f32_32x32x16_bf16 v[112:127], v[222:225], v[198:201], v[112:127]
	v_mfma_f32_32x32x16_bf16 v[96:111], v[222:225], v[206:209], v[96:111]
	global_load_dwordx4 v[194:197], v[134:135], off offset:768
	global_load_dwordx4 v[198:201], v[136:137], off offset:768
	s_waitcnt vmcnt(9)
	ds_write_b128 v167, v[172:175]
	s_waitcnt vmcnt(8)
	ds_write_b128 v168, v[182:185]
	s_waitcnt lgkmcnt(0)
	s_barrier
	ds_read_b128 v[172:175], v169
	ds_read_b128 v[182:185], v169 offset:32
	ds_read_b128 v[202:205], v169 offset:4608
	ds_read_b128 v[206:209], v169 offset:4640
	ds_read_b128 v[218:221], v155
	ds_read_b128 v[222:225], v155 offset:32
	ds_read_b128 v[226:229], v155 offset:4608
	ds_read_b128 v[230:233], v155 offset:4640
	ds_read_b128 v[234:237], v155 offset:9216
	ds_read_b128 v[238:241], v155 offset:9248
	ds_read_b128 v[242:245], v155 offset:13824
	ds_read_b128 v[246:249], v155 offset:13856
	s_waitcnt lgkmcnt(5)
	v_mfma_f32_32x32x16_bf16 v[80:95], v[226:229], v[172:175], v[80:95]
	v_mfma_f32_32x32x16_bf16 v[64:79], v[226:229], v[202:205], v[64:79]
	s_waitcnt lgkmcnt(3)
	v_mfma_f32_32x32x16_bf16 v[48:63], v[234:237], v[172:175], v[48:63]
	v_mfma_f32_32x32x16_bf16 v[32:47], v[234:237], v[202:205], v[32:47]
	s_waitcnt lgkmcnt(1)
	v_mfma_f32_32x32x16_bf16 v[16:31], v[242:245], v[172:175], v[16:31]
	v_mfma_f32_32x32x16_bf16 v[0:15], v[242:245], v[202:205], v[0:15]
	v_mfma_f32_32x32x16_bf16 v[112:127], v[218:221], v[172:175], v[112:127]
	v_mfma_f32_32x32x16_bf16 v[96:111], v[218:221], v[202:205], v[96:111]
	global_load_dwordx4 v[172:175], v[148:149], off offset:896
	global_load_dwordx4 v[202:205], v[150:151], off offset:896
	s_waitcnt vmcnt(9)
	ds_write_b128 v128, v[186:189]
	s_waitcnt vmcnt(8)
	ds_write_b128 v128, v[210:213] offset:9216
	ds_read_b128 v[186:189], v169 offset:64
	ds_read_b128 v[210:213], v169 offset:4672
	ds_read_b128 v[218:221], v155 offset:64
	ds_read_b128 v[226:229], v155 offset:4672
	ds_read_b128 v[234:237], v155 offset:9280
	ds_read_b128 v[242:245], v155 offset:13888
	v_mfma_f32_32x32x16_bf16 v[80:95], v[230:233], v[182:185], v[80:95]
	v_mfma_f32_32x32x16_bf16 v[64:79], v[230:233], v[206:209], v[64:79]
	v_mfma_f32_32x32x16_bf16 v[48:63], v[238:241], v[182:185], v[48:63]
	v_mfma_f32_32x32x16_bf16 v[32:47], v[238:241], v[206:209], v[32:47]
	s_waitcnt lgkmcnt(8)
	v_mfma_f32_32x32x16_bf16 v[16:31], v[246:249], v[182:185], v[16:31]
	v_mfma_f32_32x32x16_bf16 v[0:15], v[246:249], v[206:209], v[0:15]
	v_mfma_f32_32x32x16_bf16 v[112:127], v[222:225], v[182:185], v[112:127]
	v_mfma_f32_32x32x16_bf16 v[96:111], v[222:225], v[206:209], v[96:111]
	global_load_dwordx4 v[182:185], v[144:145], off offset:896
	global_load_dwordx4 v[206:209], v[146:147], off offset:896
	s_waitcnt vmcnt(9)
	ds_write_b128 v128, v[190:193] offset:18432
	s_waitcnt vmcnt(8)
	ds_write_b128 v128, v[214:217] offset:27648
	ds_read_b128 v[190:193], v169 offset:96
	ds_read_b128 v[214:217], v169 offset:4704
	ds_read_b128 v[222:225], v155 offset:96
	ds_read_b128 v[230:233], v155 offset:4704
	ds_read_b128 v[238:241], v155 offset:9312
	ds_read_b128 v[246:249], v155 offset:13920
	s_waitcnt lgkmcnt(10)
	v_mfma_f32_32x32x16_bf16 v[80:95], v[226:229], v[186:189], v[80:95]
	v_mfma_f32_32x32x16_bf16 v[64:79], v[226:229], v[210:213], v[64:79]
	s_waitcnt lgkmcnt(9)
	v_mfma_f32_32x32x16_bf16 v[48:63], v[234:237], v[186:189], v[48:63]
	v_mfma_f32_32x32x16_bf16 v[32:47], v[234:237], v[210:213], v[32:47]
	s_waitcnt lgkmcnt(8)
	v_mfma_f32_32x32x16_bf16 v[16:31], v[242:245], v[186:189], v[16:31]
	v_mfma_f32_32x32x16_bf16 v[0:15], v[242:245], v[210:213], v[0:15]
	v_mfma_f32_32x32x16_bf16 v[112:127], v[218:221], v[186:189], v[112:127]
	v_mfma_f32_32x32x16_bf16 v[96:111], v[218:221], v[210:213], v[96:111]
	s_waitcnt vmcnt(7)
	ds_write_b128 v128, v[130:133] offset:36864
	global_load_dwordx4 v[130:133], v[140:141], off offset:896
	s_waitcnt vmcnt(7)
	ds_write_b128 v128, v[158:161] offset:46080
	global_load_dwordx4 v[158:161], v[138:139], off offset:896
	s_waitcnt lgkmcnt(4)
	v_mfma_f32_32x32x16_bf16 v[80:95], v[230:233], v[190:193], v[80:95]
	v_mfma_f32_32x32x16_bf16 v[64:79], v[230:233], v[214:217], v[64:79]
	s_waitcnt lgkmcnt(3)
	v_mfma_f32_32x32x16_bf16 v[48:63], v[238:241], v[190:193], v[48:63]
	v_mfma_f32_32x32x16_bf16 v[32:47], v[238:241], v[214:217], v[32:47]
	s_waitcnt lgkmcnt(2)
	v_mfma_f32_32x32x16_bf16 v[16:31], v[246:249], v[190:193], v[16:31]
	v_mfma_f32_32x32x16_bf16 v[0:15], v[246:249], v[214:217], v[0:15]
	v_mfma_f32_32x32x16_bf16 v[112:127], v[222:225], v[190:193], v[112:127]
	v_mfma_f32_32x32x16_bf16 v[96:111], v[222:225], v[214:217], v[96:111]
	global_load_dwordx4 v[186:189], v[134:135], off offset:896
	global_load_dwordx4 v[190:193], v[136:137], off offset:896
	s_waitcnt vmcnt(9)
	ds_write_b128 v128, v[194:197] offset:55296
	s_waitcnt vmcnt(8)
	ds_write_b128 v128, v[198:201] offset:64512
	s_waitcnt lgkmcnt(0)
	s_barrier
	ds_read_b128 v[194:197], v163 offset:36864
	ds_read_b128 v[198:201], v163 offset:36896
	ds_read_b128 v[210:213], v163 offset:41472
	ds_read_b128 v[214:217], v163 offset:41504
	ds_read_b128 v[218:221], v154
	ds_read_b128 v[222:225], v154 offset:32
	ds_read_b128 v[226:229], v154 offset:4608
	ds_read_b128 v[230:233], v154 offset:4640
	ds_read_b128 v[234:237], v154 offset:9216
	ds_read_b128 v[238:241], v154 offset:9248
	ds_read_b128 v[242:245], v154 offset:13824
	ds_read_b128 v[246:249], v154 offset:13856
	s_waitcnt lgkmcnt(5)
	v_mfma_f32_32x32x16_bf16 v[80:95], v[226:229], v[194:197], v[80:95]
	v_mfma_f32_32x32x16_bf16 v[64:79], v[226:229], v[210:213], v[64:79]
	s_waitcnt lgkmcnt(3)
	v_mfma_f32_32x32x16_bf16 v[48:63], v[234:237], v[194:197], v[48:63]
	v_mfma_f32_32x32x16_bf16 v[32:47], v[234:237], v[210:213], v[32:47]
	s_waitcnt lgkmcnt(1)
	v_mfma_f32_32x32x16_bf16 v[16:31], v[242:245], v[194:197], v[16:31]
	v_mfma_f32_32x32x16_bf16 v[0:15], v[242:245], v[210:213], v[0:15]
	v_mfma_f32_32x32x16_bf16 v[112:127], v[218:221], v[194:197], v[112:127]
	v_mfma_f32_32x32x16_bf16 v[96:111], v[218:221], v[210:213], v[96:111]
	global_load_dwordx4 v[194:197], v[148:149], off offset:1024
	global_load_dwordx4 v[210:213], v[150:151], off offset:1024
	s_waitcnt vmcnt(9)
	ds_write_b128 v164, v[172:175]
	s_waitcnt vmcnt(8)
	ds_write_b128 v164, v[202:205] offset:9216
	ds_read_b128 v[172:175], v163 offset:36928
	ds_read_b128 v[202:205], v163 offset:41536
	ds_read_b128 v[218:221], v154 offset:64
	ds_read_b128 v[226:229], v154 offset:4672
	ds_read_b128 v[234:237], v154 offset:9280
	ds_read_b128 v[242:245], v154 offset:13888
	v_mfma_f32_32x32x16_bf16 v[80:95], v[230:233], v[198:201], v[80:95]
	v_mfma_f32_32x32x16_bf16 v[64:79], v[230:233], v[214:217], v[64:79]
	v_mfma_f32_32x32x16_bf16 v[48:63], v[238:241], v[198:201], v[48:63]
	v_mfma_f32_32x32x16_bf16 v[32:47], v[238:241], v[214:217], v[32:47]
	s_waitcnt lgkmcnt(8)
	v_mfma_f32_32x32x16_bf16 v[16:31], v[246:249], v[198:201], v[16:31]
	v_mfma_f32_32x32x16_bf16 v[0:15], v[246:249], v[214:217], v[0:15]
	v_mfma_f32_32x32x16_bf16 v[112:127], v[222:225], v[198:201], v[112:127]
	v_mfma_f32_32x32x16_bf16 v[96:111], v[222:225], v[214:217], v[96:111]
	global_load_dwordx4 v[198:201], v[144:145], off offset:1024
	global_load_dwordx4 v[214:217], v[146:147], off offset:1024
	s_waitcnt vmcnt(9)
	ds_write_b128 v164, v[182:185] offset:18432
	s_waitcnt vmcnt(8)
	ds_write_b128 v164, v[206:209] offset:27648
	ds_read_b128 v[182:185], v163 offset:36960
	ds_read_b128 v[206:209], v163 offset:41568
	ds_read_b128 v[222:225], v154 offset:96
	ds_read_b128 v[230:233], v154 offset:4704
	ds_read_b128 v[238:241], v154 offset:9312
	ds_read_b128 v[246:249], v154 offset:13920
	s_waitcnt lgkmcnt(10)
	v_mfma_f32_32x32x16_bf16 v[80:95], v[226:229], v[172:175], v[80:95]
	v_mfma_f32_32x32x16_bf16 v[64:79], v[226:229], v[202:205], v[64:79]
	s_waitcnt lgkmcnt(9)
	v_mfma_f32_32x32x16_bf16 v[48:63], v[234:237], v[172:175], v[48:63]
	v_mfma_f32_32x32x16_bf16 v[32:47], v[234:237], v[202:205], v[32:47]
	s_waitcnt lgkmcnt(8)
	v_mfma_f32_32x32x16_bf16 v[16:31], v[242:245], v[172:175], v[16:31]
	v_mfma_f32_32x32x16_bf16 v[0:15], v[242:245], v[202:205], v[0:15]
	v_mfma_f32_32x32x16_bf16 v[112:127], v[218:221], v[172:175], v[112:127]
	v_mfma_f32_32x32x16_bf16 v[96:111], v[218:221], v[202:205], v[96:111]
	s_waitcnt vmcnt(7)
	ds_write_b128 v165, v[130:133]
	global_load_dwordx4 v[130:133], v[140:141], off offset:1024
	s_waitcnt vmcnt(7)
	ds_write_b128 v166, v[158:161]
	global_load_dwordx4 v[158:161], v[138:139], off offset:1024
	s_waitcnt lgkmcnt(4)
	v_mfma_f32_32x32x16_bf16 v[80:95], v[230:233], v[182:185], v[80:95]
	v_mfma_f32_32x32x16_bf16 v[64:79], v[230:233], v[206:209], v[64:79]
	s_waitcnt lgkmcnt(3)
	v_mfma_f32_32x32x16_bf16 v[48:63], v[238:241], v[182:185], v[48:63]
	v_mfma_f32_32x32x16_bf16 v[32:47], v[238:241], v[206:209], v[32:47]
	s_waitcnt lgkmcnt(2)
	v_mfma_f32_32x32x16_bf16 v[16:31], v[246:249], v[182:185], v[16:31]
	v_mfma_f32_32x32x16_bf16 v[0:15], v[246:249], v[206:209], v[0:15]
	v_mfma_f32_32x32x16_bf16 v[112:127], v[222:225], v[182:185], v[112:127]
	v_mfma_f32_32x32x16_bf16 v[96:111], v[222:225], v[206:209], v[96:111]
	global_load_dwordx4 v[172:175], v[134:135], off offset:1024
	global_load_dwordx4 v[182:185], v[136:137], off offset:1024
	s_waitcnt vmcnt(9)
	ds_write_b128 v167, v[186:189]
	s_waitcnt vmcnt(8)
	ds_write_b128 v168, v[190:193]
	s_waitcnt lgkmcnt(0)
	s_barrier
	ds_read_b128 v[186:189], v169
	ds_read_b128 v[190:193], v169 offset:32
	ds_read_b128 v[202:205], v169 offset:4608
	ds_read_b128 v[206:209], v169 offset:4640
	ds_read_b128 v[218:221], v155
	ds_read_b128 v[222:225], v155 offset:32
	ds_read_b128 v[226:229], v155 offset:4608
	ds_read_b128 v[230:233], v155 offset:4640
	ds_read_b128 v[234:237], v155 offset:9216
	ds_read_b128 v[238:241], v155 offset:9248
	ds_read_b128 v[242:245], v155 offset:13824
	ds_read_b128 v[246:249], v155 offset:13856
	s_waitcnt lgkmcnt(5)
	v_mfma_f32_32x32x16_bf16 v[80:95], v[226:229], v[186:189], v[80:95]
	v_mfma_f32_32x32x16_bf16 v[64:79], v[226:229], v[202:205], v[64:79]
	s_waitcnt lgkmcnt(3)
	v_mfma_f32_32x32x16_bf16 v[48:63], v[234:237], v[186:189], v[48:63]
	v_mfma_f32_32x32x16_bf16 v[32:47], v[234:237], v[202:205], v[32:47]
	s_waitcnt lgkmcnt(1)
	v_mfma_f32_32x32x16_bf16 v[16:31], v[242:245], v[186:189], v[16:31]
	v_mfma_f32_32x32x16_bf16 v[0:15], v[242:245], v[202:205], v[0:15]
	v_mfma_f32_32x32x16_bf16 v[112:127], v[218:221], v[186:189], v[112:127]
	v_mfma_f32_32x32x16_bf16 v[96:111], v[218:221], v[202:205], v[96:111]
	global_load_dwordx4 v[186:189], v[148:149], off offset:1152
	global_load_dwordx4 v[202:205], v[150:151], off offset:1152
	s_waitcnt vmcnt(9)
	ds_write_b128 v128, v[194:197]
	s_waitcnt vmcnt(8)
	ds_write_b128 v128, v[210:213] offset:9216
	ds_read_b128 v[194:197], v169 offset:64
	ds_read_b128 v[210:213], v169 offset:4672
	ds_read_b128 v[218:221], v155 offset:64
	ds_read_b128 v[226:229], v155 offset:4672
	ds_read_b128 v[234:237], v155 offset:9280
	ds_read_b128 v[242:245], v155 offset:13888
	v_mfma_f32_32x32x16_bf16 v[80:95], v[230:233], v[190:193], v[80:95]
	v_mfma_f32_32x32x16_bf16 v[64:79], v[230:233], v[206:209], v[64:79]
	v_mfma_f32_32x32x16_bf16 v[48:63], v[238:241], v[190:193], v[48:63]
	v_mfma_f32_32x32x16_bf16 v[32:47], v[238:241], v[206:209], v[32:47]
	s_waitcnt lgkmcnt(8)
	v_mfma_f32_32x32x16_bf16 v[16:31], v[246:249], v[190:193], v[16:31]
	v_mfma_f32_32x32x16_bf16 v[0:15], v[246:249], v[206:209], v[0:15]
	v_mfma_f32_32x32x16_bf16 v[112:127], v[222:225], v[190:193], v[112:127]
	v_mfma_f32_32x32x16_bf16 v[96:111], v[222:225], v[206:209], v[96:111]
	global_load_dwordx4 v[190:193], v[144:145], off offset:1152
	global_load_dwordx4 v[206:209], v[146:147], off offset:1152
	s_waitcnt vmcnt(9)
	ds_write_b128 v128, v[198:201] offset:18432
	s_waitcnt vmcnt(8)
	ds_write_b128 v128, v[214:217] offset:27648
	ds_read_b128 v[198:201], v169 offset:96
	ds_read_b128 v[214:217], v169 offset:4704
	ds_read_b128 v[222:225], v155 offset:96
	ds_read_b128 v[230:233], v155 offset:4704
	ds_read_b128 v[238:241], v155 offset:9312
	ds_read_b128 v[246:249], v155 offset:13920
	s_waitcnt lgkmcnt(10)
	v_mfma_f32_32x32x16_bf16 v[80:95], v[226:229], v[194:197], v[80:95]
	v_mfma_f32_32x32x16_bf16 v[64:79], v[226:229], v[210:213], v[64:79]
	s_waitcnt lgkmcnt(9)
	v_mfma_f32_32x32x16_bf16 v[48:63], v[234:237], v[194:197], v[48:63]
	v_mfma_f32_32x32x16_bf16 v[32:47], v[234:237], v[210:213], v[32:47]
	s_waitcnt lgkmcnt(8)
	v_mfma_f32_32x32x16_bf16 v[16:31], v[242:245], v[194:197], v[16:31]
	v_mfma_f32_32x32x16_bf16 v[0:15], v[242:245], v[210:213], v[0:15]
	v_mfma_f32_32x32x16_bf16 v[112:127], v[218:221], v[194:197], v[112:127]
	v_mfma_f32_32x32x16_bf16 v[96:111], v[218:221], v[210:213], v[96:111]
	s_waitcnt vmcnt(7)
	ds_write_b128 v128, v[130:133] offset:36864
	global_load_dwordx4 v[130:133], v[140:141], off offset:1152
	s_waitcnt vmcnt(7)
	ds_write_b128 v128, v[158:161] offset:46080
	global_load_dwordx4 v[158:161], v[138:139], off offset:1152
	s_waitcnt lgkmcnt(4)
	v_mfma_f32_32x32x16_bf16 v[80:95], v[230:233], v[198:201], v[80:95]
	v_mfma_f32_32x32x16_bf16 v[64:79], v[230:233], v[214:217], v[64:79]
	s_waitcnt lgkmcnt(3)
	v_mfma_f32_32x32x16_bf16 v[48:63], v[238:241], v[198:201], v[48:63]
	v_mfma_f32_32x32x16_bf16 v[32:47], v[238:241], v[214:217], v[32:47]
	s_waitcnt lgkmcnt(2)
	v_mfma_f32_32x32x16_bf16 v[16:31], v[246:249], v[198:201], v[16:31]
	v_mfma_f32_32x32x16_bf16 v[0:15], v[246:249], v[214:217], v[0:15]
	v_mfma_f32_32x32x16_bf16 v[112:127], v[222:225], v[198:201], v[112:127]
	v_mfma_f32_32x32x16_bf16 v[96:111], v[222:225], v[214:217], v[96:111]
	global_load_dwordx4 v[194:197], v[134:135], off offset:1152
	global_load_dwordx4 v[198:201], v[136:137], off offset:1152
	s_waitcnt vmcnt(9)
	ds_write_b128 v128, v[172:175] offset:55296
	s_waitcnt vmcnt(8)
	ds_write_b128 v128, v[182:185] offset:64512
	s_waitcnt lgkmcnt(0)
	s_barrier
	ds_read_b128 v[172:175], v163 offset:36864
	ds_read_b128 v[182:185], v163 offset:36896
	ds_read_b128 v[210:213], v163 offset:41472
	ds_read_b128 v[214:217], v163 offset:41504
	ds_read_b128 v[218:221], v154
	ds_read_b128 v[222:225], v154 offset:32
	ds_read_b128 v[226:229], v154 offset:4608
	ds_read_b128 v[230:233], v154 offset:4640
	ds_read_b128 v[234:237], v154 offset:9216
	ds_read_b128 v[238:241], v154 offset:9248
	ds_read_b128 v[242:245], v154 offset:13824
	ds_read_b128 v[246:249], v154 offset:13856
	s_waitcnt lgkmcnt(5)
	v_mfma_f32_32x32x16_bf16 v[80:95], v[226:229], v[172:175], v[80:95]
	v_mfma_f32_32x32x16_bf16 v[64:79], v[226:229], v[210:213], v[64:79]
	s_waitcnt lgkmcnt(3)
	v_mfma_f32_32x32x16_bf16 v[48:63], v[234:237], v[172:175], v[48:63]
	v_mfma_f32_32x32x16_bf16 v[32:47], v[234:237], v[210:213], v[32:47]
	s_waitcnt lgkmcnt(1)
	v_mfma_f32_32x32x16_bf16 v[16:31], v[242:245], v[172:175], v[16:31]
	v_mfma_f32_32x32x16_bf16 v[0:15], v[242:245], v[210:213], v[0:15]
	v_mfma_f32_32x32x16_bf16 v[112:127], v[218:221], v[172:175], v[112:127]
	v_mfma_f32_32x32x16_bf16 v[96:111], v[218:221], v[210:213], v[96:111]
	global_load_dwordx4 v[172:175], v[148:149], off offset:1280
	global_load_dwordx4 v[210:213], v[150:151], off offset:1280
	s_waitcnt vmcnt(9)
	ds_write_b128 v164, v[186:189]
	s_waitcnt vmcnt(8)
	ds_write_b128 v164, v[202:205] offset:9216
	ds_read_b128 v[186:189], v163 offset:36928
	ds_read_b128 v[202:205], v163 offset:41536
	ds_read_b128 v[218:221], v154 offset:64
	ds_read_b128 v[226:229], v154 offset:4672
	ds_read_b128 v[234:237], v154 offset:9280
	ds_read_b128 v[242:245], v154 offset:13888
	v_mfma_f32_32x32x16_bf16 v[80:95], v[230:233], v[182:185], v[80:95]
	v_mfma_f32_32x32x16_bf16 v[64:79], v[230:233], v[214:217], v[64:79]
	v_mfma_f32_32x32x16_bf16 v[48:63], v[238:241], v[182:185], v[48:63]
	v_mfma_f32_32x32x16_bf16 v[32:47], v[238:241], v[214:217], v[32:47]
	s_waitcnt lgkmcnt(8)
	v_mfma_f32_32x32x16_bf16 v[16:31], v[246:249], v[182:185], v[16:31]
	v_mfma_f32_32x32x16_bf16 v[0:15], v[246:249], v[214:217], v[0:15]
	v_mfma_f32_32x32x16_bf16 v[112:127], v[222:225], v[182:185], v[112:127]
	v_mfma_f32_32x32x16_bf16 v[96:111], v[222:225], v[214:217], v[96:111]
	global_load_dwordx4 v[182:185], v[144:145], off offset:1280
	global_load_dwordx4 v[214:217], v[146:147], off offset:1280
	s_waitcnt vmcnt(9)
	ds_write_b128 v164, v[190:193] offset:18432
	s_waitcnt vmcnt(8)
	ds_write_b128 v164, v[206:209] offset:27648
	ds_read_b128 v[190:193], v163 offset:36960
	ds_read_b128 v[206:209], v163 offset:41568
	ds_read_b128 v[222:225], v154 offset:96
	ds_read_b128 v[230:233], v154 offset:4704
	ds_read_b128 v[238:241], v154 offset:9312
	ds_read_b128 v[246:249], v154 offset:13920
	s_waitcnt lgkmcnt(10)
	v_mfma_f32_32x32x16_bf16 v[80:95], v[226:229], v[186:189], v[80:95]
	v_mfma_f32_32x32x16_bf16 v[64:79], v[226:229], v[202:205], v[64:79]
	s_waitcnt lgkmcnt(9)
	v_mfma_f32_32x32x16_bf16 v[48:63], v[234:237], v[186:189], v[48:63]
	v_mfma_f32_32x32x16_bf16 v[32:47], v[234:237], v[202:205], v[32:47]
	s_waitcnt lgkmcnt(8)
	v_mfma_f32_32x32x16_bf16 v[16:31], v[242:245], v[186:189], v[16:31]
	v_mfma_f32_32x32x16_bf16 v[0:15], v[242:245], v[202:205], v[0:15]
	v_mfma_f32_32x32x16_bf16 v[112:127], v[218:221], v[186:189], v[112:127]
	v_mfma_f32_32x32x16_bf16 v[96:111], v[218:221], v[202:205], v[96:111]
	s_waitcnt vmcnt(7)
	ds_write_b128 v165, v[130:133]
	global_load_dwordx4 v[130:133], v[140:141], off offset:1280
	s_waitcnt vmcnt(7)
	ds_write_b128 v166, v[158:161]
	global_load_dwordx4 v[158:161], v[138:139], off offset:1280
	s_waitcnt lgkmcnt(4)
	v_mfma_f32_32x32x16_bf16 v[80:95], v[230:233], v[190:193], v[80:95]
	v_mfma_f32_32x32x16_bf16 v[64:79], v[230:233], v[206:209], v[64:79]
	s_waitcnt lgkmcnt(3)
	v_mfma_f32_32x32x16_bf16 v[48:63], v[238:241], v[190:193], v[48:63]
	v_mfma_f32_32x32x16_bf16 v[32:47], v[238:241], v[206:209], v[32:47]
	s_waitcnt lgkmcnt(2)
	v_mfma_f32_32x32x16_bf16 v[16:31], v[246:249], v[190:193], v[16:31]
	v_mfma_f32_32x32x16_bf16 v[0:15], v[246:249], v[206:209], v[0:15]
	v_mfma_f32_32x32x16_bf16 v[112:127], v[222:225], v[190:193], v[112:127]
	v_mfma_f32_32x32x16_bf16 v[96:111], v[222:225], v[206:209], v[96:111]
	global_load_dwordx4 v[186:189], v[134:135], off offset:1280
	global_load_dwordx4 v[190:193], v[136:137], off offset:1280
	s_waitcnt vmcnt(9)
	ds_write_b128 v167, v[194:197]
	s_waitcnt vmcnt(8)
	ds_write_b128 v168, v[198:201]
	s_waitcnt lgkmcnt(0)
	s_barrier
	ds_read_b128 v[194:197], v169
	ds_read_b128 v[198:201], v169 offset:32
	ds_read_b128 v[202:205], v169 offset:4608
	ds_read_b128 v[206:209], v169 offset:4640
	ds_read_b128 v[218:221], v155
	ds_read_b128 v[222:225], v155 offset:32
	ds_read_b128 v[226:229], v155 offset:4608
	ds_read_b128 v[230:233], v155 offset:4640
	ds_read_b128 v[234:237], v155 offset:9216
	ds_read_b128 v[238:241], v155 offset:9248
	ds_read_b128 v[242:245], v155 offset:13824
	ds_read_b128 v[246:249], v155 offset:13856
	s_waitcnt lgkmcnt(5)
	v_mfma_f32_32x32x16_bf16 v[80:95], v[226:229], v[194:197], v[80:95]
	v_mfma_f32_32x32x16_bf16 v[64:79], v[226:229], v[202:205], v[64:79]
	s_waitcnt lgkmcnt(3)
	v_mfma_f32_32x32x16_bf16 v[48:63], v[234:237], v[194:197], v[48:63]
	v_mfma_f32_32x32x16_bf16 v[32:47], v[234:237], v[202:205], v[32:47]
	s_waitcnt lgkmcnt(1)
	v_mfma_f32_32x32x16_bf16 v[16:31], v[242:245], v[194:197], v[16:31]
	v_mfma_f32_32x32x16_bf16 v[0:15], v[242:245], v[202:205], v[0:15]
	v_mfma_f32_32x32x16_bf16 v[112:127], v[218:221], v[194:197], v[112:127]
	v_mfma_f32_32x32x16_bf16 v[96:111], v[218:221], v[202:205], v[96:111]
	global_load_dwordx4 v[194:197], v[148:149], off offset:1408
	global_load_dwordx4 v[202:205], v[150:151], off offset:1408
	s_waitcnt vmcnt(9)
	ds_write_b128 v128, v[172:175]
	s_waitcnt vmcnt(8)
	ds_write_b128 v128, v[210:213] offset:9216
	ds_read_b128 v[172:175], v169 offset:64
	ds_read_b128 v[210:213], v169 offset:4672
	ds_read_b128 v[218:221], v155 offset:64
	ds_read_b128 v[226:229], v155 offset:4672
	ds_read_b128 v[234:237], v155 offset:9280
	ds_read_b128 v[242:245], v155 offset:13888
	v_mfma_f32_32x32x16_bf16 v[80:95], v[230:233], v[198:201], v[80:95]
	v_mfma_f32_32x32x16_bf16 v[64:79], v[230:233], v[206:209], v[64:79]
	v_mfma_f32_32x32x16_bf16 v[48:63], v[238:241], v[198:201], v[48:63]
	v_mfma_f32_32x32x16_bf16 v[32:47], v[238:241], v[206:209], v[32:47]
	s_waitcnt lgkmcnt(8)
	v_mfma_f32_32x32x16_bf16 v[16:31], v[246:249], v[198:201], v[16:31]
	v_mfma_f32_32x32x16_bf16 v[0:15], v[246:249], v[206:209], v[0:15]
	v_mfma_f32_32x32x16_bf16 v[112:127], v[222:225], v[198:201], v[112:127]
	v_mfma_f32_32x32x16_bf16 v[96:111], v[222:225], v[206:209], v[96:111]
	global_load_dwordx4 v[198:201], v[144:145], off offset:1408
	global_load_dwordx4 v[206:209], v[146:147], off offset:1408
	s_waitcnt vmcnt(9)
	ds_write_b128 v128, v[182:185] offset:18432
	s_waitcnt vmcnt(8)
	ds_write_b128 v128, v[214:217] offset:27648
	ds_read_b128 v[182:185], v169 offset:96
	ds_read_b128 v[214:217], v169 offset:4704
	ds_read_b128 v[222:225], v155 offset:96
	ds_read_b128 v[230:233], v155 offset:4704
	ds_read_b128 v[238:241], v155 offset:9312
	ds_read_b128 v[246:249], v155 offset:13920
	s_waitcnt lgkmcnt(10)
	v_mfma_f32_32x32x16_bf16 v[80:95], v[226:229], v[172:175], v[80:95]
	v_mfma_f32_32x32x16_bf16 v[64:79], v[226:229], v[210:213], v[64:79]
	s_waitcnt lgkmcnt(9)
	v_mfma_f32_32x32x16_bf16 v[48:63], v[234:237], v[172:175], v[48:63]
	v_mfma_f32_32x32x16_bf16 v[32:47], v[234:237], v[210:213], v[32:47]
	s_waitcnt lgkmcnt(8)
	v_mfma_f32_32x32x16_bf16 v[16:31], v[242:245], v[172:175], v[16:31]
	v_mfma_f32_32x32x16_bf16 v[0:15], v[242:245], v[210:213], v[0:15]
	v_mfma_f32_32x32x16_bf16 v[112:127], v[218:221], v[172:175], v[112:127]
	v_mfma_f32_32x32x16_bf16 v[96:111], v[218:221], v[210:213], v[96:111]
	s_waitcnt vmcnt(7)
	ds_write_b128 v128, v[130:133] offset:36864
	global_load_dwordx4 v[130:133], v[140:141], off offset:1408
	s_waitcnt vmcnt(7)
	ds_write_b128 v128, v[158:161] offset:46080
	global_load_dwordx4 v[158:161], v[138:139], off offset:1408
	s_waitcnt lgkmcnt(4)
	v_mfma_f32_32x32x16_bf16 v[80:95], v[230:233], v[182:185], v[80:95]
	v_mfma_f32_32x32x16_bf16 v[64:79], v[230:233], v[214:217], v[64:79]
	s_waitcnt lgkmcnt(3)
	v_mfma_f32_32x32x16_bf16 v[48:63], v[238:241], v[182:185], v[48:63]
	v_mfma_f32_32x32x16_bf16 v[32:47], v[238:241], v[214:217], v[32:47]
	s_waitcnt lgkmcnt(2)
	v_mfma_f32_32x32x16_bf16 v[16:31], v[246:249], v[182:185], v[16:31]
	v_mfma_f32_32x32x16_bf16 v[0:15], v[246:249], v[214:217], v[0:15]
	v_mfma_f32_32x32x16_bf16 v[112:127], v[222:225], v[182:185], v[112:127]
	v_mfma_f32_32x32x16_bf16 v[96:111], v[222:225], v[214:217], v[96:111]
	global_load_dwordx4 v[172:175], v[134:135], off offset:1408
	global_load_dwordx4 v[182:185], v[136:137], off offset:1408
	s_waitcnt vmcnt(9)
	ds_write_b128 v128, v[186:189] offset:55296
	s_waitcnt vmcnt(8)
	ds_write_b128 v128, v[190:193] offset:64512
	s_waitcnt lgkmcnt(0)
	s_barrier
	ds_read_b128 v[186:189], v163 offset:36864
	ds_read_b128 v[190:193], v163 offset:36896
	ds_read_b128 v[210:213], v163 offset:41472
	ds_read_b128 v[214:217], v163 offset:41504
	ds_read_b128 v[218:221], v154
	ds_read_b128 v[222:225], v154 offset:32
	ds_read_b128 v[226:229], v154 offset:4608
	ds_read_b128 v[230:233], v154 offset:4640
	ds_read_b128 v[234:237], v154 offset:9216
	ds_read_b128 v[238:241], v154 offset:9248
	ds_read_b128 v[242:245], v154 offset:13824
	ds_read_b128 v[246:249], v154 offset:13856
	s_waitcnt lgkmcnt(5)
	v_mfma_f32_32x32x16_bf16 v[80:95], v[226:229], v[186:189], v[80:95]
	v_mfma_f32_32x32x16_bf16 v[64:79], v[226:229], v[210:213], v[64:79]
	s_waitcnt lgkmcnt(3)
	v_mfma_f32_32x32x16_bf16 v[48:63], v[234:237], v[186:189], v[48:63]
	v_mfma_f32_32x32x16_bf16 v[32:47], v[234:237], v[210:213], v[32:47]
	s_waitcnt lgkmcnt(1)
	v_mfma_f32_32x32x16_bf16 v[16:31], v[242:245], v[186:189], v[16:31]
	v_mfma_f32_32x32x16_bf16 v[0:15], v[242:245], v[210:213], v[0:15]
	v_mfma_f32_32x32x16_bf16 v[112:127], v[218:221], v[186:189], v[112:127]
	v_mfma_f32_32x32x16_bf16 v[96:111], v[218:221], v[210:213], v[96:111]
	global_load_dwordx4 v[186:189], v[148:149], off offset:1536
	global_load_dwordx4 v[210:213], v[150:151], off offset:1536
	s_waitcnt vmcnt(9)
	ds_write_b128 v164, v[194:197]
	s_waitcnt vmcnt(8)
	ds_write_b128 v164, v[202:205] offset:9216
	ds_read_b128 v[194:197], v163 offset:36928
	ds_read_b128 v[202:205], v163 offset:41536
	ds_read_b128 v[218:221], v154 offset:64
	ds_read_b128 v[226:229], v154 offset:4672
	ds_read_b128 v[234:237], v154 offset:9280
	ds_read_b128 v[242:245], v154 offset:13888
	v_mfma_f32_32x32x16_bf16 v[80:95], v[230:233], v[190:193], v[80:95]
	v_mfma_f32_32x32x16_bf16 v[64:79], v[230:233], v[214:217], v[64:79]
	v_mfma_f32_32x32x16_bf16 v[48:63], v[238:241], v[190:193], v[48:63]
	v_mfma_f32_32x32x16_bf16 v[32:47], v[238:241], v[214:217], v[32:47]
	s_waitcnt lgkmcnt(8)
	v_mfma_f32_32x32x16_bf16 v[16:31], v[246:249], v[190:193], v[16:31]
	v_mfma_f32_32x32x16_bf16 v[0:15], v[246:249], v[214:217], v[0:15]
	v_mfma_f32_32x32x16_bf16 v[112:127], v[222:225], v[190:193], v[112:127]
	v_mfma_f32_32x32x16_bf16 v[96:111], v[222:225], v[214:217], v[96:111]
	global_load_dwordx4 v[190:193], v[144:145], off offset:1536
	global_load_dwordx4 v[214:217], v[146:147], off offset:1536
	s_waitcnt vmcnt(9)
	ds_write_b128 v164, v[198:201] offset:18432
	s_waitcnt vmcnt(8)
	ds_write_b128 v164, v[206:209] offset:27648
	ds_read_b128 v[198:201], v163 offset:36960
	ds_read_b128 v[206:209], v163 offset:41568
	ds_read_b128 v[222:225], v154 offset:96
	ds_read_b128 v[230:233], v154 offset:4704
	ds_read_b128 v[238:241], v154 offset:9312
	ds_read_b128 v[246:249], v154 offset:13920
	s_waitcnt lgkmcnt(10)
	v_mfma_f32_32x32x16_bf16 v[80:95], v[226:229], v[194:197], v[80:95]
	v_mfma_f32_32x32x16_bf16 v[64:79], v[226:229], v[202:205], v[64:79]
	s_waitcnt lgkmcnt(9)
	v_mfma_f32_32x32x16_bf16 v[48:63], v[234:237], v[194:197], v[48:63]
	v_mfma_f32_32x32x16_bf16 v[32:47], v[234:237], v[202:205], v[32:47]
	s_waitcnt lgkmcnt(8)
	v_mfma_f32_32x32x16_bf16 v[16:31], v[242:245], v[194:197], v[16:31]
	v_mfma_f32_32x32x16_bf16 v[0:15], v[242:245], v[202:205], v[0:15]
	v_mfma_f32_32x32x16_bf16 v[112:127], v[218:221], v[194:197], v[112:127]
	v_mfma_f32_32x32x16_bf16 v[96:111], v[218:221], v[202:205], v[96:111]
	s_waitcnt vmcnt(7)
	ds_write_b128 v165, v[130:133]
	global_load_dwordx4 v[130:133], v[140:141], off offset:1536
	s_waitcnt vmcnt(7)
	ds_write_b128 v166, v[158:161]
	global_load_dwordx4 v[158:161], v[138:139], off offset:1536
	s_waitcnt lgkmcnt(4)
	v_mfma_f32_32x32x16_bf16 v[80:95], v[230:233], v[198:201], v[80:95]
	v_mfma_f32_32x32x16_bf16 v[64:79], v[230:233], v[206:209], v[64:79]
	s_waitcnt lgkmcnt(3)
	v_mfma_f32_32x32x16_bf16 v[48:63], v[238:241], v[198:201], v[48:63]
	v_mfma_f32_32x32x16_bf16 v[32:47], v[238:241], v[206:209], v[32:47]
	s_waitcnt lgkmcnt(2)
	v_mfma_f32_32x32x16_bf16 v[16:31], v[246:249], v[198:201], v[16:31]
	v_mfma_f32_32x32x16_bf16 v[0:15], v[246:249], v[206:209], v[0:15]
	v_mfma_f32_32x32x16_bf16 v[112:127], v[222:225], v[198:201], v[112:127]
	v_mfma_f32_32x32x16_bf16 v[96:111], v[222:225], v[206:209], v[96:111]
	global_load_dwordx4 v[194:197], v[134:135], off offset:1536
	global_load_dwordx4 v[198:201], v[136:137], off offset:1536
	s_waitcnt vmcnt(9)
	ds_write_b128 v167, v[172:175]
	s_waitcnt vmcnt(8)
	ds_write_b128 v168, v[182:185]
	s_waitcnt lgkmcnt(0)
	s_barrier
	ds_read_b128 v[172:175], v169
	ds_read_b128 v[182:185], v169 offset:32
	ds_read_b128 v[202:205], v169 offset:4608
	ds_read_b128 v[206:209], v169 offset:4640
	ds_read_b128 v[218:221], v155
	ds_read_b128 v[222:225], v155 offset:32
	ds_read_b128 v[226:229], v155 offset:4608
	ds_read_b128 v[230:233], v155 offset:4640
	ds_read_b128 v[234:237], v155 offset:9216
	ds_read_b128 v[238:241], v155 offset:9248
	ds_read_b128 v[242:245], v155 offset:13824
	ds_read_b128 v[246:249], v155 offset:13856
	s_waitcnt lgkmcnt(5)
	v_mfma_f32_32x32x16_bf16 v[80:95], v[226:229], v[172:175], v[80:95]
	v_mfma_f32_32x32x16_bf16 v[64:79], v[226:229], v[202:205], v[64:79]
	s_waitcnt lgkmcnt(3)
	v_mfma_f32_32x32x16_bf16 v[48:63], v[234:237], v[172:175], v[48:63]
	v_mfma_f32_32x32x16_bf16 v[32:47], v[234:237], v[202:205], v[32:47]
	s_waitcnt lgkmcnt(1)
	v_mfma_f32_32x32x16_bf16 v[16:31], v[242:245], v[172:175], v[16:31]
	v_mfma_f32_32x32x16_bf16 v[0:15], v[242:245], v[202:205], v[0:15]
	v_mfma_f32_32x32x16_bf16 v[112:127], v[218:221], v[172:175], v[112:127]
	v_mfma_f32_32x32x16_bf16 v[96:111], v[218:221], v[202:205], v[96:111]
	global_load_dwordx4 v[172:175], v[148:149], off offset:1664
	global_load_dwordx4 v[202:205], v[150:151], off offset:1664
	s_waitcnt vmcnt(9)
	ds_write_b128 v128, v[186:189]
	s_waitcnt vmcnt(8)
	ds_write_b128 v128, v[210:213] offset:9216
	ds_read_b128 v[186:189], v169 offset:64
	ds_read_b128 v[210:213], v169 offset:4672
	ds_read_b128 v[218:221], v155 offset:64
	ds_read_b128 v[226:229], v155 offset:4672
	ds_read_b128 v[234:237], v155 offset:9280
	ds_read_b128 v[242:245], v155 offset:13888
	v_mfma_f32_32x32x16_bf16 v[80:95], v[230:233], v[182:185], v[80:95]
	v_mfma_f32_32x32x16_bf16 v[64:79], v[230:233], v[206:209], v[64:79]
	v_mfma_f32_32x32x16_bf16 v[48:63], v[238:241], v[182:185], v[48:63]
	v_mfma_f32_32x32x16_bf16 v[32:47], v[238:241], v[206:209], v[32:47]
	s_waitcnt lgkmcnt(8)
	v_mfma_f32_32x32x16_bf16 v[16:31], v[246:249], v[182:185], v[16:31]
	v_mfma_f32_32x32x16_bf16 v[0:15], v[246:249], v[206:209], v[0:15]
	v_mfma_f32_32x32x16_bf16 v[112:127], v[222:225], v[182:185], v[112:127]
	v_mfma_f32_32x32x16_bf16 v[96:111], v[222:225], v[206:209], v[96:111]
	global_load_dwordx4 v[182:185], v[144:145], off offset:1664
	global_load_dwordx4 v[206:209], v[146:147], off offset:1664
	s_waitcnt vmcnt(9)
	ds_write_b128 v128, v[190:193] offset:18432
	s_waitcnt vmcnt(8)
	ds_write_b128 v128, v[214:217] offset:27648
	ds_read_b128 v[190:193], v169 offset:96
	ds_read_b128 v[214:217], v169 offset:4704
	ds_read_b128 v[222:225], v155 offset:96
	ds_read_b128 v[230:233], v155 offset:4704
	ds_read_b128 v[238:241], v155 offset:9312
	ds_read_b128 v[246:249], v155 offset:13920
	s_waitcnt lgkmcnt(10)
	v_mfma_f32_32x32x16_bf16 v[80:95], v[226:229], v[186:189], v[80:95]
	v_mfma_f32_32x32x16_bf16 v[64:79], v[226:229], v[210:213], v[64:79]
	s_waitcnt lgkmcnt(9)
	v_mfma_f32_32x32x16_bf16 v[48:63], v[234:237], v[186:189], v[48:63]
	v_mfma_f32_32x32x16_bf16 v[32:47], v[234:237], v[210:213], v[32:47]
	s_waitcnt lgkmcnt(8)
	v_mfma_f32_32x32x16_bf16 v[16:31], v[242:245], v[186:189], v[16:31]
	v_mfma_f32_32x32x16_bf16 v[0:15], v[242:245], v[210:213], v[0:15]
	v_mfma_f32_32x32x16_bf16 v[112:127], v[218:221], v[186:189], v[112:127]
	v_mfma_f32_32x32x16_bf16 v[96:111], v[218:221], v[210:213], v[96:111]
	s_waitcnt vmcnt(7)
	ds_write_b128 v128, v[130:133] offset:36864
	global_load_dwordx4 v[130:133], v[140:141], off offset:1664
	s_waitcnt vmcnt(7)
	ds_write_b128 v128, v[158:161] offset:46080
	global_load_dwordx4 v[158:161], v[138:139], off offset:1664
	s_waitcnt lgkmcnt(4)
	v_mfma_f32_32x32x16_bf16 v[80:95], v[230:233], v[190:193], v[80:95]
	v_mfma_f32_32x32x16_bf16 v[64:79], v[230:233], v[214:217], v[64:79]
	s_waitcnt lgkmcnt(3)
	v_mfma_f32_32x32x16_bf16 v[48:63], v[238:241], v[190:193], v[48:63]
	v_mfma_f32_32x32x16_bf16 v[32:47], v[238:241], v[214:217], v[32:47]
	s_waitcnt lgkmcnt(2)
	v_mfma_f32_32x32x16_bf16 v[16:31], v[246:249], v[190:193], v[16:31]
	v_mfma_f32_32x32x16_bf16 v[0:15], v[246:249], v[214:217], v[0:15]
	v_mfma_f32_32x32x16_bf16 v[112:127], v[222:225], v[190:193], v[112:127]
	v_mfma_f32_32x32x16_bf16 v[96:111], v[222:225], v[214:217], v[96:111]
	global_load_dwordx4 v[186:189], v[134:135], off offset:1664
	global_load_dwordx4 v[190:193], v[136:137], off offset:1664
	s_waitcnt vmcnt(9)
	ds_write_b128 v128, v[194:197] offset:55296
	s_waitcnt vmcnt(8)
	ds_write_b128 v128, v[198:201] offset:64512
	s_waitcnt lgkmcnt(0)
	s_barrier
	ds_read_b128 v[194:197], v163 offset:36864
	ds_read_b128 v[198:201], v163 offset:36896
	ds_read_b128 v[210:213], v163 offset:41472
	ds_read_b128 v[214:217], v163 offset:41504
	ds_read_b128 v[218:221], v154
	ds_read_b128 v[222:225], v154 offset:32
	ds_read_b128 v[226:229], v154 offset:4608
	ds_read_b128 v[230:233], v154 offset:4640
	ds_read_b128 v[234:237], v154 offset:9216
	ds_read_b128 v[238:241], v154 offset:9248
	ds_read_b128 v[242:245], v154 offset:13824
	ds_read_b128 v[246:249], v154 offset:13856
	s_waitcnt lgkmcnt(5)
	v_mfma_f32_32x32x16_bf16 v[80:95], v[226:229], v[194:197], v[80:95]
	v_mfma_f32_32x32x16_bf16 v[64:79], v[226:229], v[210:213], v[64:79]
	s_waitcnt lgkmcnt(3)
	v_mfma_f32_32x32x16_bf16 v[48:63], v[234:237], v[194:197], v[48:63]
	v_mfma_f32_32x32x16_bf16 v[32:47], v[234:237], v[210:213], v[32:47]
	s_waitcnt lgkmcnt(1)
	v_mfma_f32_32x32x16_bf16 v[16:31], v[242:245], v[194:197], v[16:31]
	v_mfma_f32_32x32x16_bf16 v[0:15], v[242:245], v[210:213], v[0:15]
	v_mfma_f32_32x32x16_bf16 v[112:127], v[218:221], v[194:197], v[112:127]
	v_mfma_f32_32x32x16_bf16 v[96:111], v[218:221], v[210:213], v[96:111]
	global_load_dwordx4 v[194:197], v[148:149], off offset:1792
	global_load_dwordx4 v[210:213], v[150:151], off offset:1792
	s_waitcnt vmcnt(9)
	ds_write_b128 v164, v[172:175]
	s_waitcnt vmcnt(8)
	ds_write_b128 v164, v[202:205] offset:9216
	ds_read_b128 v[172:175], v163 offset:36928
	ds_read_b128 v[202:205], v163 offset:41536
	ds_read_b128 v[218:221], v154 offset:64
	ds_read_b128 v[226:229], v154 offset:4672
	ds_read_b128 v[234:237], v154 offset:9280
	ds_read_b128 v[242:245], v154 offset:13888
	v_mfma_f32_32x32x16_bf16 v[80:95], v[230:233], v[198:201], v[80:95]
	v_mfma_f32_32x32x16_bf16 v[64:79], v[230:233], v[214:217], v[64:79]
	v_mfma_f32_32x32x16_bf16 v[48:63], v[238:241], v[198:201], v[48:63]
	v_mfma_f32_32x32x16_bf16 v[32:47], v[238:241], v[214:217], v[32:47]
	s_waitcnt lgkmcnt(8)
	v_mfma_f32_32x32x16_bf16 v[16:31], v[246:249], v[198:201], v[16:31]
	v_mfma_f32_32x32x16_bf16 v[0:15], v[246:249], v[214:217], v[0:15]
	v_mfma_f32_32x32x16_bf16 v[112:127], v[222:225], v[198:201], v[112:127]
	v_mfma_f32_32x32x16_bf16 v[96:111], v[222:225], v[214:217], v[96:111]
	global_load_dwordx4 v[198:201], v[144:145], off offset:1792
	global_load_dwordx4 v[214:217], v[146:147], off offset:1792
	s_waitcnt vmcnt(9)
	ds_write_b128 v164, v[182:185] offset:18432
	s_waitcnt vmcnt(8)
	ds_write_b128 v164, v[206:209] offset:27648
	ds_read_b128 v[182:185], v163 offset:36960
	ds_read_b128 v[206:209], v163 offset:41568
	ds_read_b128 v[222:225], v154 offset:96
	ds_read_b128 v[230:233], v154 offset:4704
	ds_read_b128 v[238:241], v154 offset:9312
	ds_read_b128 v[246:249], v154 offset:13920
	s_waitcnt lgkmcnt(10)
	v_mfma_f32_32x32x16_bf16 v[80:95], v[226:229], v[172:175], v[80:95]
	v_mfma_f32_32x32x16_bf16 v[64:79], v[226:229], v[202:205], v[64:79]
	s_waitcnt lgkmcnt(9)
	v_mfma_f32_32x32x16_bf16 v[48:63], v[234:237], v[172:175], v[48:63]
	v_mfma_f32_32x32x16_bf16 v[32:47], v[234:237], v[202:205], v[32:47]
	s_waitcnt lgkmcnt(8)
	v_mfma_f32_32x32x16_bf16 v[16:31], v[242:245], v[172:175], v[16:31]
	v_mfma_f32_32x32x16_bf16 v[0:15], v[242:245], v[202:205], v[0:15]
	v_mfma_f32_32x32x16_bf16 v[112:127], v[218:221], v[172:175], v[112:127]
	v_mfma_f32_32x32x16_bf16 v[96:111], v[218:221], v[202:205], v[96:111]
	s_waitcnt vmcnt(7)
	ds_write_b128 v165, v[130:133]
	global_load_dwordx4 v[130:133], v[140:141], off offset:1792
	s_waitcnt vmcnt(7)
	ds_write_b128 v166, v[158:161]
	global_load_dwordx4 v[158:161], v[138:139], off offset:1792
	s_waitcnt lgkmcnt(4)
	v_mfma_f32_32x32x16_bf16 v[80:95], v[230:233], v[182:185], v[80:95]
	v_mfma_f32_32x32x16_bf16 v[64:79], v[230:233], v[206:209], v[64:79]
	s_waitcnt lgkmcnt(3)
	v_mfma_f32_32x32x16_bf16 v[48:63], v[238:241], v[182:185], v[48:63]
	v_mfma_f32_32x32x16_bf16 v[32:47], v[238:241], v[206:209], v[32:47]
	s_waitcnt lgkmcnt(2)
	v_mfma_f32_32x32x16_bf16 v[16:31], v[246:249], v[182:185], v[16:31]
	v_mfma_f32_32x32x16_bf16 v[0:15], v[246:249], v[206:209], v[0:15]
	v_mfma_f32_32x32x16_bf16 v[112:127], v[222:225], v[182:185], v[112:127]
	v_mfma_f32_32x32x16_bf16 v[96:111], v[222:225], v[206:209], v[96:111]
	global_load_dwordx4 v[172:175], v[134:135], off offset:1792
	global_load_dwordx4 v[182:185], v[136:137], off offset:1792
	s_waitcnt vmcnt(9)
	ds_write_b128 v167, v[186:189]
	s_waitcnt vmcnt(8)
	ds_write_b128 v168, v[190:193]
	s_waitcnt lgkmcnt(0)
	s_barrier
	ds_read_b128 v[186:189], v169
	ds_read_b128 v[190:193], v169 offset:32
	ds_read_b128 v[202:205], v169 offset:4608
	ds_read_b128 v[206:209], v169 offset:4640
	ds_read_b128 v[218:221], v155
	ds_read_b128 v[222:225], v155 offset:32
	ds_read_b128 v[226:229], v155 offset:4608
	ds_read_b128 v[230:233], v155 offset:4640
	ds_read_b128 v[234:237], v155 offset:9216
	ds_read_b128 v[238:241], v155 offset:9248
	ds_read_b128 v[242:245], v155 offset:13824
	ds_read_b128 v[246:249], v155 offset:13856
	s_waitcnt lgkmcnt(5)
	v_mfma_f32_32x32x16_bf16 v[80:95], v[226:229], v[186:189], v[80:95]
	v_mfma_f32_32x32x16_bf16 v[64:79], v[226:229], v[202:205], v[64:79]
	s_waitcnt lgkmcnt(3)
	v_mfma_f32_32x32x16_bf16 v[48:63], v[234:237], v[186:189], v[48:63]
	v_mfma_f32_32x32x16_bf16 v[32:47], v[234:237], v[202:205], v[32:47]
	s_waitcnt lgkmcnt(1)
	v_mfma_f32_32x32x16_bf16 v[16:31], v[242:245], v[186:189], v[16:31]
	v_mfma_f32_32x32x16_bf16 v[0:15], v[242:245], v[202:205], v[0:15]
	v_mfma_f32_32x32x16_bf16 v[112:127], v[218:221], v[186:189], v[112:127]
	v_mfma_f32_32x32x16_bf16 v[96:111], v[218:221], v[202:205], v[96:111]
	global_load_dwordx4 v[186:189], v[148:149], off offset:1920
	s_nop 0
	global_load_dwordx4 v[148:151], v[150:151], off offset:1920
	s_waitcnt vmcnt(9)
	ds_write_b128 v128, v[194:197]
	s_waitcnt vmcnt(8)
	ds_write_b128 v128, v[210:213] offset:9216
	ds_read_b128 v[194:197], v169 offset:64
	ds_read_b128 v[202:205], v169 offset:4672
	ds_read_b128 v[210:213], v155 offset:64
	ds_read_b128 v[218:221], v155 offset:4672
	ds_read_b128 v[226:229], v155 offset:9280
	ds_read_b128 v[234:237], v155 offset:13888
	v_mfma_f32_32x32x16_bf16 v[80:95], v[230:233], v[190:193], v[80:95]
	v_mfma_f32_32x32x16_bf16 v[64:79], v[230:233], v[206:209], v[64:79]
	v_mfma_f32_32x32x16_bf16 v[48:63], v[238:241], v[190:193], v[48:63]
	v_mfma_f32_32x32x16_bf16 v[32:47], v[238:241], v[206:209], v[32:47]
	s_waitcnt lgkmcnt(8)
	v_mfma_f32_32x32x16_bf16 v[16:31], v[246:249], v[190:193], v[16:31]
	v_mfma_f32_32x32x16_bf16 v[0:15], v[246:249], v[206:209], v[0:15]
	v_mfma_f32_32x32x16_bf16 v[112:127], v[222:225], v[190:193], v[112:127]
	v_mfma_f32_32x32x16_bf16 v[96:111], v[222:225], v[206:209], v[96:111]
	global_load_dwordx4 v[190:193], v[144:145], off offset:1920
	s_nop 0
	global_load_dwordx4 v[144:147], v[146:147], off offset:1920
	s_waitcnt vmcnt(9)
	ds_write_b128 v128, v[198:201] offset:18432
	s_waitcnt vmcnt(8)
	ds_write_b128 v128, v[214:217] offset:27648
	ds_read_b128 v[198:201], v169 offset:96
	ds_read_b128 v[206:209], v169 offset:4704
	ds_read_b128 v[214:217], v155 offset:96
	ds_read_b128 v[222:225], v155 offset:4704
	ds_read_b128 v[230:233], v155 offset:9312
	ds_read_b128 v[238:241], v155 offset:13920
	s_waitcnt lgkmcnt(10)
	v_mfma_f32_32x32x16_bf16 v[80:95], v[218:221], v[194:197], v[80:95]
	v_mfma_f32_32x32x16_bf16 v[64:79], v[218:221], v[202:205], v[64:79]
	s_waitcnt lgkmcnt(9)
	v_mfma_f32_32x32x16_bf16 v[48:63], v[226:229], v[194:197], v[48:63]
	v_mfma_f32_32x32x16_bf16 v[32:47], v[226:229], v[202:205], v[32:47]
	s_waitcnt lgkmcnt(8)
	v_mfma_f32_32x32x16_bf16 v[16:31], v[234:237], v[194:197], v[16:31]
	v_mfma_f32_32x32x16_bf16 v[0:15], v[234:237], v[202:205], v[0:15]
	v_mfma_f32_32x32x16_bf16 v[112:127], v[210:213], v[194:197], v[112:127]
	v_mfma_f32_32x32x16_bf16 v[96:111], v[210:213], v[202:205], v[96:111]
	s_waitcnt vmcnt(7)
	ds_write_b128 v128, v[130:133] offset:36864
	global_load_dwordx4 v[130:133], v[140:141], off offset:1920
	s_waitcnt vmcnt(7)
	ds_write_b128 v128, v[158:161] offset:46080
	global_load_dwordx4 v[138:141], v[138:139], off offset:1920
	s_waitcnt lgkmcnt(4)
	v_mfma_f32_32x32x16_bf16 v[80:95], v[222:225], v[198:201], v[80:95]
	v_mfma_f32_32x32x16_bf16 v[64:79], v[222:225], v[206:209], v[64:79]
	s_waitcnt lgkmcnt(3)
	v_mfma_f32_32x32x16_bf16 v[48:63], v[230:233], v[198:201], v[48:63]
	v_mfma_f32_32x32x16_bf16 v[32:47], v[230:233], v[206:209], v[32:47]
	s_waitcnt lgkmcnt(2)
	v_mfma_f32_32x32x16_bf16 v[16:31], v[238:241], v[198:201], v[16:31]
	v_mfma_f32_32x32x16_bf16 v[0:15], v[238:241], v[206:209], v[0:15]
	v_mfma_f32_32x32x16_bf16 v[112:127], v[214:217], v[198:201], v[112:127]
	v_mfma_f32_32x32x16_bf16 v[96:111], v[214:217], v[206:209], v[96:111]
	global_load_dwordx4 v[158:161], v[134:135], off offset:1920
	s_nop 0
	global_load_dwordx4 v[134:137], v[136:137], off offset:1920
	s_waitcnt vmcnt(9)
	ds_write_b128 v128, v[172:175] offset:55296
	s_waitcnt vmcnt(8)
	ds_write_b128 v128, v[182:185] offset:64512
	s_waitcnt lgkmcnt(0)
	s_barrier
	ds_read_b128 v[172:175], v163 offset:36864
	ds_read_b128 v[182:185], v163 offset:36896
	ds_read_b128 v[194:197], v163 offset:41472
	ds_read_b128 v[198:201], v163 offset:41504
	ds_read_b128 v[202:205], v154
	ds_read_b128 v[206:209], v154 offset:32
	ds_read_b128 v[210:213], v154 offset:4608
	ds_read_b128 v[214:217], v154 offset:4640
	ds_read_b128 v[218:221], v154 offset:9216
	ds_read_b128 v[222:225], v154 offset:9248
	ds_read_b128 v[226:229], v154 offset:13824
	ds_read_b128 v[230:233], v154 offset:13856
	s_waitcnt lgkmcnt(5)
	v_mfma_f32_32x32x16_bf16 v[80:95], v[210:213], v[172:175], v[80:95]
	v_mfma_f32_32x32x16_bf16 v[64:79], v[210:213], v[194:197], v[64:79]
	s_waitcnt lgkmcnt(3)
	v_mfma_f32_32x32x16_bf16 v[48:63], v[218:221], v[172:175], v[48:63]
	v_mfma_f32_32x32x16_bf16 v[32:47], v[218:221], v[194:197], v[32:47]
	s_waitcnt lgkmcnt(1)
	v_mfma_f32_32x32x16_bf16 v[16:31], v[226:229], v[172:175], v[16:31]
	v_mfma_f32_32x32x16_bf16 v[0:15], v[226:229], v[194:197], v[0:15]
	v_mfma_f32_32x32x16_bf16 v[112:127], v[202:205], v[172:175], v[112:127]
	v_mfma_f32_32x32x16_bf16 v[96:111], v[202:205], v[194:197], v[96:111]
	s_waitcnt vmcnt(7)
	ds_write_b128 v164, v[186:189]
	s_waitcnt vmcnt(6)
	ds_write_b128 v164, v[148:151] offset:9216
	ds_read_b128 v[148:151], v163 offset:36928
	ds_read_b128 v[172:175], v163 offset:41536
	ds_read_b128 v[186:189], v154 offset:64
	ds_read_b128 v[194:197], v154 offset:4672
	ds_read_b128 v[202:205], v154 offset:9280
	ds_read_b128 v[210:213], v154 offset:13888
	v_mfma_f32_32x32x16_bf16 v[80:95], v[214:217], v[182:185], v[80:95]
	v_mfma_f32_32x32x16_bf16 v[64:79], v[214:217], v[198:201], v[64:79]
	v_mfma_f32_32x32x16_bf16 v[48:63], v[222:225], v[182:185], v[48:63]
	v_mfma_f32_32x32x16_bf16 v[32:47], v[222:225], v[198:201], v[32:47]
	s_waitcnt lgkmcnt(8)
	v_mfma_f32_32x32x16_bf16 v[16:31], v[230:233], v[182:185], v[16:31]
	v_mfma_f32_32x32x16_bf16 v[0:15], v[230:233], v[198:201], v[0:15]
	v_mfma_f32_32x32x16_bf16 v[112:127], v[206:209], v[182:185], v[112:127]
	v_mfma_f32_32x32x16_bf16 v[96:111], v[206:209], v[198:201], v[96:111]
	s_waitcnt vmcnt(5)
	ds_write_b128 v164, v[190:193] offset:18432
	s_waitcnt vmcnt(4)
	ds_write_b128 v164, v[144:147] offset:27648
	ds_read_b128 v[144:147], v163 offset:36960
	ds_read_b128 v[182:185], v163 offset:41568
	ds_read_b128 v[190:193], v154 offset:96
	ds_read_b128 v[198:201], v154 offset:4704
	ds_read_b128 v[206:209], v154 offset:9312
	ds_read_b128 v[214:217], v154 offset:13920
	s_waitcnt lgkmcnt(10)
	v_mfma_f32_32x32x16_bf16 v[80:95], v[194:197], v[148:151], v[80:95]
	v_mfma_f32_32x32x16_bf16 v[64:79], v[194:197], v[172:175], v[64:79]
	s_waitcnt lgkmcnt(9)
	v_mfma_f32_32x32x16_bf16 v[48:63], v[202:205], v[148:151], v[48:63]
	v_mfma_f32_32x32x16_bf16 v[32:47], v[202:205], v[172:175], v[32:47]
	s_waitcnt lgkmcnt(8)
	v_mfma_f32_32x32x16_bf16 v[16:31], v[210:213], v[148:151], v[16:31]
	v_mfma_f32_32x32x16_bf16 v[0:15], v[210:213], v[172:175], v[0:15]
	v_mfma_f32_32x32x16_bf16 v[112:127], v[186:189], v[148:151], v[112:127]
	v_mfma_f32_32x32x16_bf16 v[96:111], v[186:189], v[172:175], v[96:111]
	s_waitcnt vmcnt(3)
	ds_write_b128 v165, v[130:133]
	s_waitcnt vmcnt(2)
	ds_write_b128 v166, v[138:141]
	s_waitcnt lgkmcnt(4)
	v_mfma_f32_32x32x16_bf16 v[80:95], v[198:201], v[144:147], v[80:95]
	v_mfma_f32_32x32x16_bf16 v[64:79], v[198:201], v[182:185], v[64:79]
	s_waitcnt lgkmcnt(3)
	v_mfma_f32_32x32x16_bf16 v[48:63], v[206:209], v[144:147], v[48:63]
	v_mfma_f32_32x32x16_bf16 v[32:47], v[206:209], v[182:185], v[32:47]
	s_waitcnt lgkmcnt(2)
	v_mfma_f32_32x32x16_bf16 v[16:31], v[214:217], v[144:147], v[16:31]
	v_mfma_f32_32x32x16_bf16 v[0:15], v[214:217], v[182:185], v[0:15]
	v_mfma_f32_32x32x16_bf16 v[112:127], v[190:193], v[144:147], v[112:127]
	v_mfma_f32_32x32x16_bf16 v[96:111], v[190:193], v[182:185], v[96:111]
	s_waitcnt vmcnt(1)
	ds_write_b128 v167, v[158:161]
	s_waitcnt vmcnt(0)
	ds_write_b128 v168, v[134:137]
	s_waitcnt lgkmcnt(0)
	s_barrier
	ds_read_b128 v[130:133], v169
	ds_read_b128 v[134:137], v169 offset:32
	ds_read_b128 v[138:141], v169 offset:4608
	ds_read_b128 v[144:147], v169 offset:4640
	ds_read_b128 v[148:151], v155
	ds_read_b128 v[158:161], v155 offset:32
	ds_read_b128 v[172:175], v155 offset:4608
	ds_read_b128 v[182:185], v155 offset:4640
	ds_read_b128 v[186:189], v155 offset:9216
	ds_read_b128 v[190:193], v155 offset:9248
	ds_read_b128 v[194:197], v155 offset:13824
	ds_read_b128 v[198:201], v155 offset:13856
	s_waitcnt lgkmcnt(5)
	v_mfma_f32_32x32x16_bf16 v[80:95], v[172:175], v[130:133], v[80:95]
	v_mfma_f32_32x32x16_bf16 v[64:79], v[172:175], v[138:141], v[64:79]
	s_waitcnt lgkmcnt(3)
	v_mfma_f32_32x32x16_bf16 v[48:63], v[186:189], v[130:133], v[48:63]
	v_mfma_f32_32x32x16_bf16 v[32:47], v[186:189], v[138:141], v[32:47]
	s_waitcnt lgkmcnt(1)
	v_mfma_f32_32x32x16_bf16 v[16:31], v[194:197], v[130:133], v[16:31]
	v_mfma_f32_32x32x16_bf16 v[0:15], v[194:197], v[138:141], v[0:15]
	v_mfma_f32_32x32x16_bf16 v[112:127], v[148:151], v[130:133], v[112:127]
	v_mfma_f32_32x32x16_bf16 v[96:111], v[148:151], v[138:141], v[96:111]
	ds_read_b128 v[130:133], v169 offset:64
	ds_read_b128 v[138:141], v169 offset:4672
	ds_read_b128 v[148:151], v155 offset:64
	ds_read_b128 v[172:175], v155 offset:4672
	ds_read_b128 v[186:189], v155 offset:9280
	ds_read_b128 v[194:197], v155 offset:13888
	v_mfma_f32_32x32x16_bf16 v[80:95], v[182:185], v[134:137], v[80:95]
	v_mfma_f32_32x32x16_bf16 v[64:79], v[182:185], v[144:147], v[64:79]
	v_mfma_f32_32x32x16_bf16 v[48:63], v[190:193], v[134:137], v[48:63]
	v_mfma_f32_32x32x16_bf16 v[32:47], v[190:193], v[144:147], v[32:47]
	s_waitcnt lgkmcnt(6)
	v_mfma_f32_32x32x16_bf16 v[16:31], v[198:201], v[134:137], v[16:31]
	v_mfma_f32_32x32x16_bf16 v[0:15], v[198:201], v[144:147], v[0:15]
	v_mfma_f32_32x32x16_bf16 v[112:127], v[158:161], v[134:137], v[112:127]
	v_mfma_f32_32x32x16_bf16 v[96:111], v[158:161], v[144:147], v[96:111]
	ds_read_b128 v[134:137], v169 offset:96
	ds_read_b128 v[144:147], v169 offset:4704
	ds_read_b128 v[158:161], v155 offset:96
	ds_read_b128 v[182:185], v155 offset:4704
	ds_read_b128 v[190:193], v155 offset:9312
	ds_read_b128 v[198:201], v155 offset:13920
	s_waitcnt lgkmcnt(8)
	v_mfma_f32_32x32x16_bf16 v[80:95], v[172:175], v[130:133], v[80:95]
	v_mfma_f32_32x32x16_bf16 v[64:79], v[172:175], v[138:141], v[64:79]
	s_waitcnt lgkmcnt(7)
	v_mfma_f32_32x32x16_bf16 v[48:63], v[186:189], v[130:133], v[48:63]
	v_mfma_f32_32x32x16_bf16 v[32:47], v[186:189], v[138:141], v[32:47]
	s_waitcnt lgkmcnt(6)
	v_mfma_f32_32x32x16_bf16 v[16:31], v[194:197], v[130:133], v[16:31]
	v_mfma_f32_32x32x16_bf16 v[0:15], v[194:197], v[138:141], v[0:15]
	v_mfma_f32_32x32x16_bf16 v[112:127], v[148:151], v[130:133], v[112:127]
	v_mfma_f32_32x32x16_bf16 v[96:111], v[148:151], v[138:141], v[96:111]
	s_waitcnt lgkmcnt(2)
	v_mfma_f32_32x32x16_bf16 v[80:95], v[182:185], v[134:137], v[80:95]
	v_mfma_f32_32x32x16_bf16 v[64:79], v[182:185], v[144:147], v[64:79]
	s_waitcnt lgkmcnt(1)
	v_mfma_f32_32x32x16_bf16 v[48:63], v[190:193], v[134:137], v[48:63]
	v_mfma_f32_32x32x16_bf16 v[32:47], v[190:193], v[144:147], v[32:47]
	s_waitcnt lgkmcnt(0)
	v_mfma_f32_32x32x16_bf16 v[16:31], v[198:201], v[134:137], v[16:31]
	v_mfma_f32_32x32x16_bf16 v[0:15], v[198:201], v[144:147], v[0:15]
	v_mfma_f32_32x32x16_bf16 v[112:127], v[158:161], v[134:137], v[112:127]
	v_mfma_f32_32x32x16_bf16 v[96:111], v[158:161], v[144:147], v[96:111]
	v_add_u32_e32 v130, s1, v179
	s_movk_i32 s1, 0x7fff
	v_ashrrev_i32_e32 v131, 31, v130
	v_cmp_gt_i32_e32 vcc, s1, v130
	v_lshl_add_u64 v[134:135], v[130:131], 1, s[86:87]
	s_nop 5
	v_bfe_u32 v130, v112, 16, 1
	v_add3_u32 v112, v112, v130, s24
	s_barrier
	ds_write_b16_d16_hi v156, v112
	v_bfe_u32 v112, v113, 16, 1
	v_add3_u32 v112, v113, v112, s24
	ds_write_b16_d16_hi v156, v112 offset:144
	v_bfe_u32 v112, v114, 16, 1
	v_add3_u32 v112, v114, v112, s24
	ds_write_b16_d16_hi v156, v112 offset:288
	v_bfe_u32 v112, v115, 16, 1
	v_add3_u32 v112, v115, v112, s24
	ds_write_b16_d16_hi v156, v112 offset:432
	v_bfe_u32 v112, v116, 16, 1
	v_add3_u32 v112, v116, v112, s24
	ds_write_b16_d16_hi v156, v112 offset:1152
	v_bfe_u32 v112, v117, 16, 1
	v_add3_u32 v112, v117, v112, s24
	ds_write_b16_d16_hi v156, v112 offset:1296
	v_bfe_u32 v112, v118, 16, 1
	v_add3_u32 v112, v118, v112, s24
	ds_write_b16_d16_hi v156, v112 offset:1440
	v_bfe_u32 v112, v119, 16, 1
	v_add3_u32 v112, v119, v112, s24
	ds_write_b16_d16_hi v156, v112 offset:1584
	v_bfe_u32 v112, v120, 16, 1
	v_add3_u32 v112, v120, v112, s24
	ds_write_b16_d16_hi v156, v112 offset:2304
	v_bfe_u32 v112, v121, 16, 1
	v_add3_u32 v112, v121, v112, s24
	ds_write_b16_d16_hi v156, v112 offset:2448
	v_bfe_u32 v112, v122, 16, 1
	v_add3_u32 v112, v122, v112, s24
	ds_write_b16_d16_hi v156, v112 offset:2592
	v_bfe_u32 v112, v123, 16, 1
	v_add3_u32 v112, v123, v112, s24
	ds_write_b16_d16_hi v156, v112 offset:2736
	v_bfe_u32 v112, v124, 16, 1
	v_add3_u32 v112, v124, v112, s24
	ds_write_b16_d16_hi v156, v112 offset:3456
	v_bfe_u32 v112, v125, 16, 1
	v_add3_u32 v112, v125, v112, s24
	ds_write_b16_d16_hi v156, v112 offset:3600
	v_bfe_u32 v112, v126, 16, 1
	v_add3_u32 v112, v126, v112, s24
	ds_write_b16_d16_hi v156, v112 offset:3744
	v_bfe_u32 v112, v127, 16, 1
	v_add3_u32 v112, v127, v112, s24
	ds_write_b16_d16_hi v156, v112 offset:3888
	v_bfe_u32 v112, v96, 16, 1
	v_add3_u32 v96, v96, v112, s24
	ds_write_b16_d16_hi v156, v96 offset:64
	v_bfe_u32 v96, v97, 16, 1
	v_add3_u32 v96, v97, v96, s24
	ds_write_b16_d16_hi v156, v96 offset:208
	v_bfe_u32 v96, v98, 16, 1
	v_add3_u32 v96, v98, v96, s24
	ds_write_b16_d16_hi v156, v96 offset:352
	v_bfe_u32 v96, v99, 16, 1
	v_add3_u32 v96, v99, v96, s24
	ds_write_b16_d16_hi v156, v96 offset:496
	v_bfe_u32 v96, v100, 16, 1
	v_add3_u32 v96, v100, v96, s24
	ds_write_b16_d16_hi v156, v96 offset:1216
	v_bfe_u32 v96, v101, 16, 1
	v_add3_u32 v96, v101, v96, s24
	ds_write_b16_d16_hi v156, v96 offset:1360
	v_bfe_u32 v96, v102, 16, 1
	v_add3_u32 v96, v102, v96, s24
	ds_write_b16_d16_hi v156, v96 offset:1504
	v_bfe_u32 v96, v103, 16, 1
	v_add3_u32 v96, v103, v96, s24
	ds_write_b16_d16_hi v156, v96 offset:1648
	v_bfe_u32 v96, v104, 16, 1
	v_add3_u32 v96, v104, v96, s24
	ds_write_b16_d16_hi v156, v96 offset:2368
	v_bfe_u32 v96, v105, 16, 1
	v_add3_u32 v96, v105, v96, s24
	ds_write_b16_d16_hi v156, v96 offset:2512
	v_bfe_u32 v96, v106, 16, 1
	v_add3_u32 v96, v106, v96, s24
	ds_write_b16_d16_hi v156, v96 offset:2656
	v_bfe_u32 v96, v107, 16, 1
	v_add3_u32 v96, v107, v96, s24
	ds_write_b16_d16_hi v156, v96 offset:2800
	v_bfe_u32 v96, v108, 16, 1
	v_add3_u32 v96, v108, v96, s24
	ds_write_b16_d16_hi v156, v96 offset:3520
	v_bfe_u32 v96, v109, 16, 1
	v_add3_u32 v96, v109, v96, s24
	ds_write_b16_d16_hi v156, v96 offset:3664
	v_bfe_u32 v96, v110, 16, 1
	v_add3_u32 v96, v110, v96, s24
	ds_write_b16_d16_hi v156, v96 offset:3808
	v_bfe_u32 v96, v111, 16, 1
	v_add_u32_e32 v136, s0, v153
	v_add3_u32 v96, v111, v96, s24
	ds_write_b16_d16_hi v156, v96 offset:3952
	s_and_saveexec_b64 s[0:1], vcc
	s_cbranch_execz .Lgo_242
	ds_read_b128 v[186:189], v170
	ds_read_b128 v[190:193], v170 offset:1152
	ds_read_b128 v[194:197], v170 offset:2304
	ds_read_b128 v[198:201], v170 offset:3456
	v_or_b32_e32 v202, v136, v157
	v_mad_i64_i32 v[202:203], s[10:11], v202, s88, v[134:135]
	v_or_b32_e32 v204, v136, v171
	v_mad_i64_i32 v[204:205], s[10:11], v204, s88, v[134:135]
	v_or_b32_e32 v206, v136, v252
	v_mad_i64_i32 v[206:207], s[10:11], v206, s88, v[134:135]
	v_or_b32_e32 v208, v136, v181
	v_mad_i64_i32 v[208:209], s[10:11], v208, s88, v[134:135]
	s_waitcnt lgkmcnt(3)
	global_store_dwordx4 v[202:203], v[186:189], off
	s_waitcnt lgkmcnt(2)
	global_store_dwordx4 v[204:205], v[190:193], off
	s_waitcnt lgkmcnt(1)
	global_store_dwordx4 v[206:207], v[194:197], off
	s_waitcnt lgkmcnt(0)
	global_store_dwordx4 v[208:209], v[198:201], off
.Lgo_242:
	s_or_b64 exec, exec, s[0:1]
	s_nop 0
	v_bfe_u32 v96, v80, 16, 1
	v_add3_u32 v80, v80, v96, s24
	ds_write_b16_d16_hi v156, v80
	v_bfe_u32 v80, v81, 16, 1
	v_add3_u32 v80, v81, v80, s24
	ds_write_b16_d16_hi v156, v80 offset:144
	v_bfe_u32 v80, v82, 16, 1
	v_add3_u32 v80, v82, v80, s24
	ds_write_b16_d16_hi v156, v80 offset:288
	v_bfe_u32 v80, v83, 16, 1
	v_add3_u32 v80, v83, v80, s24
	ds_write_b16_d16_hi v156, v80 offset:432
	v_bfe_u32 v80, v84, 16, 1
	v_add3_u32 v80, v84, v80, s24
	ds_write_b16_d16_hi v156, v80 offset:1152
	v_bfe_u32 v80, v85, 16, 1
	v_add3_u32 v80, v85, v80, s24
	ds_write_b16_d16_hi v156, v80 offset:1296
	v_bfe_u32 v80, v86, 16, 1
	v_add3_u32 v80, v86, v80, s24
	ds_write_b16_d16_hi v156, v80 offset:1440
	v_bfe_u32 v80, v87, 16, 1
	v_add3_u32 v80, v87, v80, s24
	ds_write_b16_d16_hi v156, v80 offset:1584
	v_bfe_u32 v80, v88, 16, 1
	v_add3_u32 v80, v88, v80, s24
	ds_write_b16_d16_hi v156, v80 offset:2304
	v_bfe_u32 v80, v89, 16, 1
	v_add3_u32 v80, v89, v80, s24
	ds_write_b16_d16_hi v156, v80 offset:2448
	v_bfe_u32 v80, v90, 16, 1
	v_add3_u32 v80, v90, v80, s24
	ds_write_b16_d16_hi v156, v80 offset:2592
	v_bfe_u32 v80, v91, 16, 1
	v_add3_u32 v80, v91, v80, s24
	ds_write_b16_d16_hi v156, v80 offset:2736
	v_bfe_u32 v80, v92, 16, 1
	v_add3_u32 v80, v92, v80, s24
	ds_write_b16_d16_hi v156, v80 offset:3456
	v_bfe_u32 v80, v93, 16, 1
	v_add3_u32 v80, v93, v80, s24
	ds_write_b16_d16_hi v156, v80 offset:3600
	v_bfe_u32 v80, v94, 16, 1
	v_add3_u32 v80, v94, v80, s24
	ds_write_b16_d16_hi v156, v80 offset:3744
	v_bfe_u32 v80, v95, 16, 1
	v_add3_u32 v80, v95, v80, s24
	ds_write_b16_d16_hi v156, v80 offset:3888
	v_bfe_u32 v80, v64, 16, 1
	v_add3_u32 v64, v64, v80, s24
	ds_write_b16_d16_hi v156, v64 offset:64
	v_bfe_u32 v64, v65, 16, 1
	v_add3_u32 v64, v65, v64, s24
	ds_write_b16_d16_hi v156, v64 offset:208
	v_bfe_u32 v64, v66, 16, 1
	v_add3_u32 v64, v66, v64, s24
	ds_write_b16_d16_hi v156, v64 offset:352
	v_bfe_u32 v64, v67, 16, 1
	v_add3_u32 v64, v67, v64, s24
	ds_write_b16_d16_hi v156, v64 offset:496
	v_bfe_u32 v64, v68, 16, 1
	v_add3_u32 v64, v68, v64, s24
	ds_write_b16_d16_hi v156, v64 offset:1216
	v_bfe_u32 v64, v69, 16, 1
	v_add3_u32 v64, v69, v64, s24
	ds_write_b16_d16_hi v156, v64 offset:1360
	v_bfe_u32 v64, v70, 16, 1
	v_add3_u32 v64, v70, v64, s24
	ds_write_b16_d16_hi v156, v64 offset:1504
	v_bfe_u32 v64, v71, 16, 1
	v_add3_u32 v64, v71, v64, s24
	ds_write_b16_d16_hi v156, v64 offset:1648
	v_bfe_u32 v64, v72, 16, 1
	v_add3_u32 v64, v72, v64, s24
	ds_write_b16_d16_hi v156, v64 offset:2368
	v_bfe_u32 v64, v73, 16, 1
	v_add3_u32 v64, v73, v64, s24
	ds_write_b16_d16_hi v156, v64 offset:2512
	v_bfe_u32 v64, v74, 16, 1
	v_add3_u32 v64, v74, v64, s24
	ds_write_b16_d16_hi v156, v64 offset:2656
	v_bfe_u32 v64, v75, 16, 1
	v_add3_u32 v64, v75, v64, s24
	ds_write_b16_d16_hi v156, v64 offset:2800
	v_bfe_u32 v64, v76, 16, 1
	v_add3_u32 v64, v76, v64, s24
	ds_write_b16_d16_hi v156, v64 offset:3520
	v_bfe_u32 v64, v77, 16, 1
	v_add3_u32 v64, v77, v64, s24
	ds_write_b16_d16_hi v156, v64 offset:3664
	v_bfe_u32 v64, v78, 16, 1
	v_add3_u32 v64, v78, v64, s24
	ds_write_b16_d16_hi v156, v64 offset:3808
	v_bfe_u32 v64, v79, 16, 1
	v_add3_u32 v64, v79, v64, s24
	ds_write_b16_d16_hi v156, v64 offset:3952
	s_and_saveexec_b64 s[0:1], vcc
	s_cbranch_execz .Lgo_244
	ds_read_b128 v[186:189], v170
	ds_read_b128 v[190:193], v170 offset:1152
	ds_read_b128 v[194:197], v170 offset:2304
	ds_read_b128 v[198:201], v170 offset:3456
	v_or_b32_e32 v70, 32, v136
	v_or_b32_e32 v202, v70, v157
	v_mad_i64_i32 v[202:203], s[10:11], v202, s88, v[134:135]
	v_or_b32_e32 v204, v70, v171
	v_mad_i64_i32 v[204:205], s[10:11], v204, s88, v[134:135]
	v_or_b32_e32 v206, v70, v252
	v_mad_i64_i32 v[206:207], s[10:11], v206, s88, v[134:135]
	v_or_b32_e32 v208, v70, v181
	v_mad_i64_i32 v[208:209], s[10:11], v208, s88, v[134:135]
	s_waitcnt lgkmcnt(3)
	global_store_dwordx4 v[202:203], v[186:189], off
	s_waitcnt lgkmcnt(2)
	global_store_dwordx4 v[204:205], v[190:193], off
	s_waitcnt lgkmcnt(1)
	global_store_dwordx4 v[206:207], v[194:197], off
	s_waitcnt lgkmcnt(0)
	global_store_dwordx4 v[208:209], v[198:201], off
.Lgo_244:
	s_or_b64 exec, exec, s[0:1]
	s_nop 0
	v_bfe_u32 v64, v48, 16, 1
	v_add3_u32 v48, v48, v64, s24
	ds_write_b16_d16_hi v156, v48
	v_bfe_u32 v48, v49, 16, 1
	v_add3_u32 v48, v49, v48, s24
	ds_write_b16_d16_hi v156, v48 offset:144
	v_bfe_u32 v48, v50, 16, 1
	v_add3_u32 v48, v50, v48, s24
	ds_write_b16_d16_hi v156, v48 offset:288
	v_bfe_u32 v48, v51, 16, 1
	v_add3_u32 v48, v51, v48, s24
	ds_write_b16_d16_hi v156, v48 offset:432
	v_bfe_u32 v48, v52, 16, 1
	v_add3_u32 v48, v52, v48, s24
	ds_write_b16_d16_hi v156, v48 offset:1152
	v_bfe_u32 v48, v53, 16, 1
	v_add3_u32 v48, v53, v48, s24
	ds_write_b16_d16_hi v156, v48 offset:1296
	v_bfe_u32 v48, v54, 16, 1
	v_add3_u32 v48, v54, v48, s24
	ds_write_b16_d16_hi v156, v48 offset:1440
	v_bfe_u32 v48, v55, 16, 1
	v_add3_u32 v48, v55, v48, s24
	ds_write_b16_d16_hi v156, v48 offset:1584
	v_bfe_u32 v48, v56, 16, 1
	v_add3_u32 v48, v56, v48, s24
	ds_write_b16_d16_hi v156, v48 offset:2304
	v_bfe_u32 v48, v57, 16, 1
	v_add3_u32 v48, v57, v48, s24
	ds_write_b16_d16_hi v156, v48 offset:2448
	v_bfe_u32 v48, v58, 16, 1
	v_add3_u32 v48, v58, v48, s24
	ds_write_b16_d16_hi v156, v48 offset:2592
	v_bfe_u32 v48, v59, 16, 1
	v_add3_u32 v48, v59, v48, s24
	ds_write_b16_d16_hi v156, v48 offset:2736
	v_bfe_u32 v48, v60, 16, 1
	v_add3_u32 v48, v60, v48, s24
	ds_write_b16_d16_hi v156, v48 offset:3456
	v_bfe_u32 v48, v61, 16, 1
	v_add3_u32 v48, v61, v48, s24
	ds_write_b16_d16_hi v156, v48 offset:3600
	v_bfe_u32 v48, v62, 16, 1
	v_add3_u32 v48, v62, v48, s24
	ds_write_b16_d16_hi v156, v48 offset:3744
	v_bfe_u32 v48, v63, 16, 1
	v_add3_u32 v48, v63, v48, s24
	ds_write_b16_d16_hi v156, v48 offset:3888
	v_bfe_u32 v48, v32, 16, 1
	v_add3_u32 v32, v32, v48, s24
	ds_write_b16_d16_hi v156, v32 offset:64
	v_bfe_u32 v32, v33, 16, 1
	v_add3_u32 v32, v33, v32, s24
	ds_write_b16_d16_hi v156, v32 offset:208
	v_bfe_u32 v32, v34, 16, 1
	v_add3_u32 v32, v34, v32, s24
	ds_write_b16_d16_hi v156, v32 offset:352
	v_bfe_u32 v32, v35, 16, 1
	v_add3_u32 v32, v35, v32, s24
	ds_write_b16_d16_hi v156, v32 offset:496
	v_bfe_u32 v32, v36, 16, 1
	v_add3_u32 v32, v36, v32, s24
	ds_write_b16_d16_hi v156, v32 offset:1216
	v_bfe_u32 v32, v37, 16, 1
	v_add3_u32 v32, v37, v32, s24
	ds_write_b16_d16_hi v156, v32 offset:1360
	v_bfe_u32 v32, v38, 16, 1
	v_add3_u32 v32, v38, v32, s24
	ds_write_b16_d16_hi v156, v32 offset:1504
	v_bfe_u32 v32, v39, 16, 1
	v_add3_u32 v32, v39, v32, s24
	ds_write_b16_d16_hi v156, v32 offset:1648
	v_bfe_u32 v32, v40, 16, 1
	v_add3_u32 v32, v40, v32, s24
	ds_write_b16_d16_hi v156, v32 offset:2368
	v_bfe_u32 v32, v41, 16, 1
	v_add3_u32 v32, v41, v32, s24
	ds_write_b16_d16_hi v156, v32 offset:2512
	v_bfe_u32 v32, v42, 16, 1
	v_add3_u32 v32, v42, v32, s24
	ds_write_b16_d16_hi v156, v32 offset:2656
	v_bfe_u32 v32, v43, 16, 1
	v_add3_u32 v32, v43, v32, s24
	ds_write_b16_d16_hi v156, v32 offset:2800
	v_bfe_u32 v32, v44, 16, 1
	v_add3_u32 v32, v44, v32, s24
	ds_write_b16_d16_hi v156, v32 offset:3520
	v_bfe_u32 v32, v45, 16, 1
	v_add3_u32 v32, v45, v32, s24
	ds_write_b16_d16_hi v156, v32 offset:3664
	v_bfe_u32 v32, v46, 16, 1
	v_add3_u32 v32, v46, v32, s24
	ds_write_b16_d16_hi v156, v32 offset:3808
	v_bfe_u32 v32, v47, 16, 1
	v_add3_u32 v32, v47, v32, s24
	ds_write_b16_d16_hi v156, v32 offset:3952
	s_and_saveexec_b64 s[0:1], vcc
	s_cbranch_execz .Lgo_246
	ds_read_b128 v[186:189], v170
	ds_read_b128 v[190:193], v170 offset:1152
	ds_read_b128 v[194:197], v170 offset:2304
	ds_read_b128 v[198:201], v170 offset:3456
	v_or_b32_e32 v38, 64, v136
	v_or_b32_e32 v202, v38, v157
	v_mad_i64_i32 v[202:203], s[10:11], v202, s88, v[134:135]
	v_or_b32_e32 v204, v38, v171
	v_mad_i64_i32 v[204:205], s[10:11], v204, s88, v[134:135]
	v_or_b32_e32 v206, v38, v252
	v_mad_i64_i32 v[206:207], s[10:11], v206, s88, v[134:135]
	v_or_b32_e32 v208, v38, v181
	v_mad_i64_i32 v[208:209], s[10:11], v208, s88, v[134:135]
	s_waitcnt lgkmcnt(3)
	global_store_dwordx4 v[202:203], v[186:189], off
	s_waitcnt lgkmcnt(2)
	global_store_dwordx4 v[204:205], v[190:193], off
	s_waitcnt lgkmcnt(1)
	global_store_dwordx4 v[206:207], v[194:197], off
	s_waitcnt lgkmcnt(0)
	global_store_dwordx4 v[208:209], v[198:201], off
.Lgo_246:
	s_or_b64 exec, exec, s[0:1]
	s_nop 0
	v_bfe_u32 v32, v16, 16, 1
	v_add3_u32 v16, v16, v32, s24
	ds_write_b16_d16_hi v156, v16
	v_bfe_u32 v16, v17, 16, 1
	v_add3_u32 v16, v17, v16, s24
	ds_write_b16_d16_hi v156, v16 offset:144
	v_bfe_u32 v16, v18, 16, 1
	v_add3_u32 v16, v18, v16, s24
	ds_write_b16_d16_hi v156, v16 offset:288
	v_bfe_u32 v16, v19, 16, 1
	v_add3_u32 v16, v19, v16, s24
	ds_write_b16_d16_hi v156, v16 offset:432
	v_bfe_u32 v16, v20, 16, 1
	v_add3_u32 v16, v20, v16, s24
	ds_write_b16_d16_hi v156, v16 offset:1152
	v_bfe_u32 v16, v21, 16, 1
	v_add3_u32 v16, v21, v16, s24
	ds_write_b16_d16_hi v156, v16 offset:1296
	v_bfe_u32 v16, v22, 16, 1
	v_add3_u32 v16, v22, v16, s24
	ds_write_b16_d16_hi v156, v16 offset:1440
	v_bfe_u32 v16, v23, 16, 1
	v_add3_u32 v16, v23, v16, s24
	ds_write_b16_d16_hi v156, v16 offset:1584
	v_bfe_u32 v16, v24, 16, 1
	v_add3_u32 v16, v24, v16, s24
	ds_write_b16_d16_hi v156, v16 offset:2304
	v_bfe_u32 v16, v25, 16, 1
	v_add3_u32 v16, v25, v16, s24
	ds_write_b16_d16_hi v156, v16 offset:2448
	v_bfe_u32 v16, v26, 16, 1
	v_add3_u32 v16, v26, v16, s24
	ds_write_b16_d16_hi v156, v16 offset:2592
	v_bfe_u32 v16, v27, 16, 1
	v_add3_u32 v16, v27, v16, s24
	ds_write_b16_d16_hi v156, v16 offset:2736
	v_bfe_u32 v16, v28, 16, 1
	v_add3_u32 v16, v28, v16, s24
	ds_write_b16_d16_hi v156, v16 offset:3456
	v_bfe_u32 v16, v29, 16, 1
	v_add3_u32 v16, v29, v16, s24
	ds_write_b16_d16_hi v156, v16 offset:3600
	v_bfe_u32 v16, v30, 16, 1
	v_add3_u32 v16, v30, v16, s24
	ds_write_b16_d16_hi v156, v16 offset:3744
	v_bfe_u32 v16, v31, 16, 1
	v_add3_u32 v16, v31, v16, s24
	ds_write_b16_d16_hi v156, v16 offset:3888
	v_bfe_u32 v16, v0, 16, 1
	v_add3_u32 v0, v0, v16, s24
	ds_write_b16_d16_hi v156, v0 offset:64
	v_bfe_u32 v0, v1, 16, 1
	v_add3_u32 v0, v1, v0, s24
	ds_write_b16_d16_hi v156, v0 offset:208
	v_bfe_u32 v0, v2, 16, 1
	v_add3_u32 v0, v2, v0, s24
	ds_write_b16_d16_hi v156, v0 offset:352
	v_bfe_u32 v0, v3, 16, 1
	v_add3_u32 v0, v3, v0, s24
	ds_write_b16_d16_hi v156, v0 offset:496
	v_bfe_u32 v0, v4, 16, 1
	v_add3_u32 v0, v4, v0, s24
	ds_write_b16_d16_hi v156, v0 offset:1216
	v_bfe_u32 v0, v5, 16, 1
	v_add3_u32 v0, v5, v0, s24
	ds_write_b16_d16_hi v156, v0 offset:1360
	v_bfe_u32 v0, v6, 16, 1
	v_add3_u32 v0, v6, v0, s24
	ds_write_b16_d16_hi v156, v0 offset:1504
	v_bfe_u32 v0, v7, 16, 1
	v_add3_u32 v0, v7, v0, s24
	ds_write_b16_d16_hi v156, v0 offset:1648
	v_bfe_u32 v0, v8, 16, 1
	v_add3_u32 v0, v8, v0, s24
	ds_write_b16_d16_hi v156, v0 offset:2368
	v_bfe_u32 v0, v9, 16, 1
	v_add3_u32 v0, v9, v0, s24
	ds_write_b16_d16_hi v156, v0 offset:2512
	v_bfe_u32 v0, v10, 16, 1
	v_add3_u32 v0, v10, v0, s24
	ds_write_b16_d16_hi v156, v0 offset:2656
	v_bfe_u32 v0, v11, 16, 1
	v_add3_u32 v0, v11, v0, s24
	ds_write_b16_d16_hi v156, v0 offset:2800
	v_bfe_u32 v0, v12, 16, 1
	v_add3_u32 v0, v12, v0, s24
	ds_write_b16_d16_hi v156, v0 offset:3520
	v_bfe_u32 v0, v13, 16, 1
	v_add3_u32 v0, v13, v0, s24
	ds_write_b16_d16_hi v156, v0 offset:3664
	v_bfe_u32 v0, v14, 16, 1
	v_add3_u32 v0, v14, v0, s24
	ds_write_b16_d16_hi v156, v0 offset:3808
	v_bfe_u32 v0, v15, 16, 1
	v_add3_u32 v0, v15, v0, s24
	ds_write_b16_d16_hi v156, v0 offset:3952
	s_and_saveexec_b64 s[0:1], vcc
	s_cbranch_execz .Lgo_237
	ds_read_b128 v[186:189], v170
	ds_read_b128 v[190:193], v170 offset:1152
	ds_read_b128 v[194:197], v170 offset:2304
	ds_read_b128 v[198:201], v170 offset:3456
	v_or_b32_e32 v6, 0x60, v136
	v_or_b32_e32 v202, v6, v157
	v_mad_i64_i32 v[202:203], s[10:11], v202, s88, v[134:135]
	v_or_b32_e32 v204, v6, v171
	v_mad_i64_i32 v[204:205], s[10:11], v204, s88, v[134:135]
	v_or_b32_e32 v206, v6, v252
	v_mad_i64_i32 v[206:207], s[10:11], v206, s88, v[134:135]
	v_or_b32_e32 v208, v6, v181
	v_mad_i64_i32 v[208:209], s[10:11], v208, s88, v[134:135]
	s_waitcnt lgkmcnt(3)
	global_store_dwordx4 v[202:203], v[186:189], off
	s_waitcnt lgkmcnt(2)
	global_store_dwordx4 v[204:205], v[190:193], off
	s_waitcnt lgkmcnt(1)
	global_store_dwordx4 v[206:207], v[194:197], off
	s_waitcnt lgkmcnt(0)
	global_store_dwordx4 v[208:209], v[198:201], off
	s_branch .Lgo_237
